# GEMM epilogues rewritten for swapped MFMA operands: 4 consecutive output columns per lane, dwordx2/dwordx4 stores and loads instead of per-element short/dword; bit-identical
# speedup vs baseline: 1.0707x; 1.0021x over previous
; #define G_LOAD(KT) do { _Pragma("unroll") for (int i = 0; i < 4; ++i) { ra[i] = *(const u32x4*)(Ag + (size_t)i * 64 * lda + (KT) * 64); rb[i] = *(const u32x4*)(Bg + (size_t)i * 64 * K + (KT) * 64); } } while (0)
; #define G_STORE(BUF) do { u16* ad = As + (BUF) * 256 * 64 + sto; u16* bd = Bs + (BUF) * 256 * 64 + sto; _Pragma("unroll") for (int i = 0; i < 4; ++i) { *(u32x4*)(ad + i * 64 * 64) = ra[i]; *(u32x4*)(bd + i * 64 * 64) = rb[i]; } } while (0)
; template <int EPI>
; DI void gemm_phase(const u16* __restrict__ A, int lda, const u16* __restrict__ Bt, int K, int N, u16* outb, int ldo,
;                    const float* r0, const float* r1, float* outf, char* lds, int bid, int nb) {
;     ...
;     G_LOAD(0);
;     G_STORE(0);
;     __syncthreads();
;     for (int kt = 0; kt < nk; ++kt) {
;       const int cur = kt & 1;
;       if (kt + 1 < nk) G_LOAD(kt + 1);
;       G_MMA(cur, fo0);
;       G_MMA(cur, fo1);
;       if (kt + 1 < nk) G_STORE(cur ^ 1);
;       __syncthreads();
;     }
.Lgm0_loop:
	s_waitcnt lgkmcnt(4)
	v_mfma_f32_16x16x32_bf16 v[124:127], v[152:155], v[188:191], v[124:127]
	v_mfma_f32_16x16x32_bf16 v[120:123], v[156:159], v[188:191], v[120:123]
	v_mfma_f32_16x16x32_bf16 v[116:119], v[160:163], v[188:191], v[116:119]
	v_mfma_f32_16x16x32_bf16 v[112:115], v[164:167], v[188:191], v[112:115]
	ds_read_b128 v[188:191], v226 offset:0
	ds_read_b128 v[168:171], v228 offset:0
	v_mfma_f32_16x16x32_bf16 v[108:111], v[152:155], v[192:195], v[108:111]
	v_mfma_f32_16x16x32_bf16 v[104:107], v[156:159], v[192:195], v[104:107]
	v_mfma_f32_16x16x32_bf16 v[100:103], v[160:163], v[192:195], v[100:103]
	v_mfma_f32_16x16x32_bf16 v[96:99], v[164:167], v[192:195], v[96:99]
	ds_read_b128 v[192:195], v226 offset:2048
	ds_read_b128 v[176:179], v228 offset:2048
	v_mfma_f32_16x16x32_bf16 v[92:95], v[152:155], v[196:199], v[92:95]
	v_mfma_f32_16x16x32_bf16 v[88:91], v[156:159], v[196:199], v[88:91]
	v_mfma_f32_16x16x32_bf16 v[84:87], v[160:163], v[196:199], v[84:87]
	v_mfma_f32_16x16x32_bf16 v[80:83], v[164:167], v[196:199], v[80:83]
	ds_read_b128 v[196:199], v226 offset:4096
	ds_read_b128 v[180:183], v228 offset:4096
	v_mfma_f32_16x16x32_bf16 v[76:79], v[152:155], v[200:203], v[76:79]
	v_mfma_f32_16x16x32_bf16 v[72:75], v[156:159], v[200:203], v[72:75]
	v_mfma_f32_16x16x32_bf16 v[68:71], v[160:163], v[200:203], v[68:71]
	v_mfma_f32_16x16x32_bf16 v[64:67], v[164:167], v[200:203], v[64:67]
	ds_read_b128 v[200:203], v226 offset:6144
	ds_read_b128 v[184:187], v228 offset:6144
	s_waitcnt lgkmcnt(11)
	v_mfma_f32_16x16x32_bf16 v[60:63], v[152:155], v[204:207], v[60:63]
	v_mfma_f32_16x16x32_bf16 v[56:59], v[156:159], v[204:207], v[56:59]
	v_mfma_f32_16x16x32_bf16 v[52:55], v[160:163], v[204:207], v[52:55]
	v_mfma_f32_16x16x32_bf16 v[48:51], v[164:167], v[204:207], v[48:51]
	ds_read_b128 v[204:207], v226 offset:8192
	ds_read_b128 v[220:223], v226 offset:14336
	s_waitcnt lgkmcnt(11)
	v_mfma_f32_16x16x32_bf16 v[44:47], v[152:155], v[208:211], v[44:47]
	v_mfma_f32_16x16x32_bf16 v[40:43], v[156:159], v[208:211], v[40:43]
	v_mfma_f32_16x16x32_bf16 v[36:39], v[160:163], v[208:211], v[36:39]
	v_mfma_f32_16x16x32_bf16 v[32:35], v[164:167], v[208:211], v[32:35]
	ds_read_b128 v[208:211], v226 offset:10240
	s_waitcnt lgkmcnt(11)
	v_mfma_f32_16x16x32_bf16 v[28:31], v[152:155], v[212:215], v[28:31]
	v_mfma_f32_16x16x32_bf16 v[24:27], v[156:159], v[212:215], v[24:27]
	v_mfma_f32_16x16x32_bf16 v[20:23], v[160:163], v[212:215], v[20:23]
	v_mfma_f32_16x16x32_bf16 v[16:19], v[164:167], v[212:215], v[16:19]
	ds_read_b128 v[212:215], v226 offset:12288
	v_mfma_f32_16x16x32_bf16 v[12:15], v[152:155], v[216:219], v[12:15]
	v_mfma_f32_16x16x32_bf16 v[8:11], v[156:159], v[216:219], v[8:11]
	v_mfma_f32_16x16x32_bf16 v[4:7], v[160:163], v[216:219], v[4:7]
	v_mfma_f32_16x16x32_bf16 v[0:3], v[164:167], v[216:219], v[0:3]
	s_waitcnt vmcnt(0) lgkmcnt(0)
	s_barrier
	v_mfma_f32_16x16x32_bf16 v[124:127], v[168:171], v[188:191], v[124:127]
	v_mfma_f32_16x16x32_bf16 v[120:123], v[176:179], v[188:191], v[120:123]
	v_mfma_f32_16x16x32_bf16 v[116:119], v[180:183], v[188:191], v[116:119]
	v_mfma_f32_16x16x32_bf16 v[112:115], v[184:187], v[188:191], v[112:115]
	ds_read_b128 v[188:191], v225 offset:0
	ds_read_b128 v[152:155], v227 offset:0
	s_add_u32 s12, s98, 0x0
	s_addc_u32 s13, s99, 0
	s_add_u32 m0, s97, 0x0
	s_nop 0
	global_load_lds_dwordx4 v224, s[12:13]
	v_mfma_f32_16x16x32_bf16 v[108:111], v[168:171], v[192:195], v[108:111]
	v_mfma_f32_16x16x32_bf16 v[104:107], v[176:179], v[192:195], v[104:107]
	v_mfma_f32_16x16x32_bf16 v[100:103], v[180:183], v[192:195], v[100:103]
	v_mfma_f32_16x16x32_bf16 v[96:99], v[184:187], v[192:195], v[96:99]
	ds_read_b128 v[192:195], v225 offset:2048
	ds_read_b128 v[156:159], v227 offset:2048
	s_add_u32 s12, s100, 0x0
	s_addc_u32 s13, s101, 0
	s_add_u32 m0, s97, 0x10000
	s_nop 0
	global_load_lds_dwordx4 v224, s[12:13]
	v_mfma_f32_16x16x32_bf16 v[92:95], v[168:171], v[196:199], v[92:95]
	v_mfma_f32_16x16x32_bf16 v[88:91], v[176:179], v[196:199], v[88:91]
	v_mfma_f32_16x16x32_bf16 v[84:87], v[180:183], v[196:199], v[84:87]
	v_mfma_f32_16x16x32_bf16 v[80:83], v[184:187], v[196:199], v[80:83]
	ds_read_b128 v[196:199], v225 offset:4096
	ds_read_b128 v[160:163], v227 offset:4096
	s_add_u32 s12, s98, 0x20000
	s_addc_u32 s13, s99, 0
	s_add_u32 m0, s97, 0x2000
	s_nop 0
	global_load_lds_dwordx4 v224, s[12:13]
	v_mfma_f32_16x16x32_bf16 v[76:79], v[168:171], v[200:203], v[76:79]
	v_mfma_f32_16x16x32_bf16 v[72:75], v[176:179], v[200:203], v[72:75]
	v_mfma_f32_16x16x32_bf16 v[68:71], v[180:183], v[200:203], v[68:71]
	v_mfma_f32_16x16x32_bf16 v[64:67], v[184:187], v[200:203], v[64:67]
	ds_read_b128 v[200:203], v225 offset:6144
	ds_read_b128 v[164:167], v227 offset:6144
	s_add_u32 s12, s100, 0x20000
	s_addc_u32 s13, s101, 0
	s_add_u32 m0, s97, 0x12000
	s_nop 0
	global_load_lds_dwordx4 v224, s[12:13]
	v_mfma_f32_16x16x32_bf16 v[60:63], v[168:171], v[204:207], v[60:63]
	v_mfma_f32_16x16x32_bf16 v[56:59], v[176:179], v[204:207], v[56:59]
	v_mfma_f32_16x16x32_bf16 v[52:55], v[180:183], v[204:207], v[52:55]
	v_mfma_f32_16x16x32_bf16 v[48:51], v[184:187], v[204:207], v[48:51]
	ds_read_b128 v[204:207], v225 offset:8192
	ds_read_b128 v[216:219], v225 offset:14336
	s_add_u32 s12, s98, 0x40000
	s_addc_u32 s13, s99, 0
	s_add_u32 m0, s97, 0x4000
	s_nop 0
	global_load_lds_dwordx4 v224, s[12:13]
	v_mfma_f32_16x16x32_bf16 v[44:47], v[168:171], v[208:211], v[44:47]
	v_mfma_f32_16x16x32_bf16 v[40:43], v[176:179], v[208:211], v[40:43]
	v_mfma_f32_16x16x32_bf16 v[36:39], v[180:183], v[208:211], v[36:39]
	v_mfma_f32_16x16x32_bf16 v[32:35], v[184:187], v[208:211], v[32:35]
	ds_read_b128 v[208:211], v225 offset:10240
	s_add_u32 s12, s100, 0x40000
	s_addc_u32 s13, s101, 0
	s_add_u32 m0, s97, 0x14000
	s_nop 0
	global_load_lds_dwordx4 v224, s[12:13]
	v_mfma_f32_16x16x32_bf16 v[28:31], v[168:171], v[212:215], v[28:31]
	v_mfma_f32_16x16x32_bf16 v[24:27], v[176:179], v[212:215], v[24:27]
	v_mfma_f32_16x16x32_bf16 v[20:23], v[180:183], v[212:215], v[20:23]
	v_mfma_f32_16x16x32_bf16 v[16:19], v[184:187], v[212:215], v[16:19]
	ds_read_b128 v[212:215], v225 offset:12288
	s_add_u32 s12, s98, 0x60000
	s_addc_u32 s13, s99, 0
	s_add_u32 m0, s97, 0x6000
	s_nop 0
	global_load_lds_dwordx4 v224, s[12:13]
	v_mfma_f32_16x16x32_bf16 v[12:15], v[168:171], v[220:223], v[12:15]
	v_mfma_f32_16x16x32_bf16 v[8:11], v[176:179], v[220:223], v[8:11]
	v_mfma_f32_16x16x32_bf16 v[4:7], v[180:183], v[220:223], v[4:7]
	v_mfma_f32_16x16x32_bf16 v[0:3], v[184:187], v[220:223], v[0:3]
	s_add_u32 s12, s100, 0x60000
	s_addc_u32 s13, s101, 0
	s_add_u32 m0, s97, 0x16000
	s_nop 0
	global_load_lds_dwordx4 v224, s[12:13]
	v_xor_b32_e32 v225, 0x8000, v225
	v_xor_b32_e32 v227, 0x8000, v227
	v_xor_b32_e32 v226, 0x8000, v226
	v_xor_b32_e32 v228, 0x8000, v228
	s_xor_b32 s97, s97, 0x8000
	s_add_u32 s98, s98, 0x80
	s_addc_u32 s99, s99, 0
	s_add_u32 s100, s100, 0x80
	s_addc_u32 s101, s101, 0
	s_sub_u32 s28, s28, 1
	s_cmp_lg_u32 s28, 0
	s_cbranch_scc1 .Lgm0_loop
; #define G_LOAD(KT) do { _Pragma("unroll") for (int i = 0; i < 4; ++i) { ra[i] = *(const u32x4*)(Ag + (size_t)i * 64 * lda + (KT) * 64); rb[i] = *(const u32x4*)(Bg + (size_t)i * 64 * K + (KT) * 64); } } while (0)
; #define G_STORE(BUF) do { u16* ad = As + (BUF) * 256 * 64 + sto; u16* bd = Bs + (BUF) * 256 * 64 + sto; _Pragma("unroll") for (int i = 0; i < 4; ++i) { *(u32x4*)(ad + i * 64 * 64) = ra[i]; *(u32x4*)(bd + i * 64 * 64) = rb[i]; } } while (0)
; template <int EPI>
; DI void gemm_phase(const u16* __restrict__ A, int lda, const u16* __restrict__ Bt, int K, int N, u16* outb, int ldo,
;                    const float* r0, const float* r1, float* outf, char* lds, int bid, int nb) {
;     ...
;     G_LOAD(0);
;     G_STORE(0);
;     __syncthreads();
;     for (int kt = 0; kt < nk; ++kt) {
;       const int cur = kt & 1;
;       if (kt + 1 < nk) G_LOAD(kt + 1);
;       G_MMA(cur, fo0);
;       G_MMA(cur, fo1);
;       if (kt + 1 < nk) G_STORE(cur ^ 1);
;       __syncthreads();
;     }
	s_waitcnt lgkmcnt(4)
	v_mfma_f32_16x16x32_bf16 v[124:127], v[152:155], v[188:191], v[124:127]
	v_mfma_f32_16x16x32_bf16 v[120:123], v[156:159], v[188:191], v[120:123]
	v_mfma_f32_16x16x32_bf16 v[116:119], v[160:163], v[188:191], v[116:119]
	v_mfma_f32_16x16x32_bf16 v[112:115], v[164:167], v[188:191], v[112:115]
	ds_read_b128 v[188:191], v226 offset:0
	ds_read_b128 v[168:171], v228 offset:0
	v_mfma_f32_16x16x32_bf16 v[108:111], v[152:155], v[192:195], v[108:111]
	v_mfma_f32_16x16x32_bf16 v[104:107], v[156:159], v[192:195], v[104:107]
	v_mfma_f32_16x16x32_bf16 v[100:103], v[160:163], v[192:195], v[100:103]
	v_mfma_f32_16x16x32_bf16 v[96:99], v[164:167], v[192:195], v[96:99]
	ds_read_b128 v[192:195], v226 offset:2048
	ds_read_b128 v[176:179], v228 offset:2048
	v_mfma_f32_16x16x32_bf16 v[92:95], v[152:155], v[196:199], v[92:95]
	v_mfma_f32_16x16x32_bf16 v[88:91], v[156:159], v[196:199], v[88:91]
	v_mfma_f32_16x16x32_bf16 v[84:87], v[160:163], v[196:199], v[84:87]
	v_mfma_f32_16x16x32_bf16 v[80:83], v[164:167], v[196:199], v[80:83]
	ds_read_b128 v[196:199], v226 offset:4096
	ds_read_b128 v[180:183], v228 offset:4096
	v_mfma_f32_16x16x32_bf16 v[76:79], v[152:155], v[200:203], v[76:79]
	v_mfma_f32_16x16x32_bf16 v[72:75], v[156:159], v[200:203], v[72:75]
	v_mfma_f32_16x16x32_bf16 v[68:71], v[160:163], v[200:203], v[68:71]
	v_mfma_f32_16x16x32_bf16 v[64:67], v[164:167], v[200:203], v[64:67]
	ds_read_b128 v[200:203], v226 offset:6144
	ds_read_b128 v[184:187], v228 offset:6144
	s_waitcnt lgkmcnt(11)
	v_mfma_f32_16x16x32_bf16 v[60:63], v[152:155], v[204:207], v[60:63]
	v_mfma_f32_16x16x32_bf16 v[56:59], v[156:159], v[204:207], v[56:59]
	v_mfma_f32_16x16x32_bf16 v[52:55], v[160:163], v[204:207], v[52:55]
	v_mfma_f32_16x16x32_bf16 v[48:51], v[164:167], v[204:207], v[48:51]
	ds_read_b128 v[204:207], v226 offset:8192
	ds_read_b128 v[220:223], v226 offset:14336
	s_waitcnt lgkmcnt(11)
	v_mfma_f32_16x16x32_bf16 v[44:47], v[152:155], v[208:211], v[44:47]
	v_mfma_f32_16x16x32_bf16 v[40:43], v[156:159], v[208:211], v[40:43]
	v_mfma_f32_16x16x32_bf16 v[36:39], v[160:163], v[208:211], v[36:39]
	v_mfma_f32_16x16x32_bf16 v[32:35], v[164:167], v[208:211], v[32:35]
	ds_read_b128 v[208:211], v226 offset:10240
	s_waitcnt lgkmcnt(11)
	v_mfma_f32_16x16x32_bf16 v[28:31], v[152:155], v[212:215], v[28:31]
	v_mfma_f32_16x16x32_bf16 v[24:27], v[156:159], v[212:215], v[24:27]
	v_mfma_f32_16x16x32_bf16 v[20:23], v[160:163], v[212:215], v[20:23]
	v_mfma_f32_16x16x32_bf16 v[16:19], v[164:167], v[212:215], v[16:19]
	ds_read_b128 v[212:215], v226 offset:12288
	v_mfma_f32_16x16x32_bf16 v[12:15], v[152:155], v[216:219], v[12:15]
	v_mfma_f32_16x16x32_bf16 v[8:11], v[156:159], v[216:219], v[8:11]
	v_mfma_f32_16x16x32_bf16 v[4:7], v[160:163], v[216:219], v[4:7]
	v_mfma_f32_16x16x32_bf16 v[0:3], v[164:167], v[216:219], v[0:3]
	s_waitcnt vmcnt(0) lgkmcnt(0)
	s_barrier
	v_mfma_f32_16x16x32_bf16 v[124:127], v[168:171], v[188:191], v[124:127]
	v_mfma_f32_16x16x32_bf16 v[120:123], v[176:179], v[188:191], v[120:123]
	v_mfma_f32_16x16x32_bf16 v[116:119], v[180:183], v[188:191], v[116:119]
	v_mfma_f32_16x16x32_bf16 v[112:115], v[184:187], v[188:191], v[112:115]
	ds_read_b128 v[188:191], v225 offset:0
	ds_read_b128 v[152:155], v227 offset:0
	v_mfma_f32_16x16x32_bf16 v[108:111], v[168:171], v[192:195], v[108:111]
	v_mfma_f32_16x16x32_bf16 v[104:107], v[176:179], v[192:195], v[104:107]
	v_mfma_f32_16x16x32_bf16 v[100:103], v[180:183], v[192:195], v[100:103]
	v_mfma_f32_16x16x32_bf16 v[96:99], v[184:187], v[192:195], v[96:99]
	ds_read_b128 v[192:195], v225 offset:2048
	ds_read_b128 v[156:159], v227 offset:2048
	v_mfma_f32_16x16x32_bf16 v[92:95], v[168:171], v[196:199], v[92:95]
	v_mfma_f32_16x16x32_bf16 v[88:91], v[176:179], v[196:199], v[88:91]
	v_mfma_f32_16x16x32_bf16 v[84:87], v[180:183], v[196:199], v[84:87]
	v_mfma_f32_16x16x32_bf16 v[80:83], v[184:187], v[196:199], v[80:83]
	ds_read_b128 v[196:199], v225 offset:4096
	ds_read_b128 v[160:163], v227 offset:4096
	v_mfma_f32_16x16x32_bf16 v[76:79], v[168:171], v[200:203], v[76:79]
	v_mfma_f32_16x16x32_bf16 v[72:75], v[176:179], v[200:203], v[72:75]
	v_mfma_f32_16x16x32_bf16 v[68:71], v[180:183], v[200:203], v[68:71]
	v_mfma_f32_16x16x32_bf16 v[64:67], v[184:187], v[200:203], v[64:67]
	ds_read_b128 v[200:203], v225 offset:6144
	ds_read_b128 v[164:167], v227 offset:6144
	v_mfma_f32_16x16x32_bf16 v[60:63], v[168:171], v[204:207], v[60:63]
	v_mfma_f32_16x16x32_bf16 v[56:59], v[176:179], v[204:207], v[56:59]
	v_mfma_f32_16x16x32_bf16 v[52:55], v[180:183], v[204:207], v[52:55]
	v_mfma_f32_16x16x32_bf16 v[48:51], v[184:187], v[204:207], v[48:51]
	ds_read_b128 v[204:207], v225 offset:8192
	ds_read_b128 v[216:219], v225 offset:14336
	v_mfma_f32_16x16x32_bf16 v[44:47], v[168:171], v[208:211], v[44:47]
	v_mfma_f32_16x16x32_bf16 v[40:43], v[176:179], v[208:211], v[40:43]
	v_mfma_f32_16x16x32_bf16 v[36:39], v[180:183], v[208:211], v[36:39]
	v_mfma_f32_16x16x32_bf16 v[32:35], v[184:187], v[208:211], v[32:35]
	ds_read_b128 v[208:211], v225 offset:10240
	v_mfma_f32_16x16x32_bf16 v[28:31], v[168:171], v[212:215], v[28:31]
	v_mfma_f32_16x16x32_bf16 v[24:27], v[176:179], v[212:215], v[24:27]
	v_mfma_f32_16x16x32_bf16 v[20:23], v[180:183], v[212:215], v[20:23]
	v_mfma_f32_16x16x32_bf16 v[16:19], v[184:187], v[212:215], v[16:19]
	ds_read_b128 v[212:215], v225 offset:12288
	v_mfma_f32_16x16x32_bf16 v[12:15], v[168:171], v[220:223], v[12:15]
	v_mfma_f32_16x16x32_bf16 v[8:11], v[176:179], v[220:223], v[8:11]
	v_mfma_f32_16x16x32_bf16 v[4:7], v[180:183], v[220:223], v[4:7]
	v_mfma_f32_16x16x32_bf16 v[0:3], v[184:187], v[220:223], v[0:3]
	v_xor_b32_e32 v226, 0x8000, v226
	v_xor_b32_e32 v228, 0x8000, v228
	s_waitcnt lgkmcnt(4)
; #define G_LOAD(KT) do { _Pragma("unroll") for (int i = 0; i < 4; ++i) { ra[i] = *(const u32x4*)(Ag + (size_t)i * 64 * lda + (KT) * 64); rb[i] = *(const u32x4*)(Bg + (size_t)i * 64 * K + (KT) * 64); } } while (0)
; #define G_STORE(BUF) do { u16* ad = As + (BUF) * 256 * 64 + sto; u16* bd = Bs + (BUF) * 256 * 64 + sto; _Pragma("unroll") for (int i = 0; i < 4; ++i) { *(u32x4*)(ad + i * 64 * 64) = ra[i]; *(u32x4*)(bd + i * 64 * 64) = rb[i]; } } while (0)
; template <int EPI>
; DI void gemm_phase(const u16* __restrict__ A, int lda, const u16* __restrict__ Bt, int K, int N, u16* outb, int ldo,
;                    const float* r0, const float* r1, float* outf, char* lds, int bid, int nb) {
;     ...
;     G_LOAD(0);
;     G_STORE(0);
;     __syncthreads();
;     for (int kt = 0; kt < nk; ++kt) {
;       const int cur = kt & 1;
;       if (kt + 1 < nk) G_LOAD(kt + 1);
;       G_MMA(cur, fo0);
;       G_MMA(cur, fo1);
;       if (kt + 1 < nk) G_STORE(cur ^ 1);
;       __syncthreads();
;     }
	v_mfma_f32_16x16x32_bf16 v[124:127], v[152:155], v[188:191], v[124:127]
	v_mfma_f32_16x16x32_bf16 v[120:123], v[156:159], v[188:191], v[120:123]
	v_mfma_f32_16x16x32_bf16 v[116:119], v[160:163], v[188:191], v[116:119]
	v_mfma_f32_16x16x32_bf16 v[112:115], v[164:167], v[188:191], v[112:115]
	ds_read_b128 v[188:191], v226 offset:0
	ds_read_b128 v[168:171], v228 offset:0
	v_mfma_f32_16x16x32_bf16 v[108:111], v[152:155], v[192:195], v[108:111]
	v_mfma_f32_16x16x32_bf16 v[104:107], v[156:159], v[192:195], v[104:107]
	v_mfma_f32_16x16x32_bf16 v[100:103], v[160:163], v[192:195], v[100:103]
	v_mfma_f32_16x16x32_bf16 v[96:99], v[164:167], v[192:195], v[96:99]
	ds_read_b128 v[192:195], v226 offset:2048
	ds_read_b128 v[176:179], v228 offset:2048
	v_mfma_f32_16x16x32_bf16 v[92:95], v[152:155], v[196:199], v[92:95]
	v_mfma_f32_16x16x32_bf16 v[88:91], v[156:159], v[196:199], v[88:91]
	v_mfma_f32_16x16x32_bf16 v[84:87], v[160:163], v[196:199], v[84:87]
	v_mfma_f32_16x16x32_bf16 v[80:83], v[164:167], v[196:199], v[80:83]
	ds_read_b128 v[196:199], v226 offset:4096
	ds_read_b128 v[180:183], v228 offset:4096
	v_mfma_f32_16x16x32_bf16 v[76:79], v[152:155], v[200:203], v[76:79]
	v_mfma_f32_16x16x32_bf16 v[72:75], v[156:159], v[200:203], v[72:75]
	v_mfma_f32_16x16x32_bf16 v[68:71], v[160:163], v[200:203], v[68:71]
	v_mfma_f32_16x16x32_bf16 v[64:67], v[164:167], v[200:203], v[64:67]
	ds_read_b128 v[200:203], v226 offset:6144
	ds_read_b128 v[184:187], v228 offset:6144
	s_waitcnt lgkmcnt(11)
	v_mfma_f32_16x16x32_bf16 v[60:63], v[152:155], v[204:207], v[60:63]
	v_mfma_f32_16x16x32_bf16 v[56:59], v[156:159], v[204:207], v[56:59]
	v_mfma_f32_16x16x32_bf16 v[52:55], v[160:163], v[204:207], v[52:55]
	v_mfma_f32_16x16x32_bf16 v[48:51], v[164:167], v[204:207], v[48:51]
	ds_read_b128 v[204:207], v226 offset:8192
	ds_read_b128 v[220:223], v226 offset:14336
	s_waitcnt lgkmcnt(11)
	v_mfma_f32_16x16x32_bf16 v[44:47], v[152:155], v[208:211], v[44:47]
	v_mfma_f32_16x16x32_bf16 v[40:43], v[156:159], v[208:211], v[40:43]
	v_mfma_f32_16x16x32_bf16 v[36:39], v[160:163], v[208:211], v[36:39]
	v_mfma_f32_16x16x32_bf16 v[32:35], v[164:167], v[208:211], v[32:35]
	ds_read_b128 v[208:211], v226 offset:10240
	s_waitcnt lgkmcnt(11)
	v_mfma_f32_16x16x32_bf16 v[28:31], v[152:155], v[212:215], v[28:31]
	v_mfma_f32_16x16x32_bf16 v[24:27], v[156:159], v[212:215], v[24:27]
	v_mfma_f32_16x16x32_bf16 v[20:23], v[160:163], v[212:215], v[20:23]
	v_mfma_f32_16x16x32_bf16 v[16:19], v[164:167], v[212:215], v[16:19]
	ds_read_b128 v[212:215], v226 offset:12288
	v_mfma_f32_16x16x32_bf16 v[12:15], v[152:155], v[216:219], v[12:15]
	v_mfma_f32_16x16x32_bf16 v[8:11], v[156:159], v[216:219], v[8:11]
	v_mfma_f32_16x16x32_bf16 v[4:7], v[160:163], v[216:219], v[4:7]
	v_mfma_f32_16x16x32_bf16 v[0:3], v[164:167], v[216:219], v[0:3]
	s_waitcnt vmcnt(0) lgkmcnt(0)
	s_barrier
; DI u16 f2bf(float a) { return (u16)(pk2(a, 0.f) & 0xffffu); }
; template <int EPI>
; DI void gemm_phase(const u16* __restrict__ A, int lda, const u16* __restrict__ Bt, int K, int N, u16* outb, int ldo,
;                    const float* r0, const float* r1, float* outf, char* lds, int bid, int nb) {
;     ...
;     const int mrow = tm * 256 + wr * 128 + quad * 4;
;     if constexpr (EPI == EPI_BF16) {
;       const int col = tn * 256 + wc * 64 + l15;
; #pragma unroll
;       for (int i = 0; i < 8; ++i)
; #pragma unroll
;         for (int r = 0; r < 4; ++r) {
;           u16* o0 = outb + (size_t)(mrow + i * 16 + r) * ldo + col;
;           o0[0] = f2bf(acc[i][0][r]); o0[16] = f2bf(acc[i][1][r]); o0[32] = f2bf(acc[i][2][r]); o0[48] = f2bf(acc[i][3][r]);
;         }
	v_mfma_f32_16x16x32_bf16 v[124:127], v[168:171], v[188:191], v[124:127]
	v_mfma_f32_16x16x32_bf16 v[120:123], v[176:179], v[188:191], v[120:123]
	v_mfma_f32_16x16x32_bf16 v[116:119], v[180:183], v[188:191], v[116:119]
	v_mfma_f32_16x16x32_bf16 v[112:115], v[184:187], v[188:191], v[112:115]
	v_mfma_f32_16x16x32_bf16 v[108:111], v[168:171], v[192:195], v[108:111]
	v_mfma_f32_16x16x32_bf16 v[104:107], v[176:179], v[192:195], v[104:107]
	v_mfma_f32_16x16x32_bf16 v[100:103], v[180:183], v[192:195], v[100:103]
	v_mfma_f32_16x16x32_bf16 v[96:99], v[184:187], v[192:195], v[96:99]
	v_mfma_f32_16x16x32_bf16 v[92:95], v[168:171], v[196:199], v[92:95]
	v_mfma_f32_16x16x32_bf16 v[88:91], v[176:179], v[196:199], v[88:91]
	v_mfma_f32_16x16x32_bf16 v[84:87], v[180:183], v[196:199], v[84:87]
	v_mfma_f32_16x16x32_bf16 v[80:83], v[184:187], v[196:199], v[80:83]
	v_mfma_f32_16x16x32_bf16 v[76:79], v[168:171], v[200:203], v[76:79]
	v_mfma_f32_16x16x32_bf16 v[72:75], v[176:179], v[200:203], v[72:75]
	v_mfma_f32_16x16x32_bf16 v[68:71], v[180:183], v[200:203], v[68:71]
	v_mfma_f32_16x16x32_bf16 v[64:67], v[184:187], v[200:203], v[64:67]
	v_mfma_f32_16x16x32_bf16 v[60:63], v[168:171], v[204:207], v[60:63]
	v_mfma_f32_16x16x32_bf16 v[56:59], v[176:179], v[204:207], v[56:59]
	v_mfma_f32_16x16x32_bf16 v[52:55], v[180:183], v[204:207], v[52:55]
	v_mfma_f32_16x16x32_bf16 v[48:51], v[184:187], v[204:207], v[48:51]
	v_mfma_f32_16x16x32_bf16 v[44:47], v[168:171], v[208:211], v[44:47]
	v_mfma_f32_16x16x32_bf16 v[40:43], v[176:179], v[208:211], v[40:43]
	v_mfma_f32_16x16x32_bf16 v[36:39], v[180:183], v[208:211], v[36:39]
	v_mfma_f32_16x16x32_bf16 v[32:35], v[184:187], v[208:211], v[32:35]
	v_mfma_f32_16x16x32_bf16 v[28:31], v[168:171], v[212:215], v[28:31]
	v_mfma_f32_16x16x32_bf16 v[24:27], v[176:179], v[212:215], v[24:27]
	v_mfma_f32_16x16x32_bf16 v[20:23], v[180:183], v[212:215], v[20:23]
	v_mfma_f32_16x16x32_bf16 v[16:19], v[184:187], v[212:215], v[16:19]
	v_mfma_f32_16x16x32_bf16 v[12:15], v[168:171], v[220:223], v[12:15]
	v_mfma_f32_16x16x32_bf16 v[8:11], v[176:179], v[220:223], v[8:11]
	v_mfma_f32_16x16x32_bf16 v[4:7], v[180:183], v[220:223], v[4:7]
	v_mfma_f32_16x16x32_bf16 v[0:3], v[184:187], v[220:223], v[0:3]
	s_nop 7
	s_nop 3
	v_and_b32_e32 v225, 15, v174
	v_lshrrev_b32_e32 v226, 8, v174
	v_lshl_or_b32 v225, v226, 7, v225
	v_bfe_u32 v226, v174, 6, 2
	v_bfe_u32 v227, v174, 4, 2
	v_lshlrev_b32_e32 v227, 2, v227
	v_add_u32_e32 v225, s56, v225
	v_lshl_add_u32 v226, v226, 6, v227
	v_add_u32_e32 v226, s57, v226
	v_lshlrev_b32_e32 v226, 1, v226
	v_mov_b32_e32 v227, 0x1400
	v_mad_u32_u24 v224, v225, v227, v226
	v_cvt_pk_bf16_f32 v188, v124, v125
	v_cvt_pk_bf16_f32 v189, v126, v127
	global_store_dwordx2 v224, v[188:189], s[8:9] offset:0
	v_cvt_pk_bf16_f32 v190, v120, v121
	v_cvt_pk_bf16_f32 v191, v122, v123
	global_store_dwordx2 v224, v[190:191], s[8:9] offset:32
	v_cvt_pk_bf16_f32 v192, v116, v117
	v_cvt_pk_bf16_f32 v193, v118, v119
	global_store_dwordx2 v224, v[192:193], s[8:9] offset:64
	v_cvt_pk_bf16_f32 v194, v112, v113
	v_cvt_pk_bf16_f32 v195, v114, v115
	global_store_dwordx2 v224, v[194:195], s[8:9] offset:96
	v_add_u32_e32 v224, 0x14000, v224
	v_cvt_pk_bf16_f32 v196, v108, v109
	v_cvt_pk_bf16_f32 v197, v110, v111
	global_store_dwordx2 v224, v[196:197], s[8:9] offset:0
	v_cvt_pk_bf16_f32 v198, v104, v105
	v_cvt_pk_bf16_f32 v199, v106, v107
	global_store_dwordx2 v224, v[198:199], s[8:9] offset:32
	v_cvt_pk_bf16_f32 v200, v100, v101
	v_cvt_pk_bf16_f32 v201, v102, v103
	global_store_dwordx2 v224, v[200:201], s[8:9] offset:64
	v_cvt_pk_bf16_f32 v202, v96, v97
	v_cvt_pk_bf16_f32 v203, v98, v99
	global_store_dwordx2 v224, v[202:203], s[8:9] offset:96
	v_add_u32_e32 v224, 0x14000, v224
	v_cvt_pk_bf16_f32 v204, v92, v93
	v_cvt_pk_bf16_f32 v205, v94, v95
	global_store_dwordx2 v224, v[204:205], s[8:9] offset:0
	v_cvt_pk_bf16_f32 v206, v88, v89
	v_cvt_pk_bf16_f32 v207, v90, v91
	global_store_dwordx2 v224, v[206:207], s[8:9] offset:32
	v_cvt_pk_bf16_f32 v208, v84, v85
	v_cvt_pk_bf16_f32 v209, v86, v87
	global_store_dwordx2 v224, v[208:209], s[8:9] offset:64
	v_cvt_pk_bf16_f32 v210, v80, v81
	v_cvt_pk_bf16_f32 v211, v82, v83
	global_store_dwordx2 v224, v[210:211], s[8:9] offset:96
	v_add_u32_e32 v224, 0x14000, v224
	v_cvt_pk_bf16_f32 v212, v76, v77
	v_cvt_pk_bf16_f32 v213, v78, v79
	global_store_dwordx2 v224, v[212:213], s[8:9] offset:0
	v_cvt_pk_bf16_f32 v214, v72, v73
	v_cvt_pk_bf16_f32 v215, v74, v75
	global_store_dwordx2 v224, v[214:215], s[8:9] offset:32
	v_cvt_pk_bf16_f32 v216, v68, v69
	v_cvt_pk_bf16_f32 v217, v70, v71
	global_store_dwordx2 v224, v[216:217], s[8:9] offset:64
	v_cvt_pk_bf16_f32 v218, v64, v65
	v_cvt_pk_bf16_f32 v219, v66, v67
	global_store_dwordx2 v224, v[218:219], s[8:9] offset:96
	v_add_u32_e32 v224, 0x14000, v224
	v_cvt_pk_bf16_f32 v188, v60, v61
	v_cvt_pk_bf16_f32 v189, v62, v63
	global_store_dwordx2 v224, v[188:189], s[8:9] offset:0
	v_cvt_pk_bf16_f32 v190, v56, v57
	v_cvt_pk_bf16_f32 v191, v58, v59
	global_store_dwordx2 v224, v[190:191], s[8:9] offset:32
	v_cvt_pk_bf16_f32 v192, v52, v53
	v_cvt_pk_bf16_f32 v193, v54, v55
	global_store_dwordx2 v224, v[192:193], s[8:9] offset:64
	v_cvt_pk_bf16_f32 v194, v48, v49
	v_cvt_pk_bf16_f32 v195, v50, v51
	global_store_dwordx2 v224, v[194:195], s[8:9] offset:96
	v_add_u32_e32 v224, 0x14000, v224
	v_cvt_pk_bf16_f32 v196, v44, v45
	v_cvt_pk_bf16_f32 v197, v46, v47
	global_store_dwordx2 v224, v[196:197], s[8:9] offset:0
	v_cvt_pk_bf16_f32 v198, v40, v41
	v_cvt_pk_bf16_f32 v199, v42, v43
	global_store_dwordx2 v224, v[198:199], s[8:9] offset:32
	v_cvt_pk_bf16_f32 v200, v36, v37
	v_cvt_pk_bf16_f32 v201, v38, v39
	global_store_dwordx2 v224, v[200:201], s[8:9] offset:64
	v_cvt_pk_bf16_f32 v202, v32, v33
	v_cvt_pk_bf16_f32 v203, v34, v35
	global_store_dwordx2 v224, v[202:203], s[8:9] offset:96
	v_add_u32_e32 v224, 0x14000, v224
	v_cvt_pk_bf16_f32 v204, v28, v29
	v_cvt_pk_bf16_f32 v205, v30, v31
	global_store_dwordx2 v224, v[204:205], s[8:9] offset:0
	v_cvt_pk_bf16_f32 v206, v24, v25
	v_cvt_pk_bf16_f32 v207, v26, v27
	global_store_dwordx2 v224, v[206:207], s[8:9] offset:32
	v_cvt_pk_bf16_f32 v208, v20, v21
	v_cvt_pk_bf16_f32 v209, v22, v23
	global_store_dwordx2 v224, v[208:209], s[8:9] offset:64
	v_cvt_pk_bf16_f32 v210, v16, v17
	v_cvt_pk_bf16_f32 v211, v18, v19
	global_store_dwordx2 v224, v[210:211], s[8:9] offset:96
	v_add_u32_e32 v224, 0x14000, v224
	v_cvt_pk_bf16_f32 v212, v12, v13
	v_cvt_pk_bf16_f32 v213, v14, v15
	global_store_dwordx2 v224, v[212:213], s[8:9] offset:0
	v_cvt_pk_bf16_f32 v214, v8, v9
	v_cvt_pk_bf16_f32 v215, v10, v11
	global_store_dwordx2 v224, v[214:215], s[8:9] offset:32
	v_cvt_pk_bf16_f32 v216, v4, v5
	v_cvt_pk_bf16_f32 v217, v6, v7
	global_store_dwordx2 v224, v[216:217], s[8:9] offset:64
	v_cvt_pk_bf16_f32 v218, v0, v1
	v_cvt_pk_bf16_f32 v219, v2, v3
	global_store_dwordx2 v224, v[218:219], s[8:9] offset:96
	s_add_i32 s18, s18, 1
	s_cmp_eq_u32 s18, s14
	s_cbranch_scc0 .LBB0_283

; #define G_LOAD(KT) do { _Pragma("unroll") for (int i = 0; i < 4; ++i) { ra[i] = *(const u32x4*)(Ag + (size_t)i * 64 * lda + (KT) * 64); rb[i] = *(const u32x4*)(Bg + (size_t)i * 64 * K + (KT) * 64); } } while (0)
; #define G_STORE(BUF) do { u16* ad = As + (BUF) * 256 * 64 + sto; u16* bd = Bs + (BUF) * 256 * 64 + sto; _Pragma("unroll") for (int i = 0; i < 4; ++i) { *(u32x4*)(ad + i * 64 * 64) = ra[i]; *(u32x4*)(bd + i * 64 * 64) = rb[i]; } } while (0)
; template <int EPI>
; DI void gemm_phase(const u16* __restrict__ A, int lda, const u16* __restrict__ Bt, int K, int N, u16* outb, int ldo,
;                    const float* r0, const float* r1, float* outf, char* lds, int bid, int nb) {
;     ...
;     G_LOAD(0);
;     G_STORE(0);
;     __syncthreads();
;     for (int kt = 0; kt < nk; ++kt) {
;       const int cur = kt & 1;
;       if (kt + 1 < nk) G_LOAD(kt + 1);
;       G_MMA(cur, fo0);
;       G_MMA(cur, fo1);
;       if (kt + 1 < nk) G_STORE(cur ^ 1);
;       __syncthreads();
;     }
.Lgm1_loop:
	s_waitcnt lgkmcnt(4)
	v_mfma_f32_16x16x32_bf16 v[124:127], v[152:155], v[188:191], v[124:127]
	v_mfma_f32_16x16x32_bf16 v[120:123], v[156:159], v[188:191], v[120:123]
	v_mfma_f32_16x16x32_bf16 v[116:119], v[160:163], v[188:191], v[116:119]
	v_mfma_f32_16x16x32_bf16 v[112:115], v[164:167], v[188:191], v[112:115]
	ds_read_b128 v[188:191], v226 offset:0
	ds_read_b128 v[168:171], v228 offset:0
	v_mfma_f32_16x16x32_bf16 v[108:111], v[152:155], v[192:195], v[108:111]
	v_mfma_f32_16x16x32_bf16 v[104:107], v[156:159], v[192:195], v[104:107]
	v_mfma_f32_16x16x32_bf16 v[100:103], v[160:163], v[192:195], v[100:103]
	v_mfma_f32_16x16x32_bf16 v[96:99], v[164:167], v[192:195], v[96:99]
	ds_read_b128 v[192:195], v226 offset:2048
	ds_read_b128 v[176:179], v228 offset:2048
	v_mfma_f32_16x16x32_bf16 v[92:95], v[152:155], v[196:199], v[92:95]
	v_mfma_f32_16x16x32_bf16 v[88:91], v[156:159], v[196:199], v[88:91]
	v_mfma_f32_16x16x32_bf16 v[84:87], v[160:163], v[196:199], v[84:87]
	v_mfma_f32_16x16x32_bf16 v[80:83], v[164:167], v[196:199], v[80:83]
	ds_read_b128 v[196:199], v226 offset:4096
	ds_read_b128 v[180:183], v228 offset:4096
	v_mfma_f32_16x16x32_bf16 v[76:79], v[152:155], v[200:203], v[76:79]
	v_mfma_f32_16x16x32_bf16 v[72:75], v[156:159], v[200:203], v[72:75]
	v_mfma_f32_16x16x32_bf16 v[68:71], v[160:163], v[200:203], v[68:71]
	v_mfma_f32_16x16x32_bf16 v[64:67], v[164:167], v[200:203], v[64:67]
	ds_read_b128 v[200:203], v226 offset:6144
	ds_read_b128 v[184:187], v228 offset:6144
	s_waitcnt lgkmcnt(11)
	v_mfma_f32_16x16x32_bf16 v[60:63], v[152:155], v[204:207], v[60:63]
	v_mfma_f32_16x16x32_bf16 v[56:59], v[156:159], v[204:207], v[56:59]
	v_mfma_f32_16x16x32_bf16 v[52:55], v[160:163], v[204:207], v[52:55]
	v_mfma_f32_16x16x32_bf16 v[48:51], v[164:167], v[204:207], v[48:51]
	ds_read_b128 v[204:207], v226 offset:8192
	ds_read_b128 v[220:223], v226 offset:14336
	s_waitcnt lgkmcnt(11)
	v_mfma_f32_16x16x32_bf16 v[44:47], v[152:155], v[208:211], v[44:47]
	v_mfma_f32_16x16x32_bf16 v[40:43], v[156:159], v[208:211], v[40:43]
	v_mfma_f32_16x16x32_bf16 v[36:39], v[160:163], v[208:211], v[36:39]
	v_mfma_f32_16x16x32_bf16 v[32:35], v[164:167], v[208:211], v[32:35]
	ds_read_b128 v[208:211], v226 offset:10240
	s_waitcnt lgkmcnt(11)
	v_mfma_f32_16x16x32_bf16 v[28:31], v[152:155], v[212:215], v[28:31]
	v_mfma_f32_16x16x32_bf16 v[24:27], v[156:159], v[212:215], v[24:27]
	v_mfma_f32_16x16x32_bf16 v[20:23], v[160:163], v[212:215], v[20:23]
	v_mfma_f32_16x16x32_bf16 v[16:19], v[164:167], v[212:215], v[16:19]
	ds_read_b128 v[212:215], v226 offset:12288
	v_mfma_f32_16x16x32_bf16 v[12:15], v[152:155], v[216:219], v[12:15]
	v_mfma_f32_16x16x32_bf16 v[8:11], v[156:159], v[216:219], v[8:11]
	v_mfma_f32_16x16x32_bf16 v[4:7], v[160:163], v[216:219], v[4:7]
	v_mfma_f32_16x16x32_bf16 v[0:3], v[164:167], v[216:219], v[0:3]
	s_waitcnt vmcnt(0) lgkmcnt(0)
	s_barrier
	v_mfma_f32_16x16x32_bf16 v[124:127], v[168:171], v[188:191], v[124:127]
	v_mfma_f32_16x16x32_bf16 v[120:123], v[176:179], v[188:191], v[120:123]
	v_mfma_f32_16x16x32_bf16 v[116:119], v[180:183], v[188:191], v[116:119]
	v_mfma_f32_16x16x32_bf16 v[112:115], v[184:187], v[188:191], v[112:115]
	ds_read_b128 v[188:191], v225 offset:0
	ds_read_b128 v[152:155], v227 offset:0
	s_add_u32 s8, s98, 0x0
	s_addc_u32 s9, s99, 0
	s_add_u32 m0, s97, 0x0
	s_nop 0
	global_load_lds_dwordx4 v224, s[8:9]
	v_mfma_f32_16x16x32_bf16 v[108:111], v[168:171], v[192:195], v[108:111]
	v_mfma_f32_16x16x32_bf16 v[104:107], v[176:179], v[192:195], v[104:107]
	v_mfma_f32_16x16x32_bf16 v[100:103], v[180:183], v[192:195], v[100:103]
	v_mfma_f32_16x16x32_bf16 v[96:99], v[184:187], v[192:195], v[96:99]
	ds_read_b128 v[192:195], v225 offset:2048
	ds_read_b128 v[156:159], v227 offset:2048
	s_add_u32 s8, s100, 0x0
	s_addc_u32 s9, s101, 0
	s_add_u32 m0, s97, 0x10000
	s_nop 0
	global_load_lds_dwordx4 v224, s[8:9]
	v_mfma_f32_16x16x32_bf16 v[92:95], v[168:171], v[196:199], v[92:95]
	v_mfma_f32_16x16x32_bf16 v[88:91], v[176:179], v[196:199], v[88:91]
	v_mfma_f32_16x16x32_bf16 v[84:87], v[180:183], v[196:199], v[84:87]
	v_mfma_f32_16x16x32_bf16 v[80:83], v[184:187], v[196:199], v[80:83]
	ds_read_b128 v[196:199], v225 offset:4096
	ds_read_b128 v[160:163], v227 offset:4096
	s_add_u32 s8, s98, 0x20000
	s_addc_u32 s9, s99, 0
	s_add_u32 m0, s97, 0x2000
	s_nop 0
	global_load_lds_dwordx4 v224, s[8:9]
	v_mfma_f32_16x16x32_bf16 v[76:79], v[168:171], v[200:203], v[76:79]
	v_mfma_f32_16x16x32_bf16 v[72:75], v[176:179], v[200:203], v[72:75]
	v_mfma_f32_16x16x32_bf16 v[68:71], v[180:183], v[200:203], v[68:71]
	v_mfma_f32_16x16x32_bf16 v[64:67], v[184:187], v[200:203], v[64:67]
	ds_read_b128 v[200:203], v225 offset:6144
	ds_read_b128 v[164:167], v227 offset:6144
	s_add_u32 s8, s100, 0x20000
	s_addc_u32 s9, s101, 0
	s_add_u32 m0, s97, 0x12000
	s_nop 0
	global_load_lds_dwordx4 v224, s[8:9]
	v_mfma_f32_16x16x32_bf16 v[60:63], v[168:171], v[204:207], v[60:63]
	v_mfma_f32_16x16x32_bf16 v[56:59], v[176:179], v[204:207], v[56:59]
	v_mfma_f32_16x16x32_bf16 v[52:55], v[180:183], v[204:207], v[52:55]
	v_mfma_f32_16x16x32_bf16 v[48:51], v[184:187], v[204:207], v[48:51]
	ds_read_b128 v[204:207], v225 offset:8192
	ds_read_b128 v[216:219], v225 offset:14336
	s_add_u32 s8, s98, 0x40000
	s_addc_u32 s9, s99, 0
	s_add_u32 m0, s97, 0x4000
	s_nop 0
	global_load_lds_dwordx4 v224, s[8:9]
	v_mfma_f32_16x16x32_bf16 v[44:47], v[168:171], v[208:211], v[44:47]
	v_mfma_f32_16x16x32_bf16 v[40:43], v[176:179], v[208:211], v[40:43]
	v_mfma_f32_16x16x32_bf16 v[36:39], v[180:183], v[208:211], v[36:39]
	v_mfma_f32_16x16x32_bf16 v[32:35], v[184:187], v[208:211], v[32:35]
	ds_read_b128 v[208:211], v225 offset:10240
	s_add_u32 s8, s100, 0x40000
	s_addc_u32 s9, s101, 0
	s_add_u32 m0, s97, 0x14000
	s_nop 0
	global_load_lds_dwordx4 v224, s[8:9]
	v_mfma_f32_16x16x32_bf16 v[28:31], v[168:171], v[212:215], v[28:31]
	v_mfma_f32_16x16x32_bf16 v[24:27], v[176:179], v[212:215], v[24:27]
	v_mfma_f32_16x16x32_bf16 v[20:23], v[180:183], v[212:215], v[20:23]
	v_mfma_f32_16x16x32_bf16 v[16:19], v[184:187], v[212:215], v[16:19]
	ds_read_b128 v[212:215], v225 offset:12288
	s_add_u32 s8, s98, 0x60000
	s_addc_u32 s9, s99, 0
	s_add_u32 m0, s97, 0x6000
	s_nop 0
	global_load_lds_dwordx4 v224, s[8:9]
	v_mfma_f32_16x16x32_bf16 v[12:15], v[168:171], v[220:223], v[12:15]
	v_mfma_f32_16x16x32_bf16 v[8:11], v[176:179], v[220:223], v[8:11]
	v_mfma_f32_16x16x32_bf16 v[4:7], v[180:183], v[220:223], v[4:7]
	v_mfma_f32_16x16x32_bf16 v[0:3], v[184:187], v[220:223], v[0:3]
	s_add_u32 s8, s100, 0x60000
	s_addc_u32 s9, s101, 0
	s_add_u32 m0, s97, 0x16000
	s_nop 0
	global_load_lds_dwordx4 v224, s[8:9]
	v_xor_b32_e32 v225, 0x8000, v225
	v_xor_b32_e32 v227, 0x8000, v227
	v_xor_b32_e32 v226, 0x8000, v226
	v_xor_b32_e32 v228, 0x8000, v228
	s_xor_b32 s97, s97, 0x8000
	s_add_u32 s98, s98, 0x80
	s_addc_u32 s99, s99, 0
	s_add_u32 s100, s100, 0x80
	s_addc_u32 s101, s101, 0
	s_sub_u32 s28, s28, 1
	s_cmp_lg_u32 s28, 0
	s_cbranch_scc1 .Lgm1_loop
; #define G_LOAD(KT) do { _Pragma("unroll") for (int i = 0; i < 4; ++i) { ra[i] = *(const u32x4*)(Ag + (size_t)i * 64 * lda + (KT) * 64); rb[i] = *(const u32x4*)(Bg + (size_t)i * 64 * K + (KT) * 64); } } while (0)
; #define G_STORE(BUF) do { u16* ad = As + (BUF) * 256 * 64 + sto; u16* bd = Bs + (BUF) * 256 * 64 + sto; _Pragma("unroll") for (int i = 0; i < 4; ++i) { *(u32x4*)(ad + i * 64 * 64) = ra[i]; *(u32x4*)(bd + i * 64 * 64) = rb[i]; } } while (0)
; template <int EPI>
; DI void gemm_phase(const u16* __restrict__ A, int lda, const u16* __restrict__ Bt, int K, int N, u16* outb, int ldo,
;                    const float* r0, const float* r1, float* outf, char* lds, int bid, int nb) {
;     ...
;     G_LOAD(0);
;     G_STORE(0);
;     __syncthreads();
;     for (int kt = 0; kt < nk; ++kt) {
;       const int cur = kt & 1;
;       if (kt + 1 < nk) G_LOAD(kt + 1);
;       G_MMA(cur, fo0);
;       G_MMA(cur, fo1);
;       if (kt + 1 < nk) G_STORE(cur ^ 1);
;       __syncthreads();
;     }
	s_waitcnt lgkmcnt(4)
	v_mfma_f32_16x16x32_bf16 v[124:127], v[152:155], v[188:191], v[124:127]
	v_mfma_f32_16x16x32_bf16 v[120:123], v[156:159], v[188:191], v[120:123]
	v_mfma_f32_16x16x32_bf16 v[116:119], v[160:163], v[188:191], v[116:119]
	v_mfma_f32_16x16x32_bf16 v[112:115], v[164:167], v[188:191], v[112:115]
	ds_read_b128 v[188:191], v226 offset:0
	ds_read_b128 v[168:171], v228 offset:0
	v_mfma_f32_16x16x32_bf16 v[108:111], v[152:155], v[192:195], v[108:111]
	v_mfma_f32_16x16x32_bf16 v[104:107], v[156:159], v[192:195], v[104:107]
	v_mfma_f32_16x16x32_bf16 v[100:103], v[160:163], v[192:195], v[100:103]
	v_mfma_f32_16x16x32_bf16 v[96:99], v[164:167], v[192:195], v[96:99]
	ds_read_b128 v[192:195], v226 offset:2048
	ds_read_b128 v[176:179], v228 offset:2048
	v_mfma_f32_16x16x32_bf16 v[92:95], v[152:155], v[196:199], v[92:95]
	v_mfma_f32_16x16x32_bf16 v[88:91], v[156:159], v[196:199], v[88:91]
	v_mfma_f32_16x16x32_bf16 v[84:87], v[160:163], v[196:199], v[84:87]
	v_mfma_f32_16x16x32_bf16 v[80:83], v[164:167], v[196:199], v[80:83]
	ds_read_b128 v[196:199], v226 offset:4096
	ds_read_b128 v[180:183], v228 offset:4096
	v_mfma_f32_16x16x32_bf16 v[76:79], v[152:155], v[200:203], v[76:79]
	v_mfma_f32_16x16x32_bf16 v[72:75], v[156:159], v[200:203], v[72:75]
	v_mfma_f32_16x16x32_bf16 v[68:71], v[160:163], v[200:203], v[68:71]
	v_mfma_f32_16x16x32_bf16 v[64:67], v[164:167], v[200:203], v[64:67]
	ds_read_b128 v[200:203], v226 offset:6144
	ds_read_b128 v[184:187], v228 offset:6144
	s_waitcnt lgkmcnt(11)
	v_mfma_f32_16x16x32_bf16 v[60:63], v[152:155], v[204:207], v[60:63]
	v_mfma_f32_16x16x32_bf16 v[56:59], v[156:159], v[204:207], v[56:59]
	v_mfma_f32_16x16x32_bf16 v[52:55], v[160:163], v[204:207], v[52:55]
	v_mfma_f32_16x16x32_bf16 v[48:51], v[164:167], v[204:207], v[48:51]
	ds_read_b128 v[204:207], v226 offset:8192
	ds_read_b128 v[220:223], v226 offset:14336
	s_waitcnt lgkmcnt(11)
	v_mfma_f32_16x16x32_bf16 v[44:47], v[152:155], v[208:211], v[44:47]
	v_mfma_f32_16x16x32_bf16 v[40:43], v[156:159], v[208:211], v[40:43]
	v_mfma_f32_16x16x32_bf16 v[36:39], v[160:163], v[208:211], v[36:39]
	v_mfma_f32_16x16x32_bf16 v[32:35], v[164:167], v[208:211], v[32:35]
	ds_read_b128 v[208:211], v226 offset:10240
	s_waitcnt lgkmcnt(11)
	v_mfma_f32_16x16x32_bf16 v[28:31], v[152:155], v[212:215], v[28:31]
	v_mfma_f32_16x16x32_bf16 v[24:27], v[156:159], v[212:215], v[24:27]
	v_mfma_f32_16x16x32_bf16 v[20:23], v[160:163], v[212:215], v[20:23]
	v_mfma_f32_16x16x32_bf16 v[16:19], v[164:167], v[212:215], v[16:19]
	ds_read_b128 v[212:215], v226 offset:12288
	v_mfma_f32_16x16x32_bf16 v[12:15], v[152:155], v[216:219], v[12:15]
	v_mfma_f32_16x16x32_bf16 v[8:11], v[156:159], v[216:219], v[8:11]
	v_mfma_f32_16x16x32_bf16 v[4:7], v[160:163], v[216:219], v[4:7]
	v_mfma_f32_16x16x32_bf16 v[0:3], v[164:167], v[216:219], v[0:3]
	s_waitcnt vmcnt(0) lgkmcnt(0)
	s_barrier
	v_mfma_f32_16x16x32_bf16 v[124:127], v[168:171], v[188:191], v[124:127]
	v_mfma_f32_16x16x32_bf16 v[120:123], v[176:179], v[188:191], v[120:123]
	v_mfma_f32_16x16x32_bf16 v[116:119], v[180:183], v[188:191], v[116:119]
	v_mfma_f32_16x16x32_bf16 v[112:115], v[184:187], v[188:191], v[112:115]
	ds_read_b128 v[188:191], v225 offset:0
	ds_read_b128 v[152:155], v227 offset:0
	v_mfma_f32_16x16x32_bf16 v[108:111], v[168:171], v[192:195], v[108:111]
	v_mfma_f32_16x16x32_bf16 v[104:107], v[176:179], v[192:195], v[104:107]
	v_mfma_f32_16x16x32_bf16 v[100:103], v[180:183], v[192:195], v[100:103]
	v_mfma_f32_16x16x32_bf16 v[96:99], v[184:187], v[192:195], v[96:99]
	ds_read_b128 v[192:195], v225 offset:2048
	ds_read_b128 v[156:159], v227 offset:2048
	v_mfma_f32_16x16x32_bf16 v[92:95], v[168:171], v[196:199], v[92:95]
	v_mfma_f32_16x16x32_bf16 v[88:91], v[176:179], v[196:199], v[88:91]
	v_mfma_f32_16x16x32_bf16 v[84:87], v[180:183], v[196:199], v[84:87]
	v_mfma_f32_16x16x32_bf16 v[80:83], v[184:187], v[196:199], v[80:83]
	ds_read_b128 v[196:199], v225 offset:4096
	ds_read_b128 v[160:163], v227 offset:4096
	v_mfma_f32_16x16x32_bf16 v[76:79], v[168:171], v[200:203], v[76:79]
	v_mfma_f32_16x16x32_bf16 v[72:75], v[176:179], v[200:203], v[72:75]
	v_mfma_f32_16x16x32_bf16 v[68:71], v[180:183], v[200:203], v[68:71]
	v_mfma_f32_16x16x32_bf16 v[64:67], v[184:187], v[200:203], v[64:67]
	ds_read_b128 v[200:203], v225 offset:6144
	ds_read_b128 v[164:167], v227 offset:6144
	v_mfma_f32_16x16x32_bf16 v[60:63], v[168:171], v[204:207], v[60:63]
	v_mfma_f32_16x16x32_bf16 v[56:59], v[176:179], v[204:207], v[56:59]
	v_mfma_f32_16x16x32_bf16 v[52:55], v[180:183], v[204:207], v[52:55]
	v_mfma_f32_16x16x32_bf16 v[48:51], v[184:187], v[204:207], v[48:51]
	ds_read_b128 v[204:207], v225 offset:8192
	ds_read_b128 v[216:219], v225 offset:14336
	v_mfma_f32_16x16x32_bf16 v[44:47], v[168:171], v[208:211], v[44:47]
	v_mfma_f32_16x16x32_bf16 v[40:43], v[176:179], v[208:211], v[40:43]
	v_mfma_f32_16x16x32_bf16 v[36:39], v[180:183], v[208:211], v[36:39]
	v_mfma_f32_16x16x32_bf16 v[32:35], v[184:187], v[208:211], v[32:35]
	ds_read_b128 v[208:211], v225 offset:10240
	v_mfma_f32_16x16x32_bf16 v[28:31], v[168:171], v[212:215], v[28:31]
	v_mfma_f32_16x16x32_bf16 v[24:27], v[176:179], v[212:215], v[24:27]
	v_mfma_f32_16x16x32_bf16 v[20:23], v[180:183], v[212:215], v[20:23]
	v_mfma_f32_16x16x32_bf16 v[16:19], v[184:187], v[212:215], v[16:19]
	ds_read_b128 v[212:215], v225 offset:12288
	v_mfma_f32_16x16x32_bf16 v[12:15], v[168:171], v[220:223], v[12:15]
	v_mfma_f32_16x16x32_bf16 v[8:11], v[176:179], v[220:223], v[8:11]
	v_mfma_f32_16x16x32_bf16 v[4:7], v[180:183], v[220:223], v[4:7]
	v_mfma_f32_16x16x32_bf16 v[0:3], v[184:187], v[220:223], v[0:3]
	v_xor_b32_e32 v226, 0x8000, v226
	v_xor_b32_e32 v228, 0x8000, v228
	s_waitcnt lgkmcnt(4)
; template <int EPI>
; DI void gemm_phase(const u16* __restrict__ A, int lda, const u16* __restrict__ Bt, int K, int N, u16* outb, int ldo,
;                    const float* r0, const float* r1, float* outf, char* lds, int bid, int nb) {
;     ...
;     } else if constexpr (EPI == EPI_RESID) {
;       const int col = tn * 256 + wc * 64 + l15;
;       const float* rb_ = (tm * 256 < M_P) ? r0 : (r1 - (size_t)M_P * DM);
; #pragma unroll
;       for (int i = 0; i < 8; ++i)
; #pragma unroll
;         for (int r = 0; r < 4; ++r) {
;           const size_t i0 = (size_t)(mrow + i * 16 + r) * DM + col;
;           const float x0 = rb_[i0], x1 = rb_[i0 + 16], x2 = rb_[i0 + 32], x3 = rb_[i0 + 48];
;           outf[i0] = x0 + acc[i][0][r]; outf[i0 + 16] = x1 + acc[i][1][r]; outf[i0 + 32] = x2 + acc[i][2][r]; outf[i0 + 48] = x3 + acc[i][3][r];
	v_mfma_f32_16x16x32_bf16 v[124:127], v[152:155], v[188:191], v[124:127]
	v_mfma_f32_16x16x32_bf16 v[120:123], v[156:159], v[188:191], v[120:123]
	v_mfma_f32_16x16x32_bf16 v[116:119], v[160:163], v[188:191], v[116:119]
	v_mfma_f32_16x16x32_bf16 v[112:115], v[164:167], v[188:191], v[112:115]
	ds_read_b128 v[188:191], v226 offset:0
	ds_read_b128 v[168:171], v228 offset:0
	v_mfma_f32_16x16x32_bf16 v[108:111], v[152:155], v[192:195], v[108:111]
	v_mfma_f32_16x16x32_bf16 v[104:107], v[156:159], v[192:195], v[104:107]
	v_mfma_f32_16x16x32_bf16 v[100:103], v[160:163], v[192:195], v[100:103]
	v_mfma_f32_16x16x32_bf16 v[96:99], v[164:167], v[192:195], v[96:99]
	ds_read_b128 v[192:195], v226 offset:2048
	ds_read_b128 v[176:179], v228 offset:2048
	v_mfma_f32_16x16x32_bf16 v[92:95], v[152:155], v[196:199], v[92:95]
	v_mfma_f32_16x16x32_bf16 v[88:91], v[156:159], v[196:199], v[88:91]
	v_mfma_f32_16x16x32_bf16 v[84:87], v[160:163], v[196:199], v[84:87]
	v_mfma_f32_16x16x32_bf16 v[80:83], v[164:167], v[196:199], v[80:83]
	ds_read_b128 v[196:199], v226 offset:4096
	ds_read_b128 v[180:183], v228 offset:4096
	v_mfma_f32_16x16x32_bf16 v[76:79], v[152:155], v[200:203], v[76:79]
	v_mfma_f32_16x16x32_bf16 v[72:75], v[156:159], v[200:203], v[72:75]
	v_mfma_f32_16x16x32_bf16 v[68:71], v[160:163], v[200:203], v[68:71]
	v_mfma_f32_16x16x32_bf16 v[64:67], v[164:167], v[200:203], v[64:67]
	ds_read_b128 v[200:203], v226 offset:6144
	ds_read_b128 v[184:187], v228 offset:6144
	s_waitcnt lgkmcnt(11)
	v_mfma_f32_16x16x32_bf16 v[60:63], v[152:155], v[204:207], v[60:63]
	v_mfma_f32_16x16x32_bf16 v[56:59], v[156:159], v[204:207], v[56:59]
	v_mfma_f32_16x16x32_bf16 v[52:55], v[160:163], v[204:207], v[52:55]
	v_mfma_f32_16x16x32_bf16 v[48:51], v[164:167], v[204:207], v[48:51]
	ds_read_b128 v[204:207], v226 offset:8192
	ds_read_b128 v[220:223], v226 offset:14336
	s_waitcnt lgkmcnt(11)
	v_mfma_f32_16x16x32_bf16 v[44:47], v[152:155], v[208:211], v[44:47]
	v_mfma_f32_16x16x32_bf16 v[40:43], v[156:159], v[208:211], v[40:43]
	v_mfma_f32_16x16x32_bf16 v[36:39], v[160:163], v[208:211], v[36:39]
	v_mfma_f32_16x16x32_bf16 v[32:35], v[164:167], v[208:211], v[32:35]
	ds_read_b128 v[208:211], v226 offset:10240
	s_waitcnt lgkmcnt(11)
	v_mfma_f32_16x16x32_bf16 v[28:31], v[152:155], v[212:215], v[28:31]
	v_mfma_f32_16x16x32_bf16 v[24:27], v[156:159], v[212:215], v[24:27]
	v_mfma_f32_16x16x32_bf16 v[20:23], v[160:163], v[212:215], v[20:23]
	v_mfma_f32_16x16x32_bf16 v[16:19], v[164:167], v[212:215], v[16:19]
	ds_read_b128 v[212:215], v226 offset:12288
	v_mfma_f32_16x16x32_bf16 v[12:15], v[152:155], v[216:219], v[12:15]
	v_mfma_f32_16x16x32_bf16 v[8:11], v[156:159], v[216:219], v[8:11]
	v_mfma_f32_16x16x32_bf16 v[4:7], v[160:163], v[216:219], v[4:7]
	v_mfma_f32_16x16x32_bf16 v[0:3], v[164:167], v[216:219], v[0:3]
	s_waitcnt vmcnt(0) lgkmcnt(0)
	s_barrier
	v_mfma_f32_16x16x32_bf16 v[124:127], v[168:171], v[188:191], v[124:127]
	v_mfma_f32_16x16x32_bf16 v[120:123], v[176:179], v[188:191], v[120:123]
	v_mfma_f32_16x16x32_bf16 v[116:119], v[180:183], v[188:191], v[116:119]
	v_mfma_f32_16x16x32_bf16 v[112:115], v[184:187], v[188:191], v[112:115]
	v_mfma_f32_16x16x32_bf16 v[108:111], v[168:171], v[192:195], v[108:111]
	v_mfma_f32_16x16x32_bf16 v[104:107], v[176:179], v[192:195], v[104:107]
	v_mfma_f32_16x16x32_bf16 v[100:103], v[180:183], v[192:195], v[100:103]
	v_mfma_f32_16x16x32_bf16 v[96:99], v[184:187], v[192:195], v[96:99]
	v_mfma_f32_16x16x32_bf16 v[92:95], v[168:171], v[196:199], v[92:95]
	v_mfma_f32_16x16x32_bf16 v[88:91], v[176:179], v[196:199], v[88:91]
	v_mfma_f32_16x16x32_bf16 v[84:87], v[180:183], v[196:199], v[84:87]
	v_mfma_f32_16x16x32_bf16 v[80:83], v[184:187], v[196:199], v[80:83]
	v_mfma_f32_16x16x32_bf16 v[76:79], v[168:171], v[200:203], v[76:79]
	v_mfma_f32_16x16x32_bf16 v[72:75], v[176:179], v[200:203], v[72:75]
	v_mfma_f32_16x16x32_bf16 v[68:71], v[180:183], v[200:203], v[68:71]
	v_mfma_f32_16x16x32_bf16 v[64:67], v[184:187], v[200:203], v[64:67]
	v_mfma_f32_16x16x32_bf16 v[60:63], v[168:171], v[204:207], v[60:63]
	v_mfma_f32_16x16x32_bf16 v[56:59], v[176:179], v[204:207], v[56:59]
	v_mfma_f32_16x16x32_bf16 v[52:55], v[180:183], v[204:207], v[52:55]
	v_mfma_f32_16x16x32_bf16 v[48:51], v[184:187], v[204:207], v[48:51]
	v_mfma_f32_16x16x32_bf16 v[44:47], v[168:171], v[208:211], v[44:47]
	v_mfma_f32_16x16x32_bf16 v[40:43], v[176:179], v[208:211], v[40:43]
	v_mfma_f32_16x16x32_bf16 v[36:39], v[180:183], v[208:211], v[36:39]
	v_mfma_f32_16x16x32_bf16 v[32:35], v[184:187], v[208:211], v[32:35]
	v_mfma_f32_16x16x32_bf16 v[28:31], v[168:171], v[212:215], v[28:31]
	v_mfma_f32_16x16x32_bf16 v[24:27], v[176:179], v[212:215], v[24:27]
	v_mfma_f32_16x16x32_bf16 v[20:23], v[180:183], v[212:215], v[20:23]
	v_mfma_f32_16x16x32_bf16 v[16:19], v[184:187], v[212:215], v[16:19]
	v_mfma_f32_16x16x32_bf16 v[12:15], v[168:171], v[220:223], v[12:15]
	v_mfma_f32_16x16x32_bf16 v[8:11], v[176:179], v[220:223], v[8:11]
	v_mfma_f32_16x16x32_bf16 v[4:7], v[180:183], v[220:223], v[4:7]
	v_mfma_f32_16x16x32_bf16 v[0:3], v[184:187], v[220:223], v[0:3]
	s_nop 7
	s_nop 3
	s_cmpk_lt_i32 s51, 0x80
	s_cselect_b32 s9, s37, s17
	s_cselect_b32 s8, s36, s16
	v_and_b32_e32 v225, 15, v174
	v_lshrrev_b32_e32 v226, 8, v174
	v_lshl_or_b32 v225, v226, 7, v225
	v_bfe_u32 v226, v174, 6, 2
	v_bfe_u32 v227, v174, 4, 2
	v_lshlrev_b32_e32 v227, 2, v227
	v_add_u32_e32 v225, s52, v225
	v_lshl_add_u32 v226, v226, 6, v227
	v_add_u32_e32 v226, s53, v226
	v_lshlrev_b32_e32 v226, 2, v226
	v_lshl_add_u32 v224, v225, 12, v226
	v_mov_b32_e32 v229, v224
	v_add_u32_e32 v224, 0x0, v229
	global_load_dwordx4 v[152:155], v224, s[8:9] offset:0
	global_load_dwordx4 v[156:159], v224, s[8:9] offset:64
	global_load_dwordx4 v[160:163], v224, s[8:9] offset:128
	global_load_dwordx4 v[164:167], v224, s[8:9] offset:192
	v_add_u32_e32 v228, 0x10000, v229
	global_load_dwordx4 v[168:171], v228, s[8:9] offset:0
	global_load_dwordx4 v[176:179], v228, s[8:9] offset:64
	global_load_dwordx4 v[180:183], v228, s[8:9] offset:128
	global_load_dwordx4 v[184:187], v228, s[8:9] offset:192
	s_waitcnt vmcnt(4)
; template <int EPI>
; DI void gemm_phase(const u16* __restrict__ A, int lda, const u16* __restrict__ Bt, int K, int N, u16* outb, int ldo,
;                    const float* r0, const float* r1, float* outf, char* lds, int bid, int nb) {
;     ...
;     } else if constexpr (EPI == EPI_RESID) {
;       const int col = tn * 256 + wc * 64 + l15;
;       const float* rb_ = (tm * 256 < M_P) ? r0 : (r1 - (size_t)M_P * DM);
; #pragma unroll
;       for (int i = 0; i < 8; ++i)
; #pragma unroll
;         for (int r = 0; r < 4; ++r) {
;           const size_t i0 = (size_t)(mrow + i * 16 + r) * DM + col;
;           const float x0 = rb_[i0], x1 = rb_[i0 + 16], x2 = rb_[i0 + 32], x3 = rb_[i0 + 48];
;           outf[i0] = x0 + acc[i][0][r]; outf[i0 + 16] = x1 + acc[i][1][r]; outf[i0 + 32] = x2 + acc[i][2][r]; outf[i0 + 48] = x3 + acc[i][3][r];
;         }
	v_add_f32_e32 v152, v124, v152
	v_add_f32_e32 v153, v125, v153
	v_add_f32_e32 v154, v126, v154
	v_add_f32_e32 v155, v127, v155
	v_add_f32_e32 v156, v120, v156
	v_add_f32_e32 v157, v121, v157
	v_add_f32_e32 v158, v122, v158
	v_add_f32_e32 v159, v123, v159
	v_add_f32_e32 v160, v116, v160
	v_add_f32_e32 v161, v117, v161
	v_add_f32_e32 v162, v118, v162
	v_add_f32_e32 v163, v119, v163
	v_add_f32_e32 v164, v112, v164
	v_add_f32_e32 v165, v113, v165
	v_add_f32_e32 v166, v114, v166
	v_add_f32_e32 v167, v115, v167
	global_store_dwordx4 v224, v[152:155], s[22:23] offset:0
	global_store_dwordx4 v224, v[156:159], s[22:23] offset:64
	global_store_dwordx4 v224, v[160:163], s[22:23] offset:128
	global_store_dwordx4 v224, v[164:167], s[22:23] offset:192
	s_nop 1
	v_add_u32_e32 v224, 0x20000, v229
	global_load_dwordx4 v[152:155], v224, s[8:9] offset:0
	global_load_dwordx4 v[156:159], v224, s[8:9] offset:64
	global_load_dwordx4 v[160:163], v224, s[8:9] offset:128
	global_load_dwordx4 v[164:167], v224, s[8:9] offset:192
	s_waitcnt vmcnt(8)
	v_add_f32_e32 v168, v108, v168
	v_add_f32_e32 v169, v109, v169
	v_add_f32_e32 v170, v110, v170
	v_add_f32_e32 v171, v111, v171
	v_add_f32_e32 v176, v104, v176
	v_add_f32_e32 v177, v105, v177
	v_add_f32_e32 v178, v106, v178
	v_add_f32_e32 v179, v107, v179
	v_add_f32_e32 v180, v100, v180
	v_add_f32_e32 v181, v101, v181
	v_add_f32_e32 v182, v102, v182
	v_add_f32_e32 v183, v103, v183
	v_add_f32_e32 v184, v96, v184
	v_add_f32_e32 v185, v97, v185
	v_add_f32_e32 v186, v98, v186
	v_add_f32_e32 v187, v99, v187
	global_store_dwordx4 v228, v[168:171], s[22:23] offset:0
	global_store_dwordx4 v228, v[176:179], s[22:23] offset:64
	global_store_dwordx4 v228, v[180:183], s[22:23] offset:128
	global_store_dwordx4 v228, v[184:187], s[22:23] offset:192
	s_nop 1
	v_add_u32_e32 v228, 0x30000, v229
	global_load_dwordx4 v[168:171], v228, s[8:9] offset:0
	global_load_dwordx4 v[176:179], v228, s[8:9] offset:64
	global_load_dwordx4 v[180:183], v228, s[8:9] offset:128
	global_load_dwordx4 v[184:187], v228, s[8:9] offset:192
	s_waitcnt vmcnt(8)
	v_add_f32_e32 v152, v92, v152
	v_add_f32_e32 v153, v93, v153
	v_add_f32_e32 v154, v94, v154
	v_add_f32_e32 v155, v95, v155
	v_add_f32_e32 v156, v88, v156
	v_add_f32_e32 v157, v89, v157
	v_add_f32_e32 v158, v90, v158
	v_add_f32_e32 v159, v91, v159
	v_add_f32_e32 v160, v84, v160
	v_add_f32_e32 v161, v85, v161
	v_add_f32_e32 v162, v86, v162
	v_add_f32_e32 v163, v87, v163
	v_add_f32_e32 v164, v80, v164
	v_add_f32_e32 v165, v81, v165
	v_add_f32_e32 v166, v82, v166
	v_add_f32_e32 v167, v83, v167
	global_store_dwordx4 v224, v[152:155], s[22:23] offset:0
	global_store_dwordx4 v224, v[156:159], s[22:23] offset:64
	global_store_dwordx4 v224, v[160:163], s[22:23] offset:128
	global_store_dwordx4 v224, v[164:167], s[22:23] offset:192
	s_nop 1
	v_add_u32_e32 v224, 0x40000, v229
	global_load_dwordx4 v[152:155], v224, s[8:9] offset:0
	global_load_dwordx4 v[156:159], v224, s[8:9] offset:64
	global_load_dwordx4 v[160:163], v224, s[8:9] offset:128
	global_load_dwordx4 v[164:167], v224, s[8:9] offset:192
	s_waitcnt vmcnt(8)
	v_add_f32_e32 v168, v76, v168
	v_add_f32_e32 v169, v77, v169
	v_add_f32_e32 v170, v78, v170
	v_add_f32_e32 v171, v79, v171
	v_add_f32_e32 v176, v72, v176
	v_add_f32_e32 v177, v73, v177
	v_add_f32_e32 v178, v74, v178
	v_add_f32_e32 v179, v75, v179
	v_add_f32_e32 v180, v68, v180
	v_add_f32_e32 v181, v69, v181
	v_add_f32_e32 v182, v70, v182
	v_add_f32_e32 v183, v71, v183
	v_add_f32_e32 v184, v64, v184
	v_add_f32_e32 v185, v65, v185
	v_add_f32_e32 v186, v66, v186
	v_add_f32_e32 v187, v67, v187
	global_store_dwordx4 v228, v[168:171], s[22:23] offset:0
	global_store_dwordx4 v228, v[176:179], s[22:23] offset:64
	global_store_dwordx4 v228, v[180:183], s[22:23] offset:128
	global_store_dwordx4 v228, v[184:187], s[22:23] offset:192
	s_nop 1
	v_add_u32_e32 v228, 0x50000, v229
	global_load_dwordx4 v[168:171], v228, s[8:9] offset:0
	global_load_dwordx4 v[176:179], v228, s[8:9] offset:64
	global_load_dwordx4 v[180:183], v228, s[8:9] offset:128
	global_load_dwordx4 v[184:187], v228, s[8:9] offset:192
	s_waitcnt vmcnt(8)
; template <int EPI>
; DI void gemm_phase(const u16* __restrict__ A, int lda, const u16* __restrict__ Bt, int K, int N, u16* outb, int ldo,
;                    const float* r0, const float* r1, float* outf, char* lds, int bid, int nb) {
;     ...
;     } else if constexpr (EPI == EPI_RESID) {
;       const int col = tn * 256 + wc * 64 + l15;
;       const float* rb_ = (tm * 256 < M_P) ? r0 : (r1 - (size_t)M_P * DM);
; #pragma unroll
;       for (int i = 0; i < 8; ++i)
; #pragma unroll
;         for (int r = 0; r < 4; ++r) {
;           const size_t i0 = (size_t)(mrow + i * 16 + r) * DM + col;
;           const float x0 = rb_[i0], x1 = rb_[i0 + 16], x2 = rb_[i0 + 32], x3 = rb_[i0 + 48];
;           outf[i0] = x0 + acc[i][0][r]; outf[i0 + 16] = x1 + acc[i][1][r]; outf[i0 + 32] = x2 + acc[i][2][r]; outf[i0 + 48] = x3 + acc[i][3][r];
;         }
	v_add_f32_e32 v152, v60, v152
	v_add_f32_e32 v153, v61, v153
	v_add_f32_e32 v154, v62, v154
	v_add_f32_e32 v155, v63, v155
	v_add_f32_e32 v156, v56, v156
	v_add_f32_e32 v157, v57, v157
	v_add_f32_e32 v158, v58, v158
	v_add_f32_e32 v159, v59, v159
	v_add_f32_e32 v160, v52, v160
	v_add_f32_e32 v161, v53, v161
	v_add_f32_e32 v162, v54, v162
	v_add_f32_e32 v163, v55, v163
	v_add_f32_e32 v164, v48, v164
	v_add_f32_e32 v165, v49, v165
	v_add_f32_e32 v166, v50, v166
	v_add_f32_e32 v167, v51, v167
	global_store_dwordx4 v224, v[152:155], s[22:23] offset:0
	global_store_dwordx4 v224, v[156:159], s[22:23] offset:64
	global_store_dwordx4 v224, v[160:163], s[22:23] offset:128
	global_store_dwordx4 v224, v[164:167], s[22:23] offset:192
	s_nop 1
	v_add_u32_e32 v224, 0x60000, v229
	global_load_dwordx4 v[152:155], v224, s[8:9] offset:0
	global_load_dwordx4 v[156:159], v224, s[8:9] offset:64
	global_load_dwordx4 v[160:163], v224, s[8:9] offset:128
	global_load_dwordx4 v[164:167], v224, s[8:9] offset:192
	s_waitcnt vmcnt(8)
	v_add_f32_e32 v168, v44, v168
	v_add_f32_e32 v169, v45, v169
	v_add_f32_e32 v170, v46, v170
	v_add_f32_e32 v171, v47, v171
	v_add_f32_e32 v176, v40, v176
	v_add_f32_e32 v177, v41, v177
	v_add_f32_e32 v178, v42, v178
	v_add_f32_e32 v179, v43, v179
	v_add_f32_e32 v180, v36, v180
	v_add_f32_e32 v181, v37, v181
	v_add_f32_e32 v182, v38, v182
	v_add_f32_e32 v183, v39, v183
	v_add_f32_e32 v184, v32, v184
	v_add_f32_e32 v185, v33, v185
	v_add_f32_e32 v186, v34, v186
	v_add_f32_e32 v187, v35, v187
	global_store_dwordx4 v228, v[168:171], s[22:23] offset:0
	global_store_dwordx4 v228, v[176:179], s[22:23] offset:64
	global_store_dwordx4 v228, v[180:183], s[22:23] offset:128
	global_store_dwordx4 v228, v[184:187], s[22:23] offset:192
	s_nop 1
	v_add_u32_e32 v228, 0x70000, v229
	global_load_dwordx4 v[168:171], v228, s[8:9] offset:0
	global_load_dwordx4 v[176:179], v228, s[8:9] offset:64
	global_load_dwordx4 v[180:183], v228, s[8:9] offset:128
	global_load_dwordx4 v[184:187], v228, s[8:9] offset:192
	s_waitcnt vmcnt(8)
	v_add_f32_e32 v152, v28, v152
	v_add_f32_e32 v153, v29, v153
	v_add_f32_e32 v154, v30, v154
	v_add_f32_e32 v155, v31, v155
	v_add_f32_e32 v156, v24, v156
	v_add_f32_e32 v157, v25, v157
	v_add_f32_e32 v158, v26, v158
	v_add_f32_e32 v159, v27, v159
	v_add_f32_e32 v160, v20, v160
	v_add_f32_e32 v161, v21, v161
	v_add_f32_e32 v162, v22, v162
	v_add_f32_e32 v163, v23, v163
	v_add_f32_e32 v164, v16, v164
	v_add_f32_e32 v165, v17, v165
	v_add_f32_e32 v166, v18, v166
	v_add_f32_e32 v167, v19, v167
	global_store_dwordx4 v224, v[152:155], s[22:23] offset:0
	global_store_dwordx4 v224, v[156:159], s[22:23] offset:64
	global_store_dwordx4 v224, v[160:163], s[22:23] offset:128
	global_store_dwordx4 v224, v[164:167], s[22:23] offset:192
	s_waitcnt vmcnt(4)
	v_add_f32_e32 v168, v12, v168
	v_add_f32_e32 v169, v13, v169
	v_add_f32_e32 v170, v14, v170
	v_add_f32_e32 v171, v15, v171
	v_add_f32_e32 v176, v8, v176
	v_add_f32_e32 v177, v9, v177
	v_add_f32_e32 v178, v10, v178
	v_add_f32_e32 v179, v11, v179
	v_add_f32_e32 v180, v4, v180
	v_add_f32_e32 v181, v5, v181
	v_add_f32_e32 v182, v6, v182
	v_add_f32_e32 v183, v7, v183
	v_add_f32_e32 v184, v0, v184
	v_add_f32_e32 v185, v1, v185
	v_add_f32_e32 v186, v2, v186
	v_add_f32_e32 v187, v3, v187
	global_store_dwordx4 v228, v[168:171], s[22:23] offset:0
	global_store_dwordx4 v228, v[176:179], s[22:23] offset:64
	global_store_dwordx4 v228, v[180:183], s[22:23] offset:128
	global_store_dwordx4 v228, v[184:187], s[22:23] offset:192
	s_add_i32 s18, s18, 1
	s_cmp_eq_u32 s18, s3
	s_cbranch_scc0 .LBB0_577

; #define G_LOAD(KT) do { _Pragma("unroll") for (int i = 0; i < 4; ++i) { ra[i] = *(const u32x4*)(Ag + (size_t)i * 64 * lda + (KT) * 64); rb[i] = *(const u32x4*)(Bg + (size_t)i * 64 * K + (KT) * 64); } } while (0)
; #define G_STORE(BUF) do { u16* ad = As + (BUF) * 256 * 64 + sto; u16* bd = Bs + (BUF) * 256 * 64 + sto; _Pragma("unroll") for (int i = 0; i < 4; ++i) { *(u32x4*)(ad + i * 64 * 64) = ra[i]; *(u32x4*)(bd + i * 64 * 64) = rb[i]; } } while (0)
; template <int EPI>
; DI void gemm_phase(const u16* __restrict__ A, int lda, const u16* __restrict__ Bt, int K, int N, u16* outb, int ldo,
;                    const float* r0, const float* r1, float* outf, char* lds, int bid, int nb) {
;     ...
;     G_LOAD(0);
;     G_STORE(0);
;     __syncthreads();
;     for (int kt = 0; kt < nk; ++kt) {
;       const int cur = kt & 1;
;       if (kt + 1 < nk) G_LOAD(kt + 1);
;       G_MMA(cur, fo0);
;       G_MMA(cur, fo1);
;       if (kt + 1 < nk) G_STORE(cur ^ 1);
;       __syncthreads();
;     }
.Lgm2_loop:
	s_waitcnt lgkmcnt(4)
	v_mfma_f32_16x16x32_bf16 v[124:127], v[152:155], v[188:191], v[124:127]
	v_mfma_f32_16x16x32_bf16 v[120:123], v[156:159], v[188:191], v[120:123]
	v_mfma_f32_16x16x32_bf16 v[116:119], v[160:163], v[188:191], v[116:119]
	v_mfma_f32_16x16x32_bf16 v[112:115], v[164:167], v[188:191], v[112:115]
	ds_read_b128 v[188:191], v226 offset:0
	ds_read_b128 v[168:171], v228 offset:0
	v_mfma_f32_16x16x32_bf16 v[108:111], v[152:155], v[192:195], v[108:111]
	v_mfma_f32_16x16x32_bf16 v[104:107], v[156:159], v[192:195], v[104:107]
	v_mfma_f32_16x16x32_bf16 v[100:103], v[160:163], v[192:195], v[100:103]
	v_mfma_f32_16x16x32_bf16 v[96:99], v[164:167], v[192:195], v[96:99]
	ds_read_b128 v[192:195], v226 offset:2048
	ds_read_b128 v[176:179], v228 offset:2048
	v_mfma_f32_16x16x32_bf16 v[92:95], v[152:155], v[196:199], v[92:95]
	v_mfma_f32_16x16x32_bf16 v[88:91], v[156:159], v[196:199], v[88:91]
	v_mfma_f32_16x16x32_bf16 v[84:87], v[160:163], v[196:199], v[84:87]
	v_mfma_f32_16x16x32_bf16 v[80:83], v[164:167], v[196:199], v[80:83]
	ds_read_b128 v[196:199], v226 offset:4096
	ds_read_b128 v[180:183], v228 offset:4096
	v_mfma_f32_16x16x32_bf16 v[76:79], v[152:155], v[200:203], v[76:79]
	v_mfma_f32_16x16x32_bf16 v[72:75], v[156:159], v[200:203], v[72:75]
	v_mfma_f32_16x16x32_bf16 v[68:71], v[160:163], v[200:203], v[68:71]
	v_mfma_f32_16x16x32_bf16 v[64:67], v[164:167], v[200:203], v[64:67]
	ds_read_b128 v[200:203], v226 offset:6144
	ds_read_b128 v[184:187], v228 offset:6144
	s_waitcnt lgkmcnt(11)
	v_mfma_f32_16x16x32_bf16 v[60:63], v[152:155], v[204:207], v[60:63]
	v_mfma_f32_16x16x32_bf16 v[56:59], v[156:159], v[204:207], v[56:59]
	v_mfma_f32_16x16x32_bf16 v[52:55], v[160:163], v[204:207], v[52:55]
	v_mfma_f32_16x16x32_bf16 v[48:51], v[164:167], v[204:207], v[48:51]
	ds_read_b128 v[204:207], v226 offset:8192
	ds_read_b128 v[220:223], v226 offset:14336
	s_waitcnt lgkmcnt(11)
	v_mfma_f32_16x16x32_bf16 v[44:47], v[152:155], v[208:211], v[44:47]
	v_mfma_f32_16x16x32_bf16 v[40:43], v[156:159], v[208:211], v[40:43]
	v_mfma_f32_16x16x32_bf16 v[36:39], v[160:163], v[208:211], v[36:39]
	v_mfma_f32_16x16x32_bf16 v[32:35], v[164:167], v[208:211], v[32:35]
	ds_read_b128 v[208:211], v226 offset:10240
	s_waitcnt lgkmcnt(11)
	v_mfma_f32_16x16x32_bf16 v[28:31], v[152:155], v[212:215], v[28:31]
	v_mfma_f32_16x16x32_bf16 v[24:27], v[156:159], v[212:215], v[24:27]
	v_mfma_f32_16x16x32_bf16 v[20:23], v[160:163], v[212:215], v[20:23]
	v_mfma_f32_16x16x32_bf16 v[16:19], v[164:167], v[212:215], v[16:19]
	ds_read_b128 v[212:215], v226 offset:12288
	v_mfma_f32_16x16x32_bf16 v[12:15], v[152:155], v[216:219], v[12:15]
	v_mfma_f32_16x16x32_bf16 v[8:11], v[156:159], v[216:219], v[8:11]
	v_mfma_f32_16x16x32_bf16 v[4:7], v[160:163], v[216:219], v[4:7]
	v_mfma_f32_16x16x32_bf16 v[0:3], v[164:167], v[216:219], v[0:3]
	s_waitcnt vmcnt(0) lgkmcnt(0)
	s_barrier
	v_mfma_f32_16x16x32_bf16 v[124:127], v[168:171], v[188:191], v[124:127]
	v_mfma_f32_16x16x32_bf16 v[120:123], v[176:179], v[188:191], v[120:123]
	v_mfma_f32_16x16x32_bf16 v[116:119], v[180:183], v[188:191], v[116:119]
	v_mfma_f32_16x16x32_bf16 v[112:115], v[184:187], v[188:191], v[112:115]
	ds_read_b128 v[188:191], v225 offset:0
	ds_read_b128 v[152:155], v227 offset:0
	s_add_u32 s14, s98, 0x0
	s_addc_u32 s15, s99, 0
	s_add_u32 m0, s97, 0x0
	s_nop 0
	global_load_lds_dwordx4 v224, s[14:15]
	v_mfma_f32_16x16x32_bf16 v[108:111], v[168:171], v[192:195], v[108:111]
	v_mfma_f32_16x16x32_bf16 v[104:107], v[176:179], v[192:195], v[104:107]
	v_mfma_f32_16x16x32_bf16 v[100:103], v[180:183], v[192:195], v[100:103]
	v_mfma_f32_16x16x32_bf16 v[96:99], v[184:187], v[192:195], v[96:99]
	ds_read_b128 v[192:195], v225 offset:2048
	ds_read_b128 v[156:159], v227 offset:2048
	s_add_u32 s14, s100, 0x0
	s_addc_u32 s15, s101, 0
	s_add_u32 m0, s97, 0x10000
	s_nop 0
	global_load_lds_dwordx4 v224, s[14:15]
	v_mfma_f32_16x16x32_bf16 v[92:95], v[168:171], v[196:199], v[92:95]
	v_mfma_f32_16x16x32_bf16 v[88:91], v[176:179], v[196:199], v[88:91]
	v_mfma_f32_16x16x32_bf16 v[84:87], v[180:183], v[196:199], v[84:87]
	v_mfma_f32_16x16x32_bf16 v[80:83], v[184:187], v[196:199], v[80:83]
	ds_read_b128 v[196:199], v225 offset:4096
	ds_read_b128 v[160:163], v227 offset:4096
	s_add_u32 s14, s98, 0x20000
	s_addc_u32 s15, s99, 0
	s_add_u32 m0, s97, 0x2000
	s_nop 0
	global_load_lds_dwordx4 v224, s[14:15]
	v_mfma_f32_16x16x32_bf16 v[76:79], v[168:171], v[200:203], v[76:79]
	v_mfma_f32_16x16x32_bf16 v[72:75], v[176:179], v[200:203], v[72:75]
	v_mfma_f32_16x16x32_bf16 v[68:71], v[180:183], v[200:203], v[68:71]
	v_mfma_f32_16x16x32_bf16 v[64:67], v[184:187], v[200:203], v[64:67]
	ds_read_b128 v[200:203], v225 offset:6144
	ds_read_b128 v[164:167], v227 offset:6144
	s_add_u32 s14, s100, 0x20000
	s_addc_u32 s15, s101, 0
	s_add_u32 m0, s97, 0x12000
	s_nop 0
	global_load_lds_dwordx4 v224, s[14:15]
	v_mfma_f32_16x16x32_bf16 v[60:63], v[168:171], v[204:207], v[60:63]
	v_mfma_f32_16x16x32_bf16 v[56:59], v[176:179], v[204:207], v[56:59]
	v_mfma_f32_16x16x32_bf16 v[52:55], v[180:183], v[204:207], v[52:55]
	v_mfma_f32_16x16x32_bf16 v[48:51], v[184:187], v[204:207], v[48:51]
	ds_read_b128 v[204:207], v225 offset:8192
	ds_read_b128 v[216:219], v225 offset:14336
	s_add_u32 s14, s98, 0x40000
	s_addc_u32 s15, s99, 0
	s_add_u32 m0, s97, 0x4000
	s_nop 0
	global_load_lds_dwordx4 v224, s[14:15]
	v_mfma_f32_16x16x32_bf16 v[44:47], v[168:171], v[208:211], v[44:47]
	v_mfma_f32_16x16x32_bf16 v[40:43], v[176:179], v[208:211], v[40:43]
	v_mfma_f32_16x16x32_bf16 v[36:39], v[180:183], v[208:211], v[36:39]
	v_mfma_f32_16x16x32_bf16 v[32:35], v[184:187], v[208:211], v[32:35]
	ds_read_b128 v[208:211], v225 offset:10240
	s_add_u32 s14, s100, 0x40000
	s_addc_u32 s15, s101, 0
	s_add_u32 m0, s97, 0x14000
	s_nop 0
	global_load_lds_dwordx4 v224, s[14:15]
	v_mfma_f32_16x16x32_bf16 v[28:31], v[168:171], v[212:215], v[28:31]
	v_mfma_f32_16x16x32_bf16 v[24:27], v[176:179], v[212:215], v[24:27]
	v_mfma_f32_16x16x32_bf16 v[20:23], v[180:183], v[212:215], v[20:23]
	v_mfma_f32_16x16x32_bf16 v[16:19], v[184:187], v[212:215], v[16:19]
	ds_read_b128 v[212:215], v225 offset:12288
	s_add_u32 s14, s98, 0x60000
	s_addc_u32 s15, s99, 0
	s_add_u32 m0, s97, 0x6000
	s_nop 0
	global_load_lds_dwordx4 v224, s[14:15]
	v_mfma_f32_16x16x32_bf16 v[12:15], v[168:171], v[220:223], v[12:15]
	v_mfma_f32_16x16x32_bf16 v[8:11], v[176:179], v[220:223], v[8:11]
	v_mfma_f32_16x16x32_bf16 v[4:7], v[180:183], v[220:223], v[4:7]
	v_mfma_f32_16x16x32_bf16 v[0:3], v[184:187], v[220:223], v[0:3]
	s_add_u32 s14, s100, 0x60000
	s_addc_u32 s15, s101, 0
	s_add_u32 m0, s97, 0x16000
	s_nop 0
	global_load_lds_dwordx4 v224, s[14:15]
	v_xor_b32_e32 v225, 0x8000, v225
	v_xor_b32_e32 v227, 0x8000, v227
	v_xor_b32_e32 v226, 0x8000, v226
	v_xor_b32_e32 v228, 0x8000, v228
	s_xor_b32 s97, s97, 0x8000
	s_add_u32 s98, s98, 0x80
	s_addc_u32 s99, s99, 0
	s_add_u32 s100, s100, 0x80
	s_addc_u32 s101, s101, 0
	s_sub_u32 s28, s28, 1
	s_cmp_lg_u32 s28, 0
	s_cbranch_scc1 .Lgm2_loop
; #define G_LOAD(KT) do { _Pragma("unroll") for (int i = 0; i < 4; ++i) { ra[i] = *(const u32x4*)(Ag + (size_t)i * 64 * lda + (KT) * 64); rb[i] = *(const u32x4*)(Bg + (size_t)i * 64 * K + (KT) * 64); } } while (0)
; #define G_STORE(BUF) do { u16* ad = As + (BUF) * 256 * 64 + sto; u16* bd = Bs + (BUF) * 256 * 64 + sto; _Pragma("unroll") for (int i = 0; i < 4; ++i) { *(u32x4*)(ad + i * 64 * 64) = ra[i]; *(u32x4*)(bd + i * 64 * 64) = rb[i]; } } while (0)
; template <int EPI>
; DI void gemm_phase(const u16* __restrict__ A, int lda, const u16* __restrict__ Bt, int K, int N, u16* outb, int ldo,
;                    const float* r0, const float* r1, float* outf, char* lds, int bid, int nb) {
;     ...
;     G_LOAD(0);
;     G_STORE(0);
;     __syncthreads();
;     for (int kt = 0; kt < nk; ++kt) {
;       const int cur = kt & 1;
;       if (kt + 1 < nk) G_LOAD(kt + 1);
;       G_MMA(cur, fo0);
;       G_MMA(cur, fo1);
;       if (kt + 1 < nk) G_STORE(cur ^ 1);
;       __syncthreads();
;     }
	s_waitcnt lgkmcnt(4)
	v_mfma_f32_16x16x32_bf16 v[124:127], v[152:155], v[188:191], v[124:127]
	v_mfma_f32_16x16x32_bf16 v[120:123], v[156:159], v[188:191], v[120:123]
	v_mfma_f32_16x16x32_bf16 v[116:119], v[160:163], v[188:191], v[116:119]
	v_mfma_f32_16x16x32_bf16 v[112:115], v[164:167], v[188:191], v[112:115]
	ds_read_b128 v[188:191], v226 offset:0
	ds_read_b128 v[168:171], v228 offset:0
	v_mfma_f32_16x16x32_bf16 v[108:111], v[152:155], v[192:195], v[108:111]
	v_mfma_f32_16x16x32_bf16 v[104:107], v[156:159], v[192:195], v[104:107]
	v_mfma_f32_16x16x32_bf16 v[100:103], v[160:163], v[192:195], v[100:103]
	v_mfma_f32_16x16x32_bf16 v[96:99], v[164:167], v[192:195], v[96:99]
	ds_read_b128 v[192:195], v226 offset:2048
	ds_read_b128 v[176:179], v228 offset:2048
	v_mfma_f32_16x16x32_bf16 v[92:95], v[152:155], v[196:199], v[92:95]
	v_mfma_f32_16x16x32_bf16 v[88:91], v[156:159], v[196:199], v[88:91]
	v_mfma_f32_16x16x32_bf16 v[84:87], v[160:163], v[196:199], v[84:87]
	v_mfma_f32_16x16x32_bf16 v[80:83], v[164:167], v[196:199], v[80:83]
	ds_read_b128 v[196:199], v226 offset:4096
	ds_read_b128 v[180:183], v228 offset:4096
	v_mfma_f32_16x16x32_bf16 v[76:79], v[152:155], v[200:203], v[76:79]
	v_mfma_f32_16x16x32_bf16 v[72:75], v[156:159], v[200:203], v[72:75]
	v_mfma_f32_16x16x32_bf16 v[68:71], v[160:163], v[200:203], v[68:71]
	v_mfma_f32_16x16x32_bf16 v[64:67], v[164:167], v[200:203], v[64:67]
	ds_read_b128 v[200:203], v226 offset:6144
	ds_read_b128 v[184:187], v228 offset:6144
	s_waitcnt lgkmcnt(11)
	v_mfma_f32_16x16x32_bf16 v[60:63], v[152:155], v[204:207], v[60:63]
	v_mfma_f32_16x16x32_bf16 v[56:59], v[156:159], v[204:207], v[56:59]
	v_mfma_f32_16x16x32_bf16 v[52:55], v[160:163], v[204:207], v[52:55]
	v_mfma_f32_16x16x32_bf16 v[48:51], v[164:167], v[204:207], v[48:51]
	ds_read_b128 v[204:207], v226 offset:8192
	ds_read_b128 v[220:223], v226 offset:14336
	s_waitcnt lgkmcnt(11)
	v_mfma_f32_16x16x32_bf16 v[44:47], v[152:155], v[208:211], v[44:47]
	v_mfma_f32_16x16x32_bf16 v[40:43], v[156:159], v[208:211], v[40:43]
	v_mfma_f32_16x16x32_bf16 v[36:39], v[160:163], v[208:211], v[36:39]
	v_mfma_f32_16x16x32_bf16 v[32:35], v[164:167], v[208:211], v[32:35]
	ds_read_b128 v[208:211], v226 offset:10240
	s_waitcnt lgkmcnt(11)
	v_mfma_f32_16x16x32_bf16 v[28:31], v[152:155], v[212:215], v[28:31]
	v_mfma_f32_16x16x32_bf16 v[24:27], v[156:159], v[212:215], v[24:27]
	v_mfma_f32_16x16x32_bf16 v[20:23], v[160:163], v[212:215], v[20:23]
	v_mfma_f32_16x16x32_bf16 v[16:19], v[164:167], v[212:215], v[16:19]
	ds_read_b128 v[212:215], v226 offset:12288
	v_mfma_f32_16x16x32_bf16 v[12:15], v[152:155], v[216:219], v[12:15]
	v_mfma_f32_16x16x32_bf16 v[8:11], v[156:159], v[216:219], v[8:11]
	v_mfma_f32_16x16x32_bf16 v[4:7], v[160:163], v[216:219], v[4:7]
	v_mfma_f32_16x16x32_bf16 v[0:3], v[164:167], v[216:219], v[0:3]
	s_waitcnt vmcnt(0) lgkmcnt(0)
	s_barrier
	v_mfma_f32_16x16x32_bf16 v[124:127], v[168:171], v[188:191], v[124:127]
	v_mfma_f32_16x16x32_bf16 v[120:123], v[176:179], v[188:191], v[120:123]
	v_mfma_f32_16x16x32_bf16 v[116:119], v[180:183], v[188:191], v[116:119]
	v_mfma_f32_16x16x32_bf16 v[112:115], v[184:187], v[188:191], v[112:115]
	ds_read_b128 v[188:191], v225 offset:0
	ds_read_b128 v[152:155], v227 offset:0
	v_mfma_f32_16x16x32_bf16 v[108:111], v[168:171], v[192:195], v[108:111]
	v_mfma_f32_16x16x32_bf16 v[104:107], v[176:179], v[192:195], v[104:107]
	v_mfma_f32_16x16x32_bf16 v[100:103], v[180:183], v[192:195], v[100:103]
	v_mfma_f32_16x16x32_bf16 v[96:99], v[184:187], v[192:195], v[96:99]
	ds_read_b128 v[192:195], v225 offset:2048
	ds_read_b128 v[156:159], v227 offset:2048
	v_mfma_f32_16x16x32_bf16 v[92:95], v[168:171], v[196:199], v[92:95]
	v_mfma_f32_16x16x32_bf16 v[88:91], v[176:179], v[196:199], v[88:91]
	v_mfma_f32_16x16x32_bf16 v[84:87], v[180:183], v[196:199], v[84:87]
	v_mfma_f32_16x16x32_bf16 v[80:83], v[184:187], v[196:199], v[80:83]
	ds_read_b128 v[196:199], v225 offset:4096
	ds_read_b128 v[160:163], v227 offset:4096
	v_mfma_f32_16x16x32_bf16 v[76:79], v[168:171], v[200:203], v[76:79]
	v_mfma_f32_16x16x32_bf16 v[72:75], v[176:179], v[200:203], v[72:75]
	v_mfma_f32_16x16x32_bf16 v[68:71], v[180:183], v[200:203], v[68:71]
	v_mfma_f32_16x16x32_bf16 v[64:67], v[184:187], v[200:203], v[64:67]
	ds_read_b128 v[200:203], v225 offset:6144
	ds_read_b128 v[164:167], v227 offset:6144
	v_mfma_f32_16x16x32_bf16 v[60:63], v[168:171], v[204:207], v[60:63]
	v_mfma_f32_16x16x32_bf16 v[56:59], v[176:179], v[204:207], v[56:59]
	v_mfma_f32_16x16x32_bf16 v[52:55], v[180:183], v[204:207], v[52:55]
	v_mfma_f32_16x16x32_bf16 v[48:51], v[184:187], v[204:207], v[48:51]
	ds_read_b128 v[204:207], v225 offset:8192
	ds_read_b128 v[216:219], v225 offset:14336
	v_mfma_f32_16x16x32_bf16 v[44:47], v[168:171], v[208:211], v[44:47]
	v_mfma_f32_16x16x32_bf16 v[40:43], v[176:179], v[208:211], v[40:43]
	v_mfma_f32_16x16x32_bf16 v[36:39], v[180:183], v[208:211], v[36:39]
	v_mfma_f32_16x16x32_bf16 v[32:35], v[184:187], v[208:211], v[32:35]
	ds_read_b128 v[208:211], v225 offset:10240
	v_mfma_f32_16x16x32_bf16 v[28:31], v[168:171], v[212:215], v[28:31]
	v_mfma_f32_16x16x32_bf16 v[24:27], v[176:179], v[212:215], v[24:27]
	v_mfma_f32_16x16x32_bf16 v[20:23], v[180:183], v[212:215], v[20:23]
	v_mfma_f32_16x16x32_bf16 v[16:19], v[184:187], v[212:215], v[16:19]
	ds_read_b128 v[212:215], v225 offset:12288
	v_mfma_f32_16x16x32_bf16 v[12:15], v[168:171], v[220:223], v[12:15]
	v_mfma_f32_16x16x32_bf16 v[8:11], v[176:179], v[220:223], v[8:11]
	v_mfma_f32_16x16x32_bf16 v[4:7], v[180:183], v[220:223], v[4:7]
	v_mfma_f32_16x16x32_bf16 v[0:3], v[184:187], v[220:223], v[0:3]
	v_xor_b32_e32 v226, 0x8000, v226
	v_xor_b32_e32 v228, 0x8000, v228
	s_waitcnt lgkmcnt(4)
; DI u16 f2bf(float a) { return (u16)(pk2(a, 0.f) & 0xffffu); }
; DI float sigmoidf_(float x) { return __builtin_amdgcn_rcpf(1.f + __builtin_amdgcn_exp2f(-1.4426950408889634f * x)); }
; template <int EPI>
; DI void gemm_phase(const u16* __restrict__ A, int lda, const u16* __restrict__ Bt, int K, int N, u16* outb, int ldo,
;                    const float* r0, const float* r1, float* outf, char* lds, int bid, int nb) {
;     ...
;     } else {
;       const int col = (tn * 4 + wc) * 32 + l15;
; #pragma unroll
;       for (int i = 0; i < 8; ++i)
; #pragma unroll
;         for (int r = 0; r < 4; ++r) {
;           const float g0 = acc[i][0][r], u0 = acc[i][2][r], g1 = acc[i][1][r], u1 = acc[i][3][r];
;           u16* o0 = outb + (size_t)(mrow + i * 16 + r) * ldo + col;
;           o0[0] = f2bf(g0 * sigmoidf_(g0) * u0); o0[16] = f2bf(g1 * sigmoidf_(g1) * u1);
;         }
	v_mfma_f32_16x16x32_bf16 v[124:127], v[152:155], v[188:191], v[124:127]
	v_mfma_f32_16x16x32_bf16 v[120:123], v[156:159], v[188:191], v[120:123]
	v_mfma_f32_16x16x32_bf16 v[116:119], v[160:163], v[188:191], v[116:119]
	v_mfma_f32_16x16x32_bf16 v[112:115], v[164:167], v[188:191], v[112:115]
	ds_read_b128 v[188:191], v226 offset:0
	ds_read_b128 v[168:171], v228 offset:0
	v_mfma_f32_16x16x32_bf16 v[108:111], v[152:155], v[192:195], v[108:111]
	v_mfma_f32_16x16x32_bf16 v[104:107], v[156:159], v[192:195], v[104:107]
	v_mfma_f32_16x16x32_bf16 v[100:103], v[160:163], v[192:195], v[100:103]
	v_mfma_f32_16x16x32_bf16 v[96:99], v[164:167], v[192:195], v[96:99]
	ds_read_b128 v[192:195], v226 offset:2048
	ds_read_b128 v[176:179], v228 offset:2048
	v_mfma_f32_16x16x32_bf16 v[92:95], v[152:155], v[196:199], v[92:95]
	v_mfma_f32_16x16x32_bf16 v[88:91], v[156:159], v[196:199], v[88:91]
	v_mfma_f32_16x16x32_bf16 v[84:87], v[160:163], v[196:199], v[84:87]
	v_mfma_f32_16x16x32_bf16 v[80:83], v[164:167], v[196:199], v[80:83]
	ds_read_b128 v[196:199], v226 offset:4096
	ds_read_b128 v[180:183], v228 offset:4096
	v_mfma_f32_16x16x32_bf16 v[76:79], v[152:155], v[200:203], v[76:79]
	v_mfma_f32_16x16x32_bf16 v[72:75], v[156:159], v[200:203], v[72:75]
	v_mfma_f32_16x16x32_bf16 v[68:71], v[160:163], v[200:203], v[68:71]
	v_mfma_f32_16x16x32_bf16 v[64:67], v[164:167], v[200:203], v[64:67]
	ds_read_b128 v[200:203], v226 offset:6144
	ds_read_b128 v[184:187], v228 offset:6144
	s_waitcnt lgkmcnt(11)
	v_mfma_f32_16x16x32_bf16 v[60:63], v[152:155], v[204:207], v[60:63]
	v_mfma_f32_16x16x32_bf16 v[56:59], v[156:159], v[204:207], v[56:59]
	v_mfma_f32_16x16x32_bf16 v[52:55], v[160:163], v[204:207], v[52:55]
	v_mfma_f32_16x16x32_bf16 v[48:51], v[164:167], v[204:207], v[48:51]
	ds_read_b128 v[204:207], v226 offset:8192
	ds_read_b128 v[220:223], v226 offset:14336
	s_waitcnt lgkmcnt(11)
	v_mfma_f32_16x16x32_bf16 v[44:47], v[152:155], v[208:211], v[44:47]
	v_mfma_f32_16x16x32_bf16 v[40:43], v[156:159], v[208:211], v[40:43]
	v_mfma_f32_16x16x32_bf16 v[36:39], v[160:163], v[208:211], v[36:39]
	v_mfma_f32_16x16x32_bf16 v[32:35], v[164:167], v[208:211], v[32:35]
	ds_read_b128 v[208:211], v226 offset:10240
	s_waitcnt lgkmcnt(11)
	v_mfma_f32_16x16x32_bf16 v[28:31], v[152:155], v[212:215], v[28:31]
	v_mfma_f32_16x16x32_bf16 v[24:27], v[156:159], v[212:215], v[24:27]
	v_mfma_f32_16x16x32_bf16 v[20:23], v[160:163], v[212:215], v[20:23]
	v_mfma_f32_16x16x32_bf16 v[16:19], v[164:167], v[212:215], v[16:19]
	ds_read_b128 v[212:215], v226 offset:12288
	v_mfma_f32_16x16x32_bf16 v[12:15], v[152:155], v[216:219], v[12:15]
	v_mfma_f32_16x16x32_bf16 v[8:11], v[156:159], v[216:219], v[8:11]
	v_mfma_f32_16x16x32_bf16 v[4:7], v[160:163], v[216:219], v[4:7]
	v_mfma_f32_16x16x32_bf16 v[0:3], v[164:167], v[216:219], v[0:3]
	s_waitcnt vmcnt(0) lgkmcnt(0)
	s_barrier
	v_mfma_f32_16x16x32_bf16 v[124:127], v[168:171], v[188:191], v[124:127]
	v_mfma_f32_16x16x32_bf16 v[120:123], v[176:179], v[188:191], v[120:123]
	v_mfma_f32_16x16x32_bf16 v[116:119], v[180:183], v[188:191], v[116:119]
	v_mfma_f32_16x16x32_bf16 v[112:115], v[184:187], v[188:191], v[112:115]
	v_mfma_f32_16x16x32_bf16 v[108:111], v[168:171], v[192:195], v[108:111]
	v_mfma_f32_16x16x32_bf16 v[104:107], v[176:179], v[192:195], v[104:107]
	v_mfma_f32_16x16x32_bf16 v[100:103], v[180:183], v[192:195], v[100:103]
	v_mfma_f32_16x16x32_bf16 v[96:99], v[184:187], v[192:195], v[96:99]
	v_mfma_f32_16x16x32_bf16 v[92:95], v[168:171], v[196:199], v[92:95]
	v_mfma_f32_16x16x32_bf16 v[88:91], v[176:179], v[196:199], v[88:91]
	v_mfma_f32_16x16x32_bf16 v[84:87], v[180:183], v[196:199], v[84:87]
	v_mfma_f32_16x16x32_bf16 v[80:83], v[184:187], v[196:199], v[80:83]
	v_mfma_f32_16x16x32_bf16 v[76:79], v[168:171], v[200:203], v[76:79]
	v_mfma_f32_16x16x32_bf16 v[72:75], v[176:179], v[200:203], v[72:75]
	v_mfma_f32_16x16x32_bf16 v[68:71], v[180:183], v[200:203], v[68:71]
	v_mfma_f32_16x16x32_bf16 v[64:67], v[184:187], v[200:203], v[64:67]
	v_mfma_f32_16x16x32_bf16 v[60:63], v[168:171], v[204:207], v[60:63]
	v_mfma_f32_16x16x32_bf16 v[56:59], v[176:179], v[204:207], v[56:59]
	v_mfma_f32_16x16x32_bf16 v[52:55], v[180:183], v[204:207], v[52:55]
	v_mfma_f32_16x16x32_bf16 v[48:51], v[184:187], v[204:207], v[48:51]
	v_mfma_f32_16x16x32_bf16 v[44:47], v[168:171], v[208:211], v[44:47]
	v_mfma_f32_16x16x32_bf16 v[40:43], v[176:179], v[208:211], v[40:43]
	v_mfma_f32_16x16x32_bf16 v[36:39], v[180:183], v[208:211], v[36:39]
	v_mfma_f32_16x16x32_bf16 v[32:35], v[184:187], v[208:211], v[32:35]
	v_mfma_f32_16x16x32_bf16 v[28:31], v[168:171], v[212:215], v[28:31]
	v_mfma_f32_16x16x32_bf16 v[24:27], v[176:179], v[212:215], v[24:27]
	v_mfma_f32_16x16x32_bf16 v[20:23], v[180:183], v[212:215], v[20:23]
	v_mfma_f32_16x16x32_bf16 v[16:19], v[184:187], v[212:215], v[16:19]
	v_mfma_f32_16x16x32_bf16 v[12:15], v[168:171], v[220:223], v[12:15]
	v_mfma_f32_16x16x32_bf16 v[8:11], v[176:179], v[220:223], v[8:11]
	v_mfma_f32_16x16x32_bf16 v[4:7], v[180:183], v[220:223], v[4:7]
	v_mfma_f32_16x16x32_bf16 v[0:3], v[184:187], v[220:223], v[0:3]
	s_nop 7
	s_nop 3
	v_and_b32_e32 v225, 15, v174
	v_lshrrev_b32_e32 v226, 8, v174
	v_lshl_or_b32 v225, v226, 7, v225
	v_bfe_u32 v226, v174, 6, 2
	v_bfe_u32 v227, v174, 4, 2
	v_lshlrev_b32_e32 v227, 2, v227
	v_add_u32_e32 v225, s49, v225
	v_lshl_add_u32 v226, v226, 5, v227
	v_lshl_or_b32 v226, s48, 7, v226
	v_lshlrev_b32_e32 v226, 1, v226
	v_mov_b32_e32 v227, 0x1600
	v_mad_u32_u24 v224, v225, v227, v226
	v_mul_f32_e32 v188, 0xbfb8aa3b, v124
	v_mul_f32_e32 v189, 0xbfb8aa3b, v125
	v_mul_f32_e32 v190, 0xbfb8aa3b, v126
	v_mul_f32_e32 v191, 0xbfb8aa3b, v127
; DI u16 f2bf(float a) { return (u16)(pk2(a, 0.f) & 0xffffu); }
; DI float sigmoidf_(float x) { return __builtin_amdgcn_rcpf(1.f + __builtin_amdgcn_exp2f(-1.4426950408889634f * x)); }
; template <int EPI>
; DI void gemm_phase(const u16* __restrict__ A, int lda, const u16* __restrict__ Bt, int K, int N, u16* outb, int ldo,
;                    const float* r0, const float* r1, float* outf, char* lds, int bid, int nb) {
;     ...
;     } else {
;       const int col = (tn * 4 + wc) * 32 + l15;
; #pragma unroll
;       for (int i = 0; i < 8; ++i)
; #pragma unroll
;         for (int r = 0; r < 4; ++r) {
;           const float g0 = acc[i][0][r], u0 = acc[i][2][r], g1 = acc[i][1][r], u1 = acc[i][3][r];
;           u16* o0 = outb + (size_t)(mrow + i * 16 + r) * ldo + col;
;           o0[0] = f2bf(g0 * sigmoidf_(g0) * u0); o0[16] = f2bf(g1 * sigmoidf_(g1) * u1);
;         }
	v_exp_f32_e32 v188, v188
	v_exp_f32_e32 v189, v189
	v_exp_f32_e32 v190, v190
	v_exp_f32_e32 v191, v191
	v_add_f32_e32 v188, 1.0, v188
	v_add_f32_e32 v189, 1.0, v189
	v_add_f32_e32 v190, 1.0, v190
	v_add_f32_e32 v191, 1.0, v191
	v_rcp_f32_e32 v188, v188
	v_rcp_f32_e32 v189, v189
	v_rcp_f32_e32 v190, v190
	v_rcp_f32_e32 v191, v191
	v_mul_f32_e32 v188, v124, v188
	v_mul_f32_e32 v189, v125, v189
	v_mul_f32_e32 v190, v126, v190
	v_mul_f32_e32 v191, v127, v191
	v_mul_f32_e32 v188, v116, v188
	v_mul_f32_e32 v189, v117, v189
	v_mul_f32_e32 v190, v118, v190
	v_mul_f32_e32 v191, v119, v191
	v_cvt_pk_bf16_f32 v200, v188, v189
	v_cvt_pk_bf16_f32 v201, v190, v191
	global_store_dwordx2 v224, v[200:201], s[8:9] offset:0
	v_mul_f32_e32 v188, 0xbfb8aa3b, v120
	v_mul_f32_e32 v189, 0xbfb8aa3b, v121
	v_mul_f32_e32 v190, 0xbfb8aa3b, v122
	v_mul_f32_e32 v191, 0xbfb8aa3b, v123
	v_exp_f32_e32 v188, v188
	v_exp_f32_e32 v189, v189
	v_exp_f32_e32 v190, v190
	v_exp_f32_e32 v191, v191
	v_add_f32_e32 v188, 1.0, v188
	v_add_f32_e32 v189, 1.0, v189
	v_add_f32_e32 v190, 1.0, v190
	v_add_f32_e32 v191, 1.0, v191
	v_rcp_f32_e32 v188, v188
	v_rcp_f32_e32 v189, v189
	v_rcp_f32_e32 v190, v190
	v_rcp_f32_e32 v191, v191
	v_mul_f32_e32 v188, v120, v188
	v_mul_f32_e32 v189, v121, v189
	v_mul_f32_e32 v190, v122, v190
	v_mul_f32_e32 v191, v123, v191
	v_mul_f32_e32 v188, v112, v188
	v_mul_f32_e32 v189, v113, v189
	v_mul_f32_e32 v190, v114, v190
	v_mul_f32_e32 v191, v115, v191
	v_cvt_pk_bf16_f32 v202, v188, v189
	v_cvt_pk_bf16_f32 v203, v190, v191
	global_store_dwordx2 v224, v[202:203], s[8:9] offset:32
	v_add_u32_e32 v224, 0x16000, v224
	v_mul_f32_e32 v188, 0xbfb8aa3b, v108
	v_mul_f32_e32 v189, 0xbfb8aa3b, v109
	v_mul_f32_e32 v190, 0xbfb8aa3b, v110
	v_mul_f32_e32 v191, 0xbfb8aa3b, v111
	v_exp_f32_e32 v188, v188
	v_exp_f32_e32 v189, v189
	v_exp_f32_e32 v190, v190
	v_exp_f32_e32 v191, v191
	v_add_f32_e32 v188, 1.0, v188
	v_add_f32_e32 v189, 1.0, v189
	v_add_f32_e32 v190, 1.0, v190
	v_add_f32_e32 v191, 1.0, v191
	v_rcp_f32_e32 v188, v188
	v_rcp_f32_e32 v189, v189
	v_rcp_f32_e32 v190, v190
	v_rcp_f32_e32 v191, v191
	v_mul_f32_e32 v188, v108, v188
	v_mul_f32_e32 v189, v109, v189
	v_mul_f32_e32 v190, v110, v190
	v_mul_f32_e32 v191, v111, v191
	v_mul_f32_e32 v188, v100, v188
	v_mul_f32_e32 v189, v101, v189
	v_mul_f32_e32 v190, v102, v190
	v_mul_f32_e32 v191, v103, v191
	v_cvt_pk_bf16_f32 v204, v188, v189
	v_cvt_pk_bf16_f32 v205, v190, v191
	global_store_dwordx2 v224, v[204:205], s[8:9] offset:0
	v_mul_f32_e32 v188, 0xbfb8aa3b, v104
	v_mul_f32_e32 v189, 0xbfb8aa3b, v105
	v_mul_f32_e32 v190, 0xbfb8aa3b, v106
	v_mul_f32_e32 v191, 0xbfb8aa3b, v107
	v_exp_f32_e32 v188, v188
	v_exp_f32_e32 v189, v189
	v_exp_f32_e32 v190, v190
	v_exp_f32_e32 v191, v191
	v_add_f32_e32 v188, 1.0, v188
	v_add_f32_e32 v189, 1.0, v189
	v_add_f32_e32 v190, 1.0, v190
	v_add_f32_e32 v191, 1.0, v191
	v_rcp_f32_e32 v188, v188
	v_rcp_f32_e32 v189, v189
	v_rcp_f32_e32 v190, v190
	v_rcp_f32_e32 v191, v191
	v_mul_f32_e32 v188, v104, v188
	v_mul_f32_e32 v189, v105, v189
	v_mul_f32_e32 v190, v106, v190
	v_mul_f32_e32 v191, v107, v191
	v_mul_f32_e32 v188, v96, v188
	v_mul_f32_e32 v189, v97, v189
	v_mul_f32_e32 v190, v98, v190
	v_mul_f32_e32 v191, v99, v191
	v_cvt_pk_bf16_f32 v206, v188, v189
	v_cvt_pk_bf16_f32 v207, v190, v191
	global_store_dwordx2 v224, v[206:207], s[8:9] offset:32
	v_add_u32_e32 v224, 0x16000, v224
	v_mul_f32_e32 v188, 0xbfb8aa3b, v92
	v_mul_f32_e32 v189, 0xbfb8aa3b, v93
	v_mul_f32_e32 v190, 0xbfb8aa3b, v94
	v_mul_f32_e32 v191, 0xbfb8aa3b, v95
	v_exp_f32_e32 v188, v188
	v_exp_f32_e32 v189, v189
	v_exp_f32_e32 v190, v190
	v_exp_f32_e32 v191, v191
	v_add_f32_e32 v188, 1.0, v188
	v_add_f32_e32 v189, 1.0, v189
	v_add_f32_e32 v190, 1.0, v190
	v_add_f32_e32 v191, 1.0, v191
	v_rcp_f32_e32 v188, v188
	v_rcp_f32_e32 v189, v189
	v_rcp_f32_e32 v190, v190
	v_rcp_f32_e32 v191, v191
	v_mul_f32_e32 v188, v92, v188
	v_mul_f32_e32 v189, v93, v189
	v_mul_f32_e32 v190, v94, v190
	v_mul_f32_e32 v191, v95, v191
	v_mul_f32_e32 v188, v84, v188
	v_mul_f32_e32 v189, v85, v189
	v_mul_f32_e32 v190, v86, v190
	v_mul_f32_e32 v191, v87, v191
	v_cvt_pk_bf16_f32 v208, v188, v189
	v_cvt_pk_bf16_f32 v209, v190, v191
	global_store_dwordx2 v224, v[208:209], s[8:9] offset:0
	v_mul_f32_e32 v188, 0xbfb8aa3b, v88
	v_mul_f32_e32 v189, 0xbfb8aa3b, v89
	v_mul_f32_e32 v190, 0xbfb8aa3b, v90
	v_mul_f32_e32 v191, 0xbfb8aa3b, v91
	v_exp_f32_e32 v188, v188
	v_exp_f32_e32 v189, v189
	v_exp_f32_e32 v190, v190
	v_exp_f32_e32 v191, v191
	v_add_f32_e32 v188, 1.0, v188
	v_add_f32_e32 v189, 1.0, v189
	v_add_f32_e32 v190, 1.0, v190
	v_add_f32_e32 v191, 1.0, v191
	v_rcp_f32_e32 v188, v188
	v_rcp_f32_e32 v189, v189
	v_rcp_f32_e32 v190, v190
	v_rcp_f32_e32 v191, v191
	v_mul_f32_e32 v188, v88, v188
	v_mul_f32_e32 v189, v89, v189
	v_mul_f32_e32 v190, v90, v190
	v_mul_f32_e32 v191, v91, v191
	v_mul_f32_e32 v188, v80, v188
	v_mul_f32_e32 v189, v81, v189
	v_mul_f32_e32 v190, v82, v190
	v_mul_f32_e32 v191, v83, v191
	v_cvt_pk_bf16_f32 v210, v188, v189
	v_cvt_pk_bf16_f32 v211, v190, v191
	global_store_dwordx2 v224, v[210:211], s[8:9] offset:32
	v_add_u32_e32 v224, 0x16000, v224
	v_mul_f32_e32 v188, 0xbfb8aa3b, v76
	v_mul_f32_e32 v189, 0xbfb8aa3b, v77
	v_mul_f32_e32 v190, 0xbfb8aa3b, v78
	v_mul_f32_e32 v191, 0xbfb8aa3b, v79
	v_exp_f32_e32 v188, v188
	v_exp_f32_e32 v189, v189
	v_exp_f32_e32 v190, v190
	v_exp_f32_e32 v191, v191
	v_add_f32_e32 v188, 1.0, v188
	v_add_f32_e32 v189, 1.0, v189
	v_add_f32_e32 v190, 1.0, v190
	v_add_f32_e32 v191, 1.0, v191
	v_rcp_f32_e32 v188, v188
	v_rcp_f32_e32 v189, v189
	v_rcp_f32_e32 v190, v190
	v_rcp_f32_e32 v191, v191
	v_mul_f32_e32 v188, v76, v188
; DI u16 f2bf(float a) { return (u16)(pk2(a, 0.f) & 0xffffu); }
; DI float sigmoidf_(float x) { return __builtin_amdgcn_rcpf(1.f + __builtin_amdgcn_exp2f(-1.4426950408889634f * x)); }
; template <int EPI>
; DI void gemm_phase(const u16* __restrict__ A, int lda, const u16* __restrict__ Bt, int K, int N, u16* outb, int ldo,
;                    const float* r0, const float* r1, float* outf, char* lds, int bid, int nb) {
;     ...
;     } else {
;       const int col = (tn * 4 + wc) * 32 + l15;
; #pragma unroll
;       for (int i = 0; i < 8; ++i)
; #pragma unroll
;         for (int r = 0; r < 4; ++r) {
;           const float g0 = acc[i][0][r], u0 = acc[i][2][r], g1 = acc[i][1][r], u1 = acc[i][3][r];
;           u16* o0 = outb + (size_t)(mrow + i * 16 + r) * ldo + col;
;           o0[0] = f2bf(g0 * sigmoidf_(g0) * u0); o0[16] = f2bf(g1 * sigmoidf_(g1) * u1);
;         }
	v_mul_f32_e32 v189, v77, v189
	v_mul_f32_e32 v190, v78, v190
	v_mul_f32_e32 v191, v79, v191
	v_mul_f32_e32 v188, v68, v188
	v_mul_f32_e32 v189, v69, v189
	v_mul_f32_e32 v190, v70, v190
	v_mul_f32_e32 v191, v71, v191
	v_cvt_pk_bf16_f32 v212, v188, v189
	v_cvt_pk_bf16_f32 v213, v190, v191
	global_store_dwordx2 v224, v[212:213], s[8:9] offset:0
	v_mul_f32_e32 v188, 0xbfb8aa3b, v72
	v_mul_f32_e32 v189, 0xbfb8aa3b, v73
	v_mul_f32_e32 v190, 0xbfb8aa3b, v74
	v_mul_f32_e32 v191, 0xbfb8aa3b, v75
	v_exp_f32_e32 v188, v188
	v_exp_f32_e32 v189, v189
	v_exp_f32_e32 v190, v190
	v_exp_f32_e32 v191, v191
	v_add_f32_e32 v188, 1.0, v188
	v_add_f32_e32 v189, 1.0, v189
	v_add_f32_e32 v190, 1.0, v190
	v_add_f32_e32 v191, 1.0, v191
	v_rcp_f32_e32 v188, v188
	v_rcp_f32_e32 v189, v189
	v_rcp_f32_e32 v190, v190
	v_rcp_f32_e32 v191, v191
	v_mul_f32_e32 v188, v72, v188
	v_mul_f32_e32 v189, v73, v189
	v_mul_f32_e32 v190, v74, v190
	v_mul_f32_e32 v191, v75, v191
	v_mul_f32_e32 v188, v64, v188
	v_mul_f32_e32 v189, v65, v189
	v_mul_f32_e32 v190, v66, v190
	v_mul_f32_e32 v191, v67, v191
	v_cvt_pk_bf16_f32 v214, v188, v189
	v_cvt_pk_bf16_f32 v215, v190, v191
	global_store_dwordx2 v224, v[214:215], s[8:9] offset:32
	v_add_u32_e32 v224, 0x16000, v224
	v_mul_f32_e32 v188, 0xbfb8aa3b, v60
	v_mul_f32_e32 v189, 0xbfb8aa3b, v61
	v_mul_f32_e32 v190, 0xbfb8aa3b, v62
	v_mul_f32_e32 v191, 0xbfb8aa3b, v63
	v_exp_f32_e32 v188, v188
	v_exp_f32_e32 v189, v189
	v_exp_f32_e32 v190, v190
	v_exp_f32_e32 v191, v191
	v_add_f32_e32 v188, 1.0, v188
	v_add_f32_e32 v189, 1.0, v189
	v_add_f32_e32 v190, 1.0, v190
	v_add_f32_e32 v191, 1.0, v191
	v_rcp_f32_e32 v188, v188
	v_rcp_f32_e32 v189, v189
	v_rcp_f32_e32 v190, v190
	v_rcp_f32_e32 v191, v191
	v_mul_f32_e32 v188, v60, v188
	v_mul_f32_e32 v189, v61, v189
	v_mul_f32_e32 v190, v62, v190
	v_mul_f32_e32 v191, v63, v191
	v_mul_f32_e32 v188, v52, v188
	v_mul_f32_e32 v189, v53, v189
	v_mul_f32_e32 v190, v54, v190
	v_mul_f32_e32 v191, v55, v191
	v_cvt_pk_bf16_f32 v200, v188, v189
	v_cvt_pk_bf16_f32 v201, v190, v191
	global_store_dwordx2 v224, v[200:201], s[8:9] offset:0
	v_mul_f32_e32 v188, 0xbfb8aa3b, v56
	v_mul_f32_e32 v189, 0xbfb8aa3b, v57
	v_mul_f32_e32 v190, 0xbfb8aa3b, v58
	v_mul_f32_e32 v191, 0xbfb8aa3b, v59
	v_exp_f32_e32 v188, v188
	v_exp_f32_e32 v189, v189
	v_exp_f32_e32 v190, v190
	v_exp_f32_e32 v191, v191
	v_add_f32_e32 v188, 1.0, v188
	v_add_f32_e32 v189, 1.0, v189
	v_add_f32_e32 v190, 1.0, v190
	v_add_f32_e32 v191, 1.0, v191
	v_rcp_f32_e32 v188, v188
	v_rcp_f32_e32 v189, v189
	v_rcp_f32_e32 v190, v190
	v_rcp_f32_e32 v191, v191
	v_mul_f32_e32 v188, v56, v188
	v_mul_f32_e32 v189, v57, v189
	v_mul_f32_e32 v190, v58, v190
	v_mul_f32_e32 v191, v59, v191
	v_mul_f32_e32 v188, v48, v188
	v_mul_f32_e32 v189, v49, v189
	v_mul_f32_e32 v190, v50, v190
	v_mul_f32_e32 v191, v51, v191
	v_cvt_pk_bf16_f32 v202, v188, v189
	v_cvt_pk_bf16_f32 v203, v190, v191
	global_store_dwordx2 v224, v[202:203], s[8:9] offset:32
	v_add_u32_e32 v224, 0x16000, v224
	v_mul_f32_e32 v188, 0xbfb8aa3b, v44
	v_mul_f32_e32 v189, 0xbfb8aa3b, v45
	v_mul_f32_e32 v190, 0xbfb8aa3b, v46
	v_mul_f32_e32 v191, 0xbfb8aa3b, v47
	v_exp_f32_e32 v188, v188
	v_exp_f32_e32 v189, v189
	v_exp_f32_e32 v190, v190
	v_exp_f32_e32 v191, v191
	v_add_f32_e32 v188, 1.0, v188
	v_add_f32_e32 v189, 1.0, v189
	v_add_f32_e32 v190, 1.0, v190
	v_add_f32_e32 v191, 1.0, v191
	v_rcp_f32_e32 v188, v188
	v_rcp_f32_e32 v189, v189
	v_rcp_f32_e32 v190, v190
	v_rcp_f32_e32 v191, v191
	v_mul_f32_e32 v188, v44, v188
	v_mul_f32_e32 v189, v45, v189
	v_mul_f32_e32 v190, v46, v190
	v_mul_f32_e32 v191, v47, v191
	v_mul_f32_e32 v188, v36, v188
	v_mul_f32_e32 v189, v37, v189
	v_mul_f32_e32 v190, v38, v190
	v_mul_f32_e32 v191, v39, v191
	v_cvt_pk_bf16_f32 v204, v188, v189
	v_cvt_pk_bf16_f32 v205, v190, v191
	global_store_dwordx2 v224, v[204:205], s[8:9] offset:0
	v_mul_f32_e32 v188, 0xbfb8aa3b, v40
	v_mul_f32_e32 v189, 0xbfb8aa3b, v41
	v_mul_f32_e32 v190, 0xbfb8aa3b, v42
	v_mul_f32_e32 v191, 0xbfb8aa3b, v43
	v_exp_f32_e32 v188, v188
	v_exp_f32_e32 v189, v189
	v_exp_f32_e32 v190, v190
	v_exp_f32_e32 v191, v191
	v_add_f32_e32 v188, 1.0, v188
; DI u16 f2bf(float a) { return (u16)(pk2(a, 0.f) & 0xffffu); }
; DI float sigmoidf_(float x) { return __builtin_amdgcn_rcpf(1.f + __builtin_amdgcn_exp2f(-1.4426950408889634f * x)); }
; template <int EPI>
; DI void gemm_phase(const u16* __restrict__ A, int lda, const u16* __restrict__ Bt, int K, int N, u16* outb, int ldo,
;                    const float* r0, const float* r1, float* outf, char* lds, int bid, int nb) {
;     ...
;     } else {
;       const int col = (tn * 4 + wc) * 32 + l15;
; #pragma unroll
;       for (int i = 0; i < 8; ++i)
; #pragma unroll
;         for (int r = 0; r < 4; ++r) {
;           const float g0 = acc[i][0][r], u0 = acc[i][2][r], g1 = acc[i][1][r], u1 = acc[i][3][r];
;           u16* o0 = outb + (size_t)(mrow + i * 16 + r) * ldo + col;
;           o0[0] = f2bf(g0 * sigmoidf_(g0) * u0); o0[16] = f2bf(g1 * sigmoidf_(g1) * u1);
;         }
	v_add_f32_e32 v189, 1.0, v189
	v_add_f32_e32 v190, 1.0, v190
	v_add_f32_e32 v191, 1.0, v191
	v_rcp_f32_e32 v188, v188
	v_rcp_f32_e32 v189, v189
	v_rcp_f32_e32 v190, v190
	v_rcp_f32_e32 v191, v191
	v_mul_f32_e32 v188, v40, v188
	v_mul_f32_e32 v189, v41, v189
	v_mul_f32_e32 v190, v42, v190
	v_mul_f32_e32 v191, v43, v191
	v_mul_f32_e32 v188, v32, v188
	v_mul_f32_e32 v189, v33, v189
	v_mul_f32_e32 v190, v34, v190
	v_mul_f32_e32 v191, v35, v191
	v_cvt_pk_bf16_f32 v206, v188, v189
	v_cvt_pk_bf16_f32 v207, v190, v191
	global_store_dwordx2 v224, v[206:207], s[8:9] offset:32
	v_add_u32_e32 v224, 0x16000, v224
	v_mul_f32_e32 v188, 0xbfb8aa3b, v28
	v_mul_f32_e32 v189, 0xbfb8aa3b, v29
	v_mul_f32_e32 v190, 0xbfb8aa3b, v30
	v_mul_f32_e32 v191, 0xbfb8aa3b, v31
	v_exp_f32_e32 v188, v188
	v_exp_f32_e32 v189, v189
	v_exp_f32_e32 v190, v190
	v_exp_f32_e32 v191, v191
	v_add_f32_e32 v188, 1.0, v188
	v_add_f32_e32 v189, 1.0, v189
	v_add_f32_e32 v190, 1.0, v190
	v_add_f32_e32 v191, 1.0, v191
	v_rcp_f32_e32 v188, v188
	v_rcp_f32_e32 v189, v189
	v_rcp_f32_e32 v190, v190
	v_rcp_f32_e32 v191, v191
	v_mul_f32_e32 v188, v28, v188
	v_mul_f32_e32 v189, v29, v189
	v_mul_f32_e32 v190, v30, v190
	v_mul_f32_e32 v191, v31, v191
	v_mul_f32_e32 v188, v20, v188
	v_mul_f32_e32 v189, v21, v189
	v_mul_f32_e32 v190, v22, v190
	v_mul_f32_e32 v191, v23, v191
	v_cvt_pk_bf16_f32 v208, v188, v189
	v_cvt_pk_bf16_f32 v209, v190, v191
	global_store_dwordx2 v224, v[208:209], s[8:9] offset:0
	v_mul_f32_e32 v188, 0xbfb8aa3b, v24
	v_mul_f32_e32 v189, 0xbfb8aa3b, v25
	v_mul_f32_e32 v190, 0xbfb8aa3b, v26
	v_mul_f32_e32 v191, 0xbfb8aa3b, v27
	v_exp_f32_e32 v188, v188
	v_exp_f32_e32 v189, v189
	v_exp_f32_e32 v190, v190
	v_exp_f32_e32 v191, v191
	v_add_f32_e32 v188, 1.0, v188
	v_add_f32_e32 v189, 1.0, v189
	v_add_f32_e32 v190, 1.0, v190
	v_add_f32_e32 v191, 1.0, v191
	v_rcp_f32_e32 v188, v188
	v_rcp_f32_e32 v189, v189
	v_rcp_f32_e32 v190, v190
	v_rcp_f32_e32 v191, v191
	v_mul_f32_e32 v188, v24, v188
	v_mul_f32_e32 v189, v25, v189
	v_mul_f32_e32 v190, v26, v190
	v_mul_f32_e32 v191, v27, v191
	v_mul_f32_e32 v188, v16, v188
	v_mul_f32_e32 v189, v17, v189
	v_mul_f32_e32 v190, v18, v190
	v_mul_f32_e32 v191, v19, v191
	v_cvt_pk_bf16_f32 v210, v188, v189
	v_cvt_pk_bf16_f32 v211, v190, v191
	global_store_dwordx2 v224, v[210:211], s[8:9] offset:32
	v_add_u32_e32 v224, 0x16000, v224
	v_mul_f32_e32 v188, 0xbfb8aa3b, v12
	v_mul_f32_e32 v189, 0xbfb8aa3b, v13
	v_mul_f32_e32 v190, 0xbfb8aa3b, v14
	v_mul_f32_e32 v191, 0xbfb8aa3b, v15
	v_exp_f32_e32 v188, v188
	v_exp_f32_e32 v189, v189
	v_exp_f32_e32 v190, v190
	v_exp_f32_e32 v191, v191
	v_add_f32_e32 v188, 1.0, v188
	v_add_f32_e32 v189, 1.0, v189
	v_add_f32_e32 v190, 1.0, v190
	v_add_f32_e32 v191, 1.0, v191
	v_rcp_f32_e32 v188, v188
	v_rcp_f32_e32 v189, v189
	v_rcp_f32_e32 v190, v190
	v_rcp_f32_e32 v191, v191
	v_mul_f32_e32 v188, v12, v188
	v_mul_f32_e32 v189, v13, v189
	v_mul_f32_e32 v190, v14, v190
	v_mul_f32_e32 v191, v15, v191
	v_mul_f32_e32 v188, v4, v188
	v_mul_f32_e32 v189, v5, v189
	v_mul_f32_e32 v190, v6, v190
	v_mul_f32_e32 v191, v7, v191
	v_cvt_pk_bf16_f32 v212, v188, v189
	v_cvt_pk_bf16_f32 v213, v190, v191
	global_store_dwordx2 v224, v[212:213], s[8:9] offset:0
	v_mul_f32_e32 v188, 0xbfb8aa3b, v8
	v_mul_f32_e32 v189, 0xbfb8aa3b, v9
	v_mul_f32_e32 v190, 0xbfb8aa3b, v10
	v_mul_f32_e32 v191, 0xbfb8aa3b, v11
	v_exp_f32_e32 v188, v188
	v_exp_f32_e32 v189, v189
	v_exp_f32_e32 v190, v190
	v_exp_f32_e32 v191, v191
	v_add_f32_e32 v188, 1.0, v188
	v_add_f32_e32 v189, 1.0, v189
	v_add_f32_e32 v190, 1.0, v190
	v_add_f32_e32 v191, 1.0, v191
	v_rcp_f32_e32 v188, v188
	v_rcp_f32_e32 v189, v189
	v_rcp_f32_e32 v190, v190
	v_rcp_f32_e32 v191, v191
	v_mul_f32_e32 v188, v8, v188
	v_mul_f32_e32 v189, v9, v189
	v_mul_f32_e32 v190, v10, v190
	v_mul_f32_e32 v191, v11, v191
	v_mul_f32_e32 v188, v0, v188
	v_mul_f32_e32 v189, v1, v189
	v_mul_f32_e32 v190, v2, v190
	v_mul_f32_e32 v191, v3, v191
	v_cvt_pk_bf16_f32 v214, v188, v189
	v_cvt_pk_bf16_f32 v215, v190, v191
	global_store_dwordx2 v224, v[214:215], s[8:9] offset:32
	s_add_i32 s19, s19, 1
	s_cmp_eq_u32 s19, s3
	s_cbranch_scc0 .LBB0_697

; #define G_LOAD(KT) do { _Pragma("unroll") for (int i = 0; i < 4; ++i) { ra[i] = *(const u32x4*)(Ag + (size_t)i * 64 * lda + (KT) * 64); rb[i] = *(const u32x4*)(Bg + (size_t)i * 64 * K + (KT) * 64); } } while (0)
; #define G_STORE(BUF) do { u16* ad = As + (BUF) * 256 * 64 + sto; u16* bd = Bs + (BUF) * 256 * 64 + sto; _Pragma("unroll") for (int i = 0; i < 4; ++i) { *(u32x4*)(ad + i * 64 * 64) = ra[i]; *(u32x4*)(bd + i * 64 * 64) = rb[i]; } } while (0)
; template <int EPI>
; DI void gemm_phase(const u16* __restrict__ A, int lda, const u16* __restrict__ Bt, int K, int N, u16* outb, int ldo,
;                    const float* r0, const float* r1, float* outf, char* lds, int bid, int nb) {
;     ...
;     G_LOAD(0);
;     G_STORE(0);
;     __syncthreads();
;     for (int kt = 0; kt < nk; ++kt) {
;       const int cur = kt & 1;
;       if (kt + 1 < nk) G_LOAD(kt + 1);
;       G_MMA(cur, fo0);
;       G_MMA(cur, fo1);
;       if (kt + 1 < nk) G_STORE(cur ^ 1);
;       __syncthreads();
;     }
.Lgm3_loop:
	s_waitcnt lgkmcnt(4)
	v_mfma_f32_16x16x32_bf16 v[124:127], v[152:155], v[188:191], v[124:127]
	v_mfma_f32_16x16x32_bf16 v[120:123], v[156:159], v[188:191], v[120:123]
	v_mfma_f32_16x16x32_bf16 v[116:119], v[160:163], v[188:191], v[116:119]
	v_mfma_f32_16x16x32_bf16 v[112:115], v[164:167], v[188:191], v[112:115]
	ds_read_b128 v[188:191], v226 offset:0
	ds_read_b128 v[168:171], v228 offset:0
	v_mfma_f32_16x16x32_bf16 v[108:111], v[152:155], v[192:195], v[108:111]
	v_mfma_f32_16x16x32_bf16 v[104:107], v[156:159], v[192:195], v[104:107]
	v_mfma_f32_16x16x32_bf16 v[100:103], v[160:163], v[192:195], v[100:103]
	v_mfma_f32_16x16x32_bf16 v[96:99], v[164:167], v[192:195], v[96:99]
	ds_read_b128 v[192:195], v226 offset:2048
	ds_read_b128 v[176:179], v228 offset:2048
	v_mfma_f32_16x16x32_bf16 v[92:95], v[152:155], v[196:199], v[92:95]
	v_mfma_f32_16x16x32_bf16 v[88:91], v[156:159], v[196:199], v[88:91]
	v_mfma_f32_16x16x32_bf16 v[84:87], v[160:163], v[196:199], v[84:87]
	v_mfma_f32_16x16x32_bf16 v[80:83], v[164:167], v[196:199], v[80:83]
	ds_read_b128 v[196:199], v226 offset:4096
	ds_read_b128 v[180:183], v228 offset:4096
	v_mfma_f32_16x16x32_bf16 v[76:79], v[152:155], v[200:203], v[76:79]
	v_mfma_f32_16x16x32_bf16 v[72:75], v[156:159], v[200:203], v[72:75]
	v_mfma_f32_16x16x32_bf16 v[68:71], v[160:163], v[200:203], v[68:71]
	v_mfma_f32_16x16x32_bf16 v[64:67], v[164:167], v[200:203], v[64:67]
	ds_read_b128 v[200:203], v226 offset:6144
	ds_read_b128 v[184:187], v228 offset:6144
	s_waitcnt lgkmcnt(11)
	v_mfma_f32_16x16x32_bf16 v[60:63], v[152:155], v[204:207], v[60:63]
	v_mfma_f32_16x16x32_bf16 v[56:59], v[156:159], v[204:207], v[56:59]
	v_mfma_f32_16x16x32_bf16 v[52:55], v[160:163], v[204:207], v[52:55]
	v_mfma_f32_16x16x32_bf16 v[48:51], v[164:167], v[204:207], v[48:51]
	ds_read_b128 v[204:207], v226 offset:8192
	ds_read_b128 v[220:223], v226 offset:14336
	s_waitcnt lgkmcnt(11)
	v_mfma_f32_16x16x32_bf16 v[44:47], v[152:155], v[208:211], v[44:47]
	v_mfma_f32_16x16x32_bf16 v[40:43], v[156:159], v[208:211], v[40:43]
	v_mfma_f32_16x16x32_bf16 v[36:39], v[160:163], v[208:211], v[36:39]
	v_mfma_f32_16x16x32_bf16 v[32:35], v[164:167], v[208:211], v[32:35]
	ds_read_b128 v[208:211], v226 offset:10240
	s_waitcnt lgkmcnt(11)
	v_mfma_f32_16x16x32_bf16 v[28:31], v[152:155], v[212:215], v[28:31]
	v_mfma_f32_16x16x32_bf16 v[24:27], v[156:159], v[212:215], v[24:27]
	v_mfma_f32_16x16x32_bf16 v[20:23], v[160:163], v[212:215], v[20:23]
	v_mfma_f32_16x16x32_bf16 v[16:19], v[164:167], v[212:215], v[16:19]
	ds_read_b128 v[212:215], v226 offset:12288
	v_mfma_f32_16x16x32_bf16 v[12:15], v[152:155], v[216:219], v[12:15]
	v_mfma_f32_16x16x32_bf16 v[8:11], v[156:159], v[216:219], v[8:11]
	v_mfma_f32_16x16x32_bf16 v[4:7], v[160:163], v[216:219], v[4:7]
	v_mfma_f32_16x16x32_bf16 v[0:3], v[164:167], v[216:219], v[0:3]
	s_waitcnt vmcnt(0) lgkmcnt(0)
	s_barrier
	v_mfma_f32_16x16x32_bf16 v[124:127], v[168:171], v[188:191], v[124:127]
	v_mfma_f32_16x16x32_bf16 v[120:123], v[176:179], v[188:191], v[120:123]
	v_mfma_f32_16x16x32_bf16 v[116:119], v[180:183], v[188:191], v[116:119]
	v_mfma_f32_16x16x32_bf16 v[112:115], v[184:187], v[188:191], v[112:115]
	ds_read_b128 v[188:191], v225 offset:0
	ds_read_b128 v[152:155], v227 offset:0
	s_add_u32 s8, s98, 0x0
	s_addc_u32 s9, s99, 0
	s_add_u32 m0, s97, 0x0
	s_nop 0
	global_load_lds_dwordx4 v224, s[8:9]
	v_mfma_f32_16x16x32_bf16 v[108:111], v[168:171], v[192:195], v[108:111]
	v_mfma_f32_16x16x32_bf16 v[104:107], v[176:179], v[192:195], v[104:107]
	v_mfma_f32_16x16x32_bf16 v[100:103], v[180:183], v[192:195], v[100:103]
	v_mfma_f32_16x16x32_bf16 v[96:99], v[184:187], v[192:195], v[96:99]
	ds_read_b128 v[192:195], v225 offset:2048
	ds_read_b128 v[156:159], v227 offset:2048
	s_add_u32 s8, s100, 0x0
	s_addc_u32 s9, s101, 0
	s_add_u32 m0, s97, 0x10000
	s_nop 0
	global_load_lds_dwordx4 v224, s[8:9]
	v_mfma_f32_16x16x32_bf16 v[92:95], v[168:171], v[196:199], v[92:95]
	v_mfma_f32_16x16x32_bf16 v[88:91], v[176:179], v[196:199], v[88:91]
	v_mfma_f32_16x16x32_bf16 v[84:87], v[180:183], v[196:199], v[84:87]
	v_mfma_f32_16x16x32_bf16 v[80:83], v[184:187], v[196:199], v[80:83]
	ds_read_b128 v[196:199], v225 offset:4096
	ds_read_b128 v[160:163], v227 offset:4096
	s_add_u32 s8, s98, 0x58000
	s_addc_u32 s9, s99, 0
	s_add_u32 m0, s97, 0x2000
	s_nop 0
	global_load_lds_dwordx4 v224, s[8:9]
	v_mfma_f32_16x16x32_bf16 v[76:79], v[168:171], v[200:203], v[76:79]
	v_mfma_f32_16x16x32_bf16 v[72:75], v[176:179], v[200:203], v[72:75]
	v_mfma_f32_16x16x32_bf16 v[68:71], v[180:183], v[200:203], v[68:71]
	v_mfma_f32_16x16x32_bf16 v[64:67], v[184:187], v[200:203], v[64:67]
	ds_read_b128 v[200:203], v225 offset:6144
	ds_read_b128 v[164:167], v227 offset:6144
	s_add_u32 s8, s100, 0x58000
	s_addc_u32 s9, s101, 0
	s_add_u32 m0, s97, 0x12000
	s_nop 0
	global_load_lds_dwordx4 v224, s[8:9]
	v_mfma_f32_16x16x32_bf16 v[60:63], v[168:171], v[204:207], v[60:63]
	v_mfma_f32_16x16x32_bf16 v[56:59], v[176:179], v[204:207], v[56:59]
	v_mfma_f32_16x16x32_bf16 v[52:55], v[180:183], v[204:207], v[52:55]
	v_mfma_f32_16x16x32_bf16 v[48:51], v[184:187], v[204:207], v[48:51]
	ds_read_b128 v[204:207], v225 offset:8192
	ds_read_b128 v[216:219], v225 offset:14336
	s_add_u32 s8, s98, 0xb0000
	s_addc_u32 s9, s99, 0
	s_add_u32 m0, s97, 0x4000
	s_nop 0
	global_load_lds_dwordx4 v224, s[8:9]
	v_mfma_f32_16x16x32_bf16 v[44:47], v[168:171], v[208:211], v[44:47]
	v_mfma_f32_16x16x32_bf16 v[40:43], v[176:179], v[208:211], v[40:43]
	v_mfma_f32_16x16x32_bf16 v[36:39], v[180:183], v[208:211], v[36:39]
	v_mfma_f32_16x16x32_bf16 v[32:35], v[184:187], v[208:211], v[32:35]
	ds_read_b128 v[208:211], v225 offset:10240
	s_add_u32 s8, s100, 0xb0000
	s_addc_u32 s9, s101, 0
	s_add_u32 m0, s97, 0x14000
	s_nop 0
	global_load_lds_dwordx4 v224, s[8:9]
	v_mfma_f32_16x16x32_bf16 v[28:31], v[168:171], v[212:215], v[28:31]
	v_mfma_f32_16x16x32_bf16 v[24:27], v[176:179], v[212:215], v[24:27]
	v_mfma_f32_16x16x32_bf16 v[20:23], v[180:183], v[212:215], v[20:23]
	v_mfma_f32_16x16x32_bf16 v[16:19], v[184:187], v[212:215], v[16:19]
	ds_read_b128 v[212:215], v225 offset:12288
	s_add_u32 s8, s98, 0x108000
	s_addc_u32 s9, s99, 0
	s_add_u32 m0, s97, 0x6000
	s_nop 0
	global_load_lds_dwordx4 v224, s[8:9]
	v_mfma_f32_16x16x32_bf16 v[12:15], v[168:171], v[220:223], v[12:15]
	v_mfma_f32_16x16x32_bf16 v[8:11], v[176:179], v[220:223], v[8:11]
	v_mfma_f32_16x16x32_bf16 v[4:7], v[180:183], v[220:223], v[4:7]
	v_mfma_f32_16x16x32_bf16 v[0:3], v[184:187], v[220:223], v[0:3]
	s_add_u32 s8, s100, 0x108000
	s_addc_u32 s9, s101, 0
	s_add_u32 m0, s97, 0x16000
	s_nop 0
	global_load_lds_dwordx4 v224, s[8:9]
	v_xor_b32_e32 v225, 0x8000, v225
	v_xor_b32_e32 v227, 0x8000, v227
	v_xor_b32_e32 v226, 0x8000, v226
	v_xor_b32_e32 v228, 0x8000, v228
	s_xor_b32 s97, s97, 0x8000
	s_add_u32 s98, s98, 0x80
	s_addc_u32 s99, s99, 0
	s_add_u32 s100, s100, 0x80
	s_addc_u32 s101, s101, 0
	s_sub_u32 s28, s28, 1
	s_cmp_lg_u32 s28, 0
	s_cbranch_scc1 .Lgm3_loop
; #define G_LOAD(KT) do { _Pragma("unroll") for (int i = 0; i < 4; ++i) { ra[i] = *(const u32x4*)(Ag + (size_t)i * 64 * lda + (KT) * 64); rb[i] = *(const u32x4*)(Bg + (size_t)i * 64 * K + (KT) * 64); } } while (0)
; #define G_STORE(BUF) do { u16* ad = As + (BUF) * 256 * 64 + sto; u16* bd = Bs + (BUF) * 256 * 64 + sto; _Pragma("unroll") for (int i = 0; i < 4; ++i) { *(u32x4*)(ad + i * 64 * 64) = ra[i]; *(u32x4*)(bd + i * 64 * 64) = rb[i]; } } while (0)
; template <int EPI>
; DI void gemm_phase(const u16* __restrict__ A, int lda, const u16* __restrict__ Bt, int K, int N, u16* outb, int ldo,
;                    const float* r0, const float* r1, float* outf, char* lds, int bid, int nb) {
;     ...
;     G_LOAD(0);
;     G_STORE(0);
;     __syncthreads();
;     for (int kt = 0; kt < nk; ++kt) {
;       const int cur = kt & 1;
;       if (kt + 1 < nk) G_LOAD(kt + 1);
;       G_MMA(cur, fo0);
;       G_MMA(cur, fo1);
;       if (kt + 1 < nk) G_STORE(cur ^ 1);
;       __syncthreads();
	s_waitcnt lgkmcnt(4)
	v_mfma_f32_16x16x32_bf16 v[124:127], v[152:155], v[188:191], v[124:127]
	v_mfma_f32_16x16x32_bf16 v[120:123], v[156:159], v[188:191], v[120:123]
	v_mfma_f32_16x16x32_bf16 v[116:119], v[160:163], v[188:191], v[116:119]
	v_mfma_f32_16x16x32_bf16 v[112:115], v[164:167], v[188:191], v[112:115]
	ds_read_b128 v[188:191], v226 offset:0
	ds_read_b128 v[168:171], v228 offset:0
	v_mfma_f32_16x16x32_bf16 v[108:111], v[152:155], v[192:195], v[108:111]
	v_mfma_f32_16x16x32_bf16 v[104:107], v[156:159], v[192:195], v[104:107]
	v_mfma_f32_16x16x32_bf16 v[100:103], v[160:163], v[192:195], v[100:103]
	v_mfma_f32_16x16x32_bf16 v[96:99], v[164:167], v[192:195], v[96:99]
	ds_read_b128 v[192:195], v226 offset:2048
	ds_read_b128 v[176:179], v228 offset:2048
	v_mfma_f32_16x16x32_bf16 v[92:95], v[152:155], v[196:199], v[92:95]
	v_mfma_f32_16x16x32_bf16 v[88:91], v[156:159], v[196:199], v[88:91]
	v_mfma_f32_16x16x32_bf16 v[84:87], v[160:163], v[196:199], v[84:87]
	v_mfma_f32_16x16x32_bf16 v[80:83], v[164:167], v[196:199], v[80:83]
	ds_read_b128 v[196:199], v226 offset:4096
	ds_read_b128 v[180:183], v228 offset:4096
	v_mfma_f32_16x16x32_bf16 v[76:79], v[152:155], v[200:203], v[76:79]
	v_mfma_f32_16x16x32_bf16 v[72:75], v[156:159], v[200:203], v[72:75]
	v_mfma_f32_16x16x32_bf16 v[68:71], v[160:163], v[200:203], v[68:71]
	v_mfma_f32_16x16x32_bf16 v[64:67], v[164:167], v[200:203], v[64:67]
	ds_read_b128 v[200:203], v226 offset:6144
	ds_read_b128 v[184:187], v228 offset:6144
	s_waitcnt lgkmcnt(11)
	v_mfma_f32_16x16x32_bf16 v[60:63], v[152:155], v[204:207], v[60:63]
	v_mfma_f32_16x16x32_bf16 v[56:59], v[156:159], v[204:207], v[56:59]
	v_mfma_f32_16x16x32_bf16 v[52:55], v[160:163], v[204:207], v[52:55]
	v_mfma_f32_16x16x32_bf16 v[48:51], v[164:167], v[204:207], v[48:51]
	ds_read_b128 v[204:207], v226 offset:8192
	ds_read_b128 v[220:223], v226 offset:14336
	s_waitcnt lgkmcnt(11)
	v_mfma_f32_16x16x32_bf16 v[44:47], v[152:155], v[208:211], v[44:47]
	v_mfma_f32_16x16x32_bf16 v[40:43], v[156:159], v[208:211], v[40:43]
	v_mfma_f32_16x16x32_bf16 v[36:39], v[160:163], v[208:211], v[36:39]
	v_mfma_f32_16x16x32_bf16 v[32:35], v[164:167], v[208:211], v[32:35]
	ds_read_b128 v[208:211], v226 offset:10240
	s_waitcnt lgkmcnt(11)
	v_mfma_f32_16x16x32_bf16 v[28:31], v[152:155], v[212:215], v[28:31]
	v_mfma_f32_16x16x32_bf16 v[24:27], v[156:159], v[212:215], v[24:27]
	v_mfma_f32_16x16x32_bf16 v[20:23], v[160:163], v[212:215], v[20:23]
	v_mfma_f32_16x16x32_bf16 v[16:19], v[164:167], v[212:215], v[16:19]
	ds_read_b128 v[212:215], v226 offset:12288
	v_mfma_f32_16x16x32_bf16 v[12:15], v[152:155], v[216:219], v[12:15]
	v_mfma_f32_16x16x32_bf16 v[8:11], v[156:159], v[216:219], v[8:11]
	v_mfma_f32_16x16x32_bf16 v[4:7], v[160:163], v[216:219], v[4:7]
	v_mfma_f32_16x16x32_bf16 v[0:3], v[164:167], v[216:219], v[0:3]
	s_waitcnt vmcnt(0) lgkmcnt(0)
	s_barrier
	v_mfma_f32_16x16x32_bf16 v[124:127], v[168:171], v[188:191], v[124:127]
	v_mfma_f32_16x16x32_bf16 v[120:123], v[176:179], v[188:191], v[120:123]
	v_mfma_f32_16x16x32_bf16 v[116:119], v[180:183], v[188:191], v[116:119]
	v_mfma_f32_16x16x32_bf16 v[112:115], v[184:187], v[188:191], v[112:115]
	ds_read_b128 v[188:191], v225 offset:0
	ds_read_b128 v[152:155], v227 offset:0
	v_mfma_f32_16x16x32_bf16 v[108:111], v[168:171], v[192:195], v[108:111]
	v_mfma_f32_16x16x32_bf16 v[104:107], v[176:179], v[192:195], v[104:107]
	v_mfma_f32_16x16x32_bf16 v[100:103], v[180:183], v[192:195], v[100:103]
	v_mfma_f32_16x16x32_bf16 v[96:99], v[184:187], v[192:195], v[96:99]
	ds_read_b128 v[192:195], v225 offset:2048
	ds_read_b128 v[156:159], v227 offset:2048
	v_mfma_f32_16x16x32_bf16 v[92:95], v[168:171], v[196:199], v[92:95]
	v_mfma_f32_16x16x32_bf16 v[88:91], v[176:179], v[196:199], v[88:91]
	v_mfma_f32_16x16x32_bf16 v[84:87], v[180:183], v[196:199], v[84:87]
	v_mfma_f32_16x16x32_bf16 v[80:83], v[184:187], v[196:199], v[80:83]
	ds_read_b128 v[196:199], v225 offset:4096
	ds_read_b128 v[160:163], v227 offset:4096
	v_mfma_f32_16x16x32_bf16 v[76:79], v[168:171], v[200:203], v[76:79]
	v_mfma_f32_16x16x32_bf16 v[72:75], v[176:179], v[200:203], v[72:75]
	v_mfma_f32_16x16x32_bf16 v[68:71], v[180:183], v[200:203], v[68:71]
	v_mfma_f32_16x16x32_bf16 v[64:67], v[184:187], v[200:203], v[64:67]
	ds_read_b128 v[200:203], v225 offset:6144
	ds_read_b128 v[164:167], v227 offset:6144
	v_mfma_f32_16x16x32_bf16 v[60:63], v[168:171], v[204:207], v[60:63]
	v_mfma_f32_16x16x32_bf16 v[56:59], v[176:179], v[204:207], v[56:59]
	v_mfma_f32_16x16x32_bf16 v[52:55], v[180:183], v[204:207], v[52:55]
	v_mfma_f32_16x16x32_bf16 v[48:51], v[184:187], v[204:207], v[48:51]
	ds_read_b128 v[204:207], v225 offset:8192
	ds_read_b128 v[216:219], v225 offset:14336
	v_mfma_f32_16x16x32_bf16 v[44:47], v[168:171], v[208:211], v[44:47]
	v_mfma_f32_16x16x32_bf16 v[40:43], v[176:179], v[208:211], v[40:43]
	v_mfma_f32_16x16x32_bf16 v[36:39], v[180:183], v[208:211], v[36:39]
	v_mfma_f32_16x16x32_bf16 v[32:35], v[184:187], v[208:211], v[32:35]
	ds_read_b128 v[208:211], v225 offset:10240
	v_mfma_f32_16x16x32_bf16 v[28:31], v[168:171], v[212:215], v[28:31]
	v_mfma_f32_16x16x32_bf16 v[24:27], v[176:179], v[212:215], v[24:27]
	v_mfma_f32_16x16x32_bf16 v[20:23], v[180:183], v[212:215], v[20:23]
	v_mfma_f32_16x16x32_bf16 v[16:19], v[184:187], v[212:215], v[16:19]
	ds_read_b128 v[212:215], v225 offset:12288
	v_mfma_f32_16x16x32_bf16 v[12:15], v[168:171], v[220:223], v[12:15]
	v_mfma_f32_16x16x32_bf16 v[8:11], v[176:179], v[220:223], v[8:11]
	v_mfma_f32_16x16x32_bf16 v[4:7], v[180:183], v[220:223], v[4:7]
	v_mfma_f32_16x16x32_bf16 v[0:3], v[184:187], v[220:223], v[0:3]
	v_xor_b32_e32 v226, 0x8000, v226
	v_xor_b32_e32 v228, 0x8000, v228
	s_waitcnt lgkmcnt(4)
; #define G_LOAD(KT) do { _Pragma("unroll") for (int i = 0; i < 4; ++i) { ra[i] = *(const u32x4*)(Ag + (size_t)i * 64 * lda + (KT) * 64); rb[i] = *(const u32x4*)(Bg + (size_t)i * 64 * K + (KT) * 64); } } while (0)
; #define G_STORE(BUF) do { u16* ad = As + (BUF) * 256 * 64 + sto; u16* bd = Bs + (BUF) * 256 * 64 + sto; _Pragma("unroll") for (int i = 0; i < 4; ++i) { *(u32x4*)(ad + i * 64 * 64) = ra[i]; *(u32x4*)(bd + i * 64 * 64) = rb[i]; } } while (0)
; template <int EPI>
; DI void gemm_phase(const u16* __restrict__ A, int lda, const u16* __restrict__ Bt, int K, int N, u16* outb, int ldo,
;                    const float* r0, const float* r1, float* outf, char* lds, int bid, int nb) {
;     ...
;     G_LOAD(0);
;     G_STORE(0);
;     __syncthreads();
;     for (int kt = 0; kt < nk; ++kt) {
;       const int cur = kt & 1;
;       if (kt + 1 < nk) G_LOAD(kt + 1);
;       G_MMA(cur, fo0);
;       G_MMA(cur, fo1);
;       if (kt + 1 < nk) G_STORE(cur ^ 1);
;       __syncthreads();
;     }
;     ...
;     } else if constexpr (EPI == EPI_RESID) {
;       const int col = tn * 256 + wc * 64 + l15;
;       const float* rb_ = (tm * 256 < M_P) ? r0 : (r1 - (size_t)M_P * DM);
; #pragma unroll
;       for (int i = 0; i < 8; ++i)
; #pragma unroll
;         for (int r = 0; r < 4; ++r) {
;           const size_t i0 = (size_t)(mrow + i * 16 + r) * DM + col;
;           const float x0 = rb_[i0], x1 = rb_[i0 + 16], x2 = rb_[i0 + 32], x3 = rb_[i0 + 48];
	v_mfma_f32_16x16x32_bf16 v[124:127], v[152:155], v[188:191], v[124:127]
	v_mfma_f32_16x16x32_bf16 v[120:123], v[156:159], v[188:191], v[120:123]
	v_mfma_f32_16x16x32_bf16 v[116:119], v[160:163], v[188:191], v[116:119]
	v_mfma_f32_16x16x32_bf16 v[112:115], v[164:167], v[188:191], v[112:115]
	ds_read_b128 v[188:191], v226 offset:0
	ds_read_b128 v[168:171], v228 offset:0
	v_mfma_f32_16x16x32_bf16 v[108:111], v[152:155], v[192:195], v[108:111]
	v_mfma_f32_16x16x32_bf16 v[104:107], v[156:159], v[192:195], v[104:107]
	v_mfma_f32_16x16x32_bf16 v[100:103], v[160:163], v[192:195], v[100:103]
	v_mfma_f32_16x16x32_bf16 v[96:99], v[164:167], v[192:195], v[96:99]
	ds_read_b128 v[192:195], v226 offset:2048
	ds_read_b128 v[176:179], v228 offset:2048
	v_mfma_f32_16x16x32_bf16 v[92:95], v[152:155], v[196:199], v[92:95]
	v_mfma_f32_16x16x32_bf16 v[88:91], v[156:159], v[196:199], v[88:91]
	v_mfma_f32_16x16x32_bf16 v[84:87], v[160:163], v[196:199], v[84:87]
	v_mfma_f32_16x16x32_bf16 v[80:83], v[164:167], v[196:199], v[80:83]
	ds_read_b128 v[196:199], v226 offset:4096
	ds_read_b128 v[180:183], v228 offset:4096
	v_mfma_f32_16x16x32_bf16 v[76:79], v[152:155], v[200:203], v[76:79]
	v_mfma_f32_16x16x32_bf16 v[72:75], v[156:159], v[200:203], v[72:75]
	v_mfma_f32_16x16x32_bf16 v[68:71], v[160:163], v[200:203], v[68:71]
	v_mfma_f32_16x16x32_bf16 v[64:67], v[164:167], v[200:203], v[64:67]
	ds_read_b128 v[200:203], v226 offset:6144
	ds_read_b128 v[184:187], v228 offset:6144
	s_waitcnt lgkmcnt(11)
	v_mfma_f32_16x16x32_bf16 v[60:63], v[152:155], v[204:207], v[60:63]
	v_mfma_f32_16x16x32_bf16 v[56:59], v[156:159], v[204:207], v[56:59]
	v_mfma_f32_16x16x32_bf16 v[52:55], v[160:163], v[204:207], v[52:55]
	v_mfma_f32_16x16x32_bf16 v[48:51], v[164:167], v[204:207], v[48:51]
	ds_read_b128 v[204:207], v226 offset:8192
	ds_read_b128 v[220:223], v226 offset:14336
	s_waitcnt lgkmcnt(11)
	v_mfma_f32_16x16x32_bf16 v[44:47], v[152:155], v[208:211], v[44:47]
	v_mfma_f32_16x16x32_bf16 v[40:43], v[156:159], v[208:211], v[40:43]
	v_mfma_f32_16x16x32_bf16 v[36:39], v[160:163], v[208:211], v[36:39]
	v_mfma_f32_16x16x32_bf16 v[32:35], v[164:167], v[208:211], v[32:35]
	ds_read_b128 v[208:211], v226 offset:10240
	s_waitcnt lgkmcnt(11)
	v_mfma_f32_16x16x32_bf16 v[28:31], v[152:155], v[212:215], v[28:31]
	v_mfma_f32_16x16x32_bf16 v[24:27], v[156:159], v[212:215], v[24:27]
	v_mfma_f32_16x16x32_bf16 v[20:23], v[160:163], v[212:215], v[20:23]
	v_mfma_f32_16x16x32_bf16 v[16:19], v[164:167], v[212:215], v[16:19]
	ds_read_b128 v[212:215], v226 offset:12288
	v_mfma_f32_16x16x32_bf16 v[12:15], v[152:155], v[216:219], v[12:15]
	v_mfma_f32_16x16x32_bf16 v[8:11], v[156:159], v[216:219], v[8:11]
	v_mfma_f32_16x16x32_bf16 v[4:7], v[160:163], v[216:219], v[4:7]
	v_mfma_f32_16x16x32_bf16 v[0:3], v[164:167], v[216:219], v[0:3]
	s_waitcnt vmcnt(0) lgkmcnt(0)
	s_barrier
	v_mfma_f32_16x16x32_bf16 v[124:127], v[168:171], v[188:191], v[124:127]
	v_mfma_f32_16x16x32_bf16 v[120:123], v[176:179], v[188:191], v[120:123]
	v_mfma_f32_16x16x32_bf16 v[116:119], v[180:183], v[188:191], v[116:119]
	v_mfma_f32_16x16x32_bf16 v[112:115], v[184:187], v[188:191], v[112:115]
	v_mfma_f32_16x16x32_bf16 v[108:111], v[168:171], v[192:195], v[108:111]
	v_mfma_f32_16x16x32_bf16 v[104:107], v[176:179], v[192:195], v[104:107]
	v_mfma_f32_16x16x32_bf16 v[100:103], v[180:183], v[192:195], v[100:103]
	v_mfma_f32_16x16x32_bf16 v[96:99], v[184:187], v[192:195], v[96:99]
	v_mfma_f32_16x16x32_bf16 v[92:95], v[168:171], v[196:199], v[92:95]
	v_mfma_f32_16x16x32_bf16 v[88:91], v[176:179], v[196:199], v[88:91]
	v_mfma_f32_16x16x32_bf16 v[84:87], v[180:183], v[196:199], v[84:87]
	v_mfma_f32_16x16x32_bf16 v[80:83], v[184:187], v[196:199], v[80:83]
	v_mfma_f32_16x16x32_bf16 v[76:79], v[168:171], v[200:203], v[76:79]
	v_mfma_f32_16x16x32_bf16 v[72:75], v[176:179], v[200:203], v[72:75]
	v_mfma_f32_16x16x32_bf16 v[68:71], v[180:183], v[200:203], v[68:71]
	v_mfma_f32_16x16x32_bf16 v[64:67], v[184:187], v[200:203], v[64:67]
	v_mfma_f32_16x16x32_bf16 v[60:63], v[168:171], v[204:207], v[60:63]
	v_mfma_f32_16x16x32_bf16 v[56:59], v[176:179], v[204:207], v[56:59]
	v_mfma_f32_16x16x32_bf16 v[52:55], v[180:183], v[204:207], v[52:55]
	v_mfma_f32_16x16x32_bf16 v[48:51], v[184:187], v[204:207], v[48:51]
	v_mfma_f32_16x16x32_bf16 v[44:47], v[168:171], v[208:211], v[44:47]
	v_mfma_f32_16x16x32_bf16 v[40:43], v[176:179], v[208:211], v[40:43]
	v_mfma_f32_16x16x32_bf16 v[36:39], v[180:183], v[208:211], v[36:39]
	v_mfma_f32_16x16x32_bf16 v[32:35], v[184:187], v[208:211], v[32:35]
	v_mfma_f32_16x16x32_bf16 v[28:31], v[168:171], v[212:215], v[28:31]
	v_mfma_f32_16x16x32_bf16 v[24:27], v[176:179], v[212:215], v[24:27]
	v_mfma_f32_16x16x32_bf16 v[20:23], v[180:183], v[212:215], v[20:23]
	v_mfma_f32_16x16x32_bf16 v[16:19], v[184:187], v[212:215], v[16:19]
	v_mfma_f32_16x16x32_bf16 v[12:15], v[168:171], v[220:223], v[12:15]
	v_mfma_f32_16x16x32_bf16 v[8:11], v[176:179], v[220:223], v[8:11]
	v_mfma_f32_16x16x32_bf16 v[4:7], v[180:183], v[220:223], v[4:7]
	v_mfma_f32_16x16x32_bf16 v[0:3], v[184:187], v[220:223], v[0:3]
	s_nop 7
	s_nop 3
	v_and_b32_e32 v225, 15, v174
	v_lshrrev_b32_e32 v226, 8, v174
	v_lshl_or_b32 v225, v226, 7, v225
	v_bfe_u32 v226, v174, 6, 2
	v_bfe_u32 v227, v174, 4, 2
	v_lshlrev_b32_e32 v227, 2, v227
	v_add_u32_e32 v225, s39, v225
	v_lshl_add_u32 v226, v226, 6, v227
	v_add_u32_e32 v226, s46, v226
	v_lshlrev_b32_e32 v226, 2, v226
	v_lshl_add_u32 v224, v225, 12, v226
	v_mov_b32_e32 v229, v224
	v_add_u32_e32 v224, 0x0, v229
	global_load_dwordx4 v[152:155], v224, s[22:23] offset:0
	global_load_dwordx4 v[156:159], v224, s[22:23] offset:64
	global_load_dwordx4 v[160:163], v224, s[22:23] offset:128
	global_load_dwordx4 v[164:167], v224, s[22:23] offset:192
	v_add_u32_e32 v228, 0x10000, v229
	global_load_dwordx4 v[168:171], v228, s[22:23] offset:0
	global_load_dwordx4 v[176:179], v228, s[22:23] offset:64
	global_load_dwordx4 v[180:183], v228, s[22:23] offset:128
	global_load_dwordx4 v[184:187], v228, s[22:23] offset:192
	s_waitcnt vmcnt(4)
; template <int EPI>
; DI void gemm_phase(const u16* __restrict__ A, int lda, const u16* __restrict__ Bt, int K, int N, u16* outb, int ldo,
;                    const float* r0, const float* r1, float* outf, char* lds, int bid, int nb) {
;     ...
;     } else if constexpr (EPI == EPI_RESID) {
;       const int col = tn * 256 + wc * 64 + l15;
;       const float* rb_ = (tm * 256 < M_P) ? r0 : (r1 - (size_t)M_P * DM);
; #pragma unroll
;       for (int i = 0; i < 8; ++i)
; #pragma unroll
;         for (int r = 0; r < 4; ++r) {
;           const size_t i0 = (size_t)(mrow + i * 16 + r) * DM + col;
;           const float x0 = rb_[i0], x1 = rb_[i0 + 16], x2 = rb_[i0 + 32], x3 = rb_[i0 + 48];
;           outf[i0] = x0 + acc[i][0][r]; outf[i0 + 16] = x1 + acc[i][1][r]; outf[i0 + 32] = x2 + acc[i][2][r]; outf[i0 + 48] = x3 + acc[i][3][r];
;         }
	v_add_f32_e32 v152, v124, v152
	v_add_f32_e32 v153, v125, v153
	v_add_f32_e32 v154, v126, v154
	v_add_f32_e32 v155, v127, v155
	v_add_f32_e32 v156, v120, v156
	v_add_f32_e32 v157, v121, v157
	v_add_f32_e32 v158, v122, v158
	v_add_f32_e32 v159, v123, v159
	v_add_f32_e32 v160, v116, v160
	v_add_f32_e32 v161, v117, v161
	v_add_f32_e32 v162, v118, v162
	v_add_f32_e32 v163, v119, v163
	v_add_f32_e32 v164, v112, v164
	v_add_f32_e32 v165, v113, v165
	v_add_f32_e32 v166, v114, v166
	v_add_f32_e32 v167, v115, v167
	global_store_dwordx4 v224, v[152:155], s[22:23] offset:0
	global_store_dwordx4 v224, v[156:159], s[22:23] offset:64
	global_store_dwordx4 v224, v[160:163], s[22:23] offset:128
	global_store_dwordx4 v224, v[164:167], s[22:23] offset:192
	s_nop 1
	v_add_u32_e32 v224, 0x20000, v229
	global_load_dwordx4 v[152:155], v224, s[22:23] offset:0
	global_load_dwordx4 v[156:159], v224, s[22:23] offset:64
	global_load_dwordx4 v[160:163], v224, s[22:23] offset:128
	global_load_dwordx4 v[164:167], v224, s[22:23] offset:192
	s_waitcnt vmcnt(8)
	v_add_f32_e32 v168, v108, v168
	v_add_f32_e32 v169, v109, v169
	v_add_f32_e32 v170, v110, v170
	v_add_f32_e32 v171, v111, v171
	v_add_f32_e32 v176, v104, v176
	v_add_f32_e32 v177, v105, v177
	v_add_f32_e32 v178, v106, v178
	v_add_f32_e32 v179, v107, v179
	v_add_f32_e32 v180, v100, v180
	v_add_f32_e32 v181, v101, v181
	v_add_f32_e32 v182, v102, v182
	v_add_f32_e32 v183, v103, v183
	v_add_f32_e32 v184, v96, v184
	v_add_f32_e32 v185, v97, v185
	v_add_f32_e32 v186, v98, v186
	v_add_f32_e32 v187, v99, v187
	global_store_dwordx4 v228, v[168:171], s[22:23] offset:0
	global_store_dwordx4 v228, v[176:179], s[22:23] offset:64
	global_store_dwordx4 v228, v[180:183], s[22:23] offset:128
	global_store_dwordx4 v228, v[184:187], s[22:23] offset:192
	s_nop 1
	v_add_u32_e32 v228, 0x30000, v229
	global_load_dwordx4 v[168:171], v228, s[22:23] offset:0
	global_load_dwordx4 v[176:179], v228, s[22:23] offset:64
	global_load_dwordx4 v[180:183], v228, s[22:23] offset:128
	global_load_dwordx4 v[184:187], v228, s[22:23] offset:192
	s_waitcnt vmcnt(8)
	v_add_f32_e32 v152, v92, v152
	v_add_f32_e32 v153, v93, v153
	v_add_f32_e32 v154, v94, v154
	v_add_f32_e32 v155, v95, v155
	v_add_f32_e32 v156, v88, v156
	v_add_f32_e32 v157, v89, v157
	v_add_f32_e32 v158, v90, v158
	v_add_f32_e32 v159, v91, v159
	v_add_f32_e32 v160, v84, v160
	v_add_f32_e32 v161, v85, v161
	v_add_f32_e32 v162, v86, v162
	v_add_f32_e32 v163, v87, v163
	v_add_f32_e32 v164, v80, v164
	v_add_f32_e32 v165, v81, v165
	v_add_f32_e32 v166, v82, v166
	v_add_f32_e32 v167, v83, v167
	global_store_dwordx4 v224, v[152:155], s[22:23] offset:0
	global_store_dwordx4 v224, v[156:159], s[22:23] offset:64
	global_store_dwordx4 v224, v[160:163], s[22:23] offset:128
	global_store_dwordx4 v224, v[164:167], s[22:23] offset:192
	s_nop 1
	v_add_u32_e32 v224, 0x40000, v229
	global_load_dwordx4 v[152:155], v224, s[22:23] offset:0
	global_load_dwordx4 v[156:159], v224, s[22:23] offset:64
	global_load_dwordx4 v[160:163], v224, s[22:23] offset:128
	global_load_dwordx4 v[164:167], v224, s[22:23] offset:192
	s_waitcnt vmcnt(8)
	v_add_f32_e32 v168, v76, v168
	v_add_f32_e32 v169, v77, v169
	v_add_f32_e32 v170, v78, v170
	v_add_f32_e32 v171, v79, v171
	v_add_f32_e32 v176, v72, v176
	v_add_f32_e32 v177, v73, v177
	v_add_f32_e32 v178, v74, v178
	v_add_f32_e32 v179, v75, v179
	v_add_f32_e32 v180, v68, v180
	v_add_f32_e32 v181, v69, v181
	v_add_f32_e32 v182, v70, v182
	v_add_f32_e32 v183, v71, v183
	v_add_f32_e32 v184, v64, v184
	v_add_f32_e32 v185, v65, v185
	v_add_f32_e32 v186, v66, v186
	v_add_f32_e32 v187, v67, v187
	global_store_dwordx4 v228, v[168:171], s[22:23] offset:0
	global_store_dwordx4 v228, v[176:179], s[22:23] offset:64
	global_store_dwordx4 v228, v[180:183], s[22:23] offset:128
	global_store_dwordx4 v228, v[184:187], s[22:23] offset:192
	s_nop 1
	v_add_u32_e32 v228, 0x50000, v229
	global_load_dwordx4 v[168:171], v228, s[22:23] offset:0
	global_load_dwordx4 v[176:179], v228, s[22:23] offset:64
	global_load_dwordx4 v[180:183], v228, s[22:23] offset:128
	global_load_dwordx4 v[184:187], v228, s[22:23] offset:192
	s_waitcnt vmcnt(8)
; template <int EPI>
; DI void gemm_phase(const u16* __restrict__ A, int lda, const u16* __restrict__ Bt, int K, int N, u16* outb, int ldo,
;                    const float* r0, const float* r1, float* outf, char* lds, int bid, int nb) {
;     ...
;     } else if constexpr (EPI == EPI_RESID) {
;       const int col = tn * 256 + wc * 64 + l15;
;       const float* rb_ = (tm * 256 < M_P) ? r0 : (r1 - (size_t)M_P * DM);
; #pragma unroll
;       for (int i = 0; i < 8; ++i)
; #pragma unroll
;         for (int r = 0; r < 4; ++r) {
;           const size_t i0 = (size_t)(mrow + i * 16 + r) * DM + col;
;           const float x0 = rb_[i0], x1 = rb_[i0 + 16], x2 = rb_[i0 + 32], x3 = rb_[i0 + 48];
;           outf[i0] = x0 + acc[i][0][r]; outf[i0 + 16] = x1 + acc[i][1][r]; outf[i0 + 32] = x2 + acc[i][2][r]; outf[i0 + 48] = x3 + acc[i][3][r];
;         }
	v_add_f32_e32 v152, v60, v152
	v_add_f32_e32 v153, v61, v153
	v_add_f32_e32 v154, v62, v154
	v_add_f32_e32 v155, v63, v155
	v_add_f32_e32 v156, v56, v156
	v_add_f32_e32 v157, v57, v157
	v_add_f32_e32 v158, v58, v158
	v_add_f32_e32 v159, v59, v159
	v_add_f32_e32 v160, v52, v160
	v_add_f32_e32 v161, v53, v161
	v_add_f32_e32 v162, v54, v162
	v_add_f32_e32 v163, v55, v163
	v_add_f32_e32 v164, v48, v164
	v_add_f32_e32 v165, v49, v165
	v_add_f32_e32 v166, v50, v166
	v_add_f32_e32 v167, v51, v167
	global_store_dwordx4 v224, v[152:155], s[22:23] offset:0
	global_store_dwordx4 v224, v[156:159], s[22:23] offset:64
	global_store_dwordx4 v224, v[160:163], s[22:23] offset:128
	global_store_dwordx4 v224, v[164:167], s[22:23] offset:192
	s_nop 1
	v_add_u32_e32 v224, 0x60000, v229
	global_load_dwordx4 v[152:155], v224, s[22:23] offset:0
	global_load_dwordx4 v[156:159], v224, s[22:23] offset:64
	global_load_dwordx4 v[160:163], v224, s[22:23] offset:128
	global_load_dwordx4 v[164:167], v224, s[22:23] offset:192
	s_waitcnt vmcnt(8)
	v_add_f32_e32 v168, v44, v168
	v_add_f32_e32 v169, v45, v169
	v_add_f32_e32 v170, v46, v170
	v_add_f32_e32 v171, v47, v171
	v_add_f32_e32 v176, v40, v176
	v_add_f32_e32 v177, v41, v177
	v_add_f32_e32 v178, v42, v178
	v_add_f32_e32 v179, v43, v179
	v_add_f32_e32 v180, v36, v180
	v_add_f32_e32 v181, v37, v181
	v_add_f32_e32 v182, v38, v182
	v_add_f32_e32 v183, v39, v183
	v_add_f32_e32 v184, v32, v184
	v_add_f32_e32 v185, v33, v185
	v_add_f32_e32 v186, v34, v186
	v_add_f32_e32 v187, v35, v187
	global_store_dwordx4 v228, v[168:171], s[22:23] offset:0
	global_store_dwordx4 v228, v[176:179], s[22:23] offset:64
	global_store_dwordx4 v228, v[180:183], s[22:23] offset:128
	global_store_dwordx4 v228, v[184:187], s[22:23] offset:192
	s_nop 1
	v_add_u32_e32 v228, 0x70000, v229
	global_load_dwordx4 v[168:171], v228, s[22:23] offset:0
	global_load_dwordx4 v[176:179], v228, s[22:23] offset:64
	global_load_dwordx4 v[180:183], v228, s[22:23] offset:128
	global_load_dwordx4 v[184:187], v228, s[22:23] offset:192
	s_waitcnt vmcnt(8)
	v_add_f32_e32 v152, v28, v152
	v_add_f32_e32 v153, v29, v153
	v_add_f32_e32 v154, v30, v154
	v_add_f32_e32 v155, v31, v155
	v_add_f32_e32 v156, v24, v156
	v_add_f32_e32 v157, v25, v157
	v_add_f32_e32 v158, v26, v158
	v_add_f32_e32 v159, v27, v159
	v_add_f32_e32 v160, v20, v160
	v_add_f32_e32 v161, v21, v161
	v_add_f32_e32 v162, v22, v162
	v_add_f32_e32 v163, v23, v163
	v_add_f32_e32 v164, v16, v164
	v_add_f32_e32 v165, v17, v165
	v_add_f32_e32 v166, v18, v166
	v_add_f32_e32 v167, v19, v167
	global_store_dwordx4 v224, v[152:155], s[22:23] offset:0
	global_store_dwordx4 v224, v[156:159], s[22:23] offset:64
	global_store_dwordx4 v224, v[160:163], s[22:23] offset:128
	global_store_dwordx4 v224, v[164:167], s[22:23] offset:192
	s_waitcnt vmcnt(4)
	v_add_f32_e32 v168, v12, v168
	v_add_f32_e32 v169, v13, v169
	v_add_f32_e32 v170, v14, v170
	v_add_f32_e32 v171, v15, v171
	v_add_f32_e32 v176, v8, v176
	v_add_f32_e32 v177, v9, v177
	v_add_f32_e32 v178, v10, v178
	v_add_f32_e32 v179, v11, v179
	v_add_f32_e32 v180, v4, v180
	v_add_f32_e32 v181, v5, v181
	v_add_f32_e32 v182, v6, v182
	v_add_f32_e32 v183, v7, v183
	v_add_f32_e32 v184, v0, v184
	v_add_f32_e32 v185, v1, v185
	v_add_f32_e32 v186, v2, v186
	v_add_f32_e32 v187, v3, v187
	global_store_dwordx4 v228, v[168:171], s[22:23] offset:0
	global_store_dwordx4 v228, v[176:179], s[22:23] offset:64
	global_store_dwordx4 v228, v[180:183], s[22:23] offset:128
	global_store_dwordx4 v228, v[184:187], s[22:23] offset:192
	s_add_i32 s16, s16, 1
	s_cmp_eq_u32 s16, s3
	s_cbranch_scc0 .LBB0_759

; #define G_LOAD(KT) do { _Pragma("unroll") for (int i = 0; i < 4; ++i) { ra[i] = *(const u32x4*)(Ag + (size_t)i * 64 * lda + (KT) * 64); rb[i] = *(const u32x4*)(Bg + (size_t)i * 64 * K + (KT) * 64); } } while (0)
; #define G_STORE(BUF) do { u16* ad = As + (BUF) * 256 * 64 + sto; u16* bd = Bs + (BUF) * 256 * 64 + sto; _Pragma("unroll") for (int i = 0; i < 4; ++i) { *(u32x4*)(ad + i * 64 * 64) = ra[i]; *(u32x4*)(bd + i * 64 * 64) = rb[i]; } } while (0)
; template <int EPI>
; DI void gemm_phase(const u16* __restrict__ A, int lda, const u16* __restrict__ Bt, int K, int N, u16* outb, int ldo,
;                    const float* r0, const float* r1, float* outf, char* lds, int bid, int nb) {
;     ...
;     G_LOAD(0);
;     G_STORE(0);
;     __syncthreads();
;     for (int kt = 0; kt < nk; ++kt) {
;       const int cur = kt & 1;
;       if (kt + 1 < nk) G_LOAD(kt + 1);
;       G_MMA(cur, fo0);
;       G_MMA(cur, fo1);
;       if (kt + 1 < nk) G_STORE(cur ^ 1);
;       __syncthreads();
;     }
.Lgm4_loop:
	s_waitcnt lgkmcnt(4)
	v_mfma_f32_16x16x32_bf16 v[124:127], v[152:155], v[188:191], v[124:127]
	v_mfma_f32_16x16x32_bf16 v[120:123], v[156:159], v[188:191], v[120:123]
	v_mfma_f32_16x16x32_bf16 v[116:119], v[160:163], v[188:191], v[116:119]
	v_mfma_f32_16x16x32_bf16 v[112:115], v[164:167], v[188:191], v[112:115]
	ds_read_b128 v[188:191], v226 offset:0
	ds_read_b128 v[168:171], v228 offset:0
	v_mfma_f32_16x16x32_bf16 v[108:111], v[152:155], v[192:195], v[108:111]
	v_mfma_f32_16x16x32_bf16 v[104:107], v[156:159], v[192:195], v[104:107]
	v_mfma_f32_16x16x32_bf16 v[100:103], v[160:163], v[192:195], v[100:103]
	v_mfma_f32_16x16x32_bf16 v[96:99], v[164:167], v[192:195], v[96:99]
	ds_read_b128 v[192:195], v226 offset:2048
	ds_read_b128 v[176:179], v228 offset:2048
	v_mfma_f32_16x16x32_bf16 v[92:95], v[152:155], v[196:199], v[92:95]
	v_mfma_f32_16x16x32_bf16 v[88:91], v[156:159], v[196:199], v[88:91]
	v_mfma_f32_16x16x32_bf16 v[84:87], v[160:163], v[196:199], v[84:87]
	v_mfma_f32_16x16x32_bf16 v[80:83], v[164:167], v[196:199], v[80:83]
	ds_read_b128 v[196:199], v226 offset:4096
	ds_read_b128 v[180:183], v228 offset:4096
	v_mfma_f32_16x16x32_bf16 v[76:79], v[152:155], v[200:203], v[76:79]
	v_mfma_f32_16x16x32_bf16 v[72:75], v[156:159], v[200:203], v[72:75]
	v_mfma_f32_16x16x32_bf16 v[68:71], v[160:163], v[200:203], v[68:71]
	v_mfma_f32_16x16x32_bf16 v[64:67], v[164:167], v[200:203], v[64:67]
	ds_read_b128 v[200:203], v226 offset:6144
	ds_read_b128 v[184:187], v228 offset:6144
	s_waitcnt lgkmcnt(11)
	v_mfma_f32_16x16x32_bf16 v[60:63], v[152:155], v[204:207], v[60:63]
	v_mfma_f32_16x16x32_bf16 v[56:59], v[156:159], v[204:207], v[56:59]
	v_mfma_f32_16x16x32_bf16 v[52:55], v[160:163], v[204:207], v[52:55]
	v_mfma_f32_16x16x32_bf16 v[48:51], v[164:167], v[204:207], v[48:51]
	ds_read_b128 v[204:207], v226 offset:8192
	ds_read_b128 v[220:223], v226 offset:14336
	s_waitcnt lgkmcnt(11)
	v_mfma_f32_16x16x32_bf16 v[44:47], v[152:155], v[208:211], v[44:47]
	v_mfma_f32_16x16x32_bf16 v[40:43], v[156:159], v[208:211], v[40:43]
	v_mfma_f32_16x16x32_bf16 v[36:39], v[160:163], v[208:211], v[36:39]
	v_mfma_f32_16x16x32_bf16 v[32:35], v[164:167], v[208:211], v[32:35]
	ds_read_b128 v[208:211], v226 offset:10240
	s_waitcnt lgkmcnt(11)
	v_mfma_f32_16x16x32_bf16 v[28:31], v[152:155], v[212:215], v[28:31]
	v_mfma_f32_16x16x32_bf16 v[24:27], v[156:159], v[212:215], v[24:27]
	v_mfma_f32_16x16x32_bf16 v[20:23], v[160:163], v[212:215], v[20:23]
	v_mfma_f32_16x16x32_bf16 v[16:19], v[164:167], v[212:215], v[16:19]
	ds_read_b128 v[212:215], v226 offset:12288
	v_mfma_f32_16x16x32_bf16 v[12:15], v[152:155], v[216:219], v[12:15]
	v_mfma_f32_16x16x32_bf16 v[8:11], v[156:159], v[216:219], v[8:11]
	v_mfma_f32_16x16x32_bf16 v[4:7], v[160:163], v[216:219], v[4:7]
	v_mfma_f32_16x16x32_bf16 v[0:3], v[164:167], v[216:219], v[0:3]
	s_waitcnt vmcnt(0) lgkmcnt(0)
	s_barrier
	v_mfma_f32_16x16x32_bf16 v[124:127], v[168:171], v[188:191], v[124:127]
	v_mfma_f32_16x16x32_bf16 v[120:123], v[176:179], v[188:191], v[120:123]
	v_mfma_f32_16x16x32_bf16 v[116:119], v[180:183], v[188:191], v[116:119]
	v_mfma_f32_16x16x32_bf16 v[112:115], v[184:187], v[188:191], v[112:115]
	ds_read_b128 v[188:191], v225 offset:0
	ds_read_b128 v[152:155], v227 offset:0
	s_add_u32 s14, s98, 0x0
	s_addc_u32 s15, s99, 0
	s_add_u32 m0, s97, 0x0
	s_nop 0
	global_load_lds_dwordx4 v224, s[14:15]
	v_mfma_f32_16x16x32_bf16 v[108:111], v[168:171], v[192:195], v[108:111]
	v_mfma_f32_16x16x32_bf16 v[104:107], v[176:179], v[192:195], v[104:107]
	v_mfma_f32_16x16x32_bf16 v[100:103], v[180:183], v[192:195], v[100:103]
	v_mfma_f32_16x16x32_bf16 v[96:99], v[184:187], v[192:195], v[96:99]
	ds_read_b128 v[192:195], v225 offset:2048
	ds_read_b128 v[156:159], v227 offset:2048
	s_add_u32 s14, s100, 0x0
	s_addc_u32 s15, s101, 0
	s_add_u32 m0, s97, 0x10000
	s_nop 0
	global_load_lds_dwordx4 v224, s[14:15]
	v_mfma_f32_16x16x32_bf16 v[92:95], v[168:171], v[196:199], v[92:95]
	v_mfma_f32_16x16x32_bf16 v[88:91], v[176:179], v[196:199], v[88:91]
	v_mfma_f32_16x16x32_bf16 v[84:87], v[180:183], v[196:199], v[84:87]
	v_mfma_f32_16x16x32_bf16 v[80:83], v[184:187], v[196:199], v[80:83]
	ds_read_b128 v[196:199], v225 offset:4096
	ds_read_b128 v[160:163], v227 offset:4096
	s_add_u32 s14, s98, 0x20000
	s_addc_u32 s15, s99, 0
	s_add_u32 m0, s97, 0x2000
	s_nop 0
	global_load_lds_dwordx4 v224, s[14:15]
	v_mfma_f32_16x16x32_bf16 v[76:79], v[168:171], v[200:203], v[76:79]
	v_mfma_f32_16x16x32_bf16 v[72:75], v[176:179], v[200:203], v[72:75]
	v_mfma_f32_16x16x32_bf16 v[68:71], v[180:183], v[200:203], v[68:71]
	v_mfma_f32_16x16x32_bf16 v[64:67], v[184:187], v[200:203], v[64:67]
	ds_read_b128 v[200:203], v225 offset:6144
	ds_read_b128 v[164:167], v227 offset:6144
	s_add_u32 s14, s100, 0x20000
	s_addc_u32 s15, s101, 0
	s_add_u32 m0, s97, 0x12000
	s_nop 0
	global_load_lds_dwordx4 v224, s[14:15]
	v_mfma_f32_16x16x32_bf16 v[60:63], v[168:171], v[204:207], v[60:63]
	v_mfma_f32_16x16x32_bf16 v[56:59], v[176:179], v[204:207], v[56:59]
	v_mfma_f32_16x16x32_bf16 v[52:55], v[180:183], v[204:207], v[52:55]
	v_mfma_f32_16x16x32_bf16 v[48:51], v[184:187], v[204:207], v[48:51]
	ds_read_b128 v[204:207], v225 offset:8192
	ds_read_b128 v[216:219], v225 offset:14336
	s_add_u32 s14, s98, 0x40000
	s_addc_u32 s15, s99, 0
	s_add_u32 m0, s97, 0x4000
	s_nop 0
	global_load_lds_dwordx4 v224, s[14:15]
	v_mfma_f32_16x16x32_bf16 v[44:47], v[168:171], v[208:211], v[44:47]
	v_mfma_f32_16x16x32_bf16 v[40:43], v[176:179], v[208:211], v[40:43]
	v_mfma_f32_16x16x32_bf16 v[36:39], v[180:183], v[208:211], v[36:39]
	v_mfma_f32_16x16x32_bf16 v[32:35], v[184:187], v[208:211], v[32:35]
	ds_read_b128 v[208:211], v225 offset:10240
	s_add_u32 s14, s100, 0x40000
	s_addc_u32 s15, s101, 0
	s_add_u32 m0, s97, 0x14000
	s_nop 0
	global_load_lds_dwordx4 v224, s[14:15]
	v_mfma_f32_16x16x32_bf16 v[28:31], v[168:171], v[212:215], v[28:31]
	v_mfma_f32_16x16x32_bf16 v[24:27], v[176:179], v[212:215], v[24:27]
	v_mfma_f32_16x16x32_bf16 v[20:23], v[180:183], v[212:215], v[20:23]
	v_mfma_f32_16x16x32_bf16 v[16:19], v[184:187], v[212:215], v[16:19]
	ds_read_b128 v[212:215], v225 offset:12288
	s_add_u32 s14, s98, 0x60000
	s_addc_u32 s15, s99, 0
	s_add_u32 m0, s97, 0x6000
	s_nop 0
	global_load_lds_dwordx4 v224, s[14:15]
	v_mfma_f32_16x16x32_bf16 v[12:15], v[168:171], v[220:223], v[12:15]
	v_mfma_f32_16x16x32_bf16 v[8:11], v[176:179], v[220:223], v[8:11]
	v_mfma_f32_16x16x32_bf16 v[4:7], v[180:183], v[220:223], v[4:7]
	v_mfma_f32_16x16x32_bf16 v[0:3], v[184:187], v[220:223], v[0:3]
	s_add_u32 s14, s100, 0x60000
	s_addc_u32 s15, s101, 0
	s_add_u32 m0, s97, 0x16000
	s_nop 0
	global_load_lds_dwordx4 v224, s[14:15]
	v_xor_b32_e32 v225, 0x8000, v225
	v_xor_b32_e32 v227, 0x8000, v227
	v_xor_b32_e32 v226, 0x8000, v226
	v_xor_b32_e32 v228, 0x8000, v228
	s_xor_b32 s97, s97, 0x8000
	s_add_u32 s98, s98, 0x80
	s_addc_u32 s99, s99, 0
	s_add_u32 s100, s100, 0x80
	s_addc_u32 s101, s101, 0
	s_sub_u32 s28, s28, 1
	s_cmp_lg_u32 s28, 0
	s_cbranch_scc1 .Lgm4_loop
; #define G_LOAD(KT) do { _Pragma("unroll") for (int i = 0; i < 4; ++i) { ra[i] = *(const u32x4*)(Ag + (size_t)i * 64 * lda + (KT) * 64); rb[i] = *(const u32x4*)(Bg + (size_t)i * 64 * K + (KT) * 64); } } while (0)
; #define G_STORE(BUF) do { u16* ad = As + (BUF) * 256 * 64 + sto; u16* bd = Bs + (BUF) * 256 * 64 + sto; _Pragma("unroll") for (int i = 0; i < 4; ++i) { *(u32x4*)(ad + i * 64 * 64) = ra[i]; *(u32x4*)(bd + i * 64 * 64) = rb[i]; } } while (0)
; template <int EPI>
; DI void gemm_phase(const u16* __restrict__ A, int lda, const u16* __restrict__ Bt, int K, int N, u16* outb, int ldo,
;                    const float* r0, const float* r1, float* outf, char* lds, int bid, int nb) {
;     ...
;     G_LOAD(0);
;     G_STORE(0);
;     __syncthreads();
;     for (int kt = 0; kt < nk; ++kt) {
;       const int cur = kt & 1;
;       if (kt + 1 < nk) G_LOAD(kt + 1);
;       G_MMA(cur, fo0);
;       G_MMA(cur, fo1);
;       if (kt + 1 < nk) G_STORE(cur ^ 1);
;       __syncthreads();
	s_waitcnt lgkmcnt(4)
	v_mfma_f32_16x16x32_bf16 v[124:127], v[152:155], v[188:191], v[124:127]
	v_mfma_f32_16x16x32_bf16 v[120:123], v[156:159], v[188:191], v[120:123]
	v_mfma_f32_16x16x32_bf16 v[116:119], v[160:163], v[188:191], v[116:119]
	v_mfma_f32_16x16x32_bf16 v[112:115], v[164:167], v[188:191], v[112:115]
	ds_read_b128 v[188:191], v226 offset:0
	ds_read_b128 v[168:171], v228 offset:0
	v_mfma_f32_16x16x32_bf16 v[108:111], v[152:155], v[192:195], v[108:111]
	v_mfma_f32_16x16x32_bf16 v[104:107], v[156:159], v[192:195], v[104:107]
	v_mfma_f32_16x16x32_bf16 v[100:103], v[160:163], v[192:195], v[100:103]
	v_mfma_f32_16x16x32_bf16 v[96:99], v[164:167], v[192:195], v[96:99]
	ds_read_b128 v[192:195], v226 offset:2048
	ds_read_b128 v[176:179], v228 offset:2048
	v_mfma_f32_16x16x32_bf16 v[92:95], v[152:155], v[196:199], v[92:95]
	v_mfma_f32_16x16x32_bf16 v[88:91], v[156:159], v[196:199], v[88:91]
	v_mfma_f32_16x16x32_bf16 v[84:87], v[160:163], v[196:199], v[84:87]
	v_mfma_f32_16x16x32_bf16 v[80:83], v[164:167], v[196:199], v[80:83]
	ds_read_b128 v[196:199], v226 offset:4096
	ds_read_b128 v[180:183], v228 offset:4096
	v_mfma_f32_16x16x32_bf16 v[76:79], v[152:155], v[200:203], v[76:79]
	v_mfma_f32_16x16x32_bf16 v[72:75], v[156:159], v[200:203], v[72:75]
	v_mfma_f32_16x16x32_bf16 v[68:71], v[160:163], v[200:203], v[68:71]
	v_mfma_f32_16x16x32_bf16 v[64:67], v[164:167], v[200:203], v[64:67]
	ds_read_b128 v[200:203], v226 offset:6144
	ds_read_b128 v[184:187], v228 offset:6144
	s_waitcnt lgkmcnt(11)
	v_mfma_f32_16x16x32_bf16 v[60:63], v[152:155], v[204:207], v[60:63]
	v_mfma_f32_16x16x32_bf16 v[56:59], v[156:159], v[204:207], v[56:59]
	v_mfma_f32_16x16x32_bf16 v[52:55], v[160:163], v[204:207], v[52:55]
	v_mfma_f32_16x16x32_bf16 v[48:51], v[164:167], v[204:207], v[48:51]
	ds_read_b128 v[204:207], v226 offset:8192
	ds_read_b128 v[220:223], v226 offset:14336
	s_waitcnt lgkmcnt(11)
	v_mfma_f32_16x16x32_bf16 v[44:47], v[152:155], v[208:211], v[44:47]
	v_mfma_f32_16x16x32_bf16 v[40:43], v[156:159], v[208:211], v[40:43]
	v_mfma_f32_16x16x32_bf16 v[36:39], v[160:163], v[208:211], v[36:39]
	v_mfma_f32_16x16x32_bf16 v[32:35], v[164:167], v[208:211], v[32:35]
	ds_read_b128 v[208:211], v226 offset:10240
	s_waitcnt lgkmcnt(11)
	v_mfma_f32_16x16x32_bf16 v[28:31], v[152:155], v[212:215], v[28:31]
	v_mfma_f32_16x16x32_bf16 v[24:27], v[156:159], v[212:215], v[24:27]
	v_mfma_f32_16x16x32_bf16 v[20:23], v[160:163], v[212:215], v[20:23]
	v_mfma_f32_16x16x32_bf16 v[16:19], v[164:167], v[212:215], v[16:19]
	ds_read_b128 v[212:215], v226 offset:12288
	v_mfma_f32_16x16x32_bf16 v[12:15], v[152:155], v[216:219], v[12:15]
	v_mfma_f32_16x16x32_bf16 v[8:11], v[156:159], v[216:219], v[8:11]
	v_mfma_f32_16x16x32_bf16 v[4:7], v[160:163], v[216:219], v[4:7]
	v_mfma_f32_16x16x32_bf16 v[0:3], v[164:167], v[216:219], v[0:3]
	s_waitcnt vmcnt(0) lgkmcnt(0)
	s_barrier
	v_mfma_f32_16x16x32_bf16 v[124:127], v[168:171], v[188:191], v[124:127]
	v_mfma_f32_16x16x32_bf16 v[120:123], v[176:179], v[188:191], v[120:123]
	v_mfma_f32_16x16x32_bf16 v[116:119], v[180:183], v[188:191], v[116:119]
	v_mfma_f32_16x16x32_bf16 v[112:115], v[184:187], v[188:191], v[112:115]
	ds_read_b128 v[188:191], v225 offset:0
	ds_read_b128 v[152:155], v227 offset:0
	v_mfma_f32_16x16x32_bf16 v[108:111], v[168:171], v[192:195], v[108:111]
	v_mfma_f32_16x16x32_bf16 v[104:107], v[176:179], v[192:195], v[104:107]
	v_mfma_f32_16x16x32_bf16 v[100:103], v[180:183], v[192:195], v[100:103]
	v_mfma_f32_16x16x32_bf16 v[96:99], v[184:187], v[192:195], v[96:99]
	ds_read_b128 v[192:195], v225 offset:2048
	ds_read_b128 v[156:159], v227 offset:2048
	v_mfma_f32_16x16x32_bf16 v[92:95], v[168:171], v[196:199], v[92:95]
	v_mfma_f32_16x16x32_bf16 v[88:91], v[176:179], v[196:199], v[88:91]
	v_mfma_f32_16x16x32_bf16 v[84:87], v[180:183], v[196:199], v[84:87]
	v_mfma_f32_16x16x32_bf16 v[80:83], v[184:187], v[196:199], v[80:83]
	ds_read_b128 v[196:199], v225 offset:4096
	ds_read_b128 v[160:163], v227 offset:4096
	v_mfma_f32_16x16x32_bf16 v[76:79], v[168:171], v[200:203], v[76:79]
	v_mfma_f32_16x16x32_bf16 v[72:75], v[176:179], v[200:203], v[72:75]
	v_mfma_f32_16x16x32_bf16 v[68:71], v[180:183], v[200:203], v[68:71]
	v_mfma_f32_16x16x32_bf16 v[64:67], v[184:187], v[200:203], v[64:67]
	ds_read_b128 v[200:203], v225 offset:6144
	ds_read_b128 v[164:167], v227 offset:6144
	v_mfma_f32_16x16x32_bf16 v[60:63], v[168:171], v[204:207], v[60:63]
	v_mfma_f32_16x16x32_bf16 v[56:59], v[176:179], v[204:207], v[56:59]
	v_mfma_f32_16x16x32_bf16 v[52:55], v[180:183], v[204:207], v[52:55]
	v_mfma_f32_16x16x32_bf16 v[48:51], v[184:187], v[204:207], v[48:51]
	ds_read_b128 v[204:207], v225 offset:8192
	ds_read_b128 v[216:219], v225 offset:14336
	v_mfma_f32_16x16x32_bf16 v[44:47], v[168:171], v[208:211], v[44:47]
	v_mfma_f32_16x16x32_bf16 v[40:43], v[176:179], v[208:211], v[40:43]
	v_mfma_f32_16x16x32_bf16 v[36:39], v[180:183], v[208:211], v[36:39]
	v_mfma_f32_16x16x32_bf16 v[32:35], v[184:187], v[208:211], v[32:35]
	ds_read_b128 v[208:211], v225 offset:10240
	v_mfma_f32_16x16x32_bf16 v[28:31], v[168:171], v[212:215], v[28:31]
	v_mfma_f32_16x16x32_bf16 v[24:27], v[176:179], v[212:215], v[24:27]
	v_mfma_f32_16x16x32_bf16 v[20:23], v[180:183], v[212:215], v[20:23]
	v_mfma_f32_16x16x32_bf16 v[16:19], v[184:187], v[212:215], v[16:19]
	ds_read_b128 v[212:215], v225 offset:12288
	v_mfma_f32_16x16x32_bf16 v[12:15], v[168:171], v[220:223], v[12:15]
	v_mfma_f32_16x16x32_bf16 v[8:11], v[176:179], v[220:223], v[8:11]
	v_mfma_f32_16x16x32_bf16 v[4:7], v[180:183], v[220:223], v[4:7]
	v_mfma_f32_16x16x32_bf16 v[0:3], v[184:187], v[220:223], v[0:3]
	v_xor_b32_e32 v226, 0x8000, v226
	v_xor_b32_e32 v228, 0x8000, v228
	s_waitcnt lgkmcnt(4)
; #define G_LOAD(KT) do { _Pragma("unroll") for (int i = 0; i < 4; ++i) { ra[i] = *(const u32x4*)(Ag + (size_t)i * 64 * lda + (KT) * 64); rb[i] = *(const u32x4*)(Bg + (size_t)i * 64 * K + (KT) * 64); } } while (0)
; #define G_STORE(BUF) do { u16* ad = As + (BUF) * 256 * 64 + sto; u16* bd = Bs + (BUF) * 256 * 64 + sto; _Pragma("unroll") for (int i = 0; i < 4; ++i) { *(u32x4*)(ad + i * 64 * 64) = ra[i]; *(u32x4*)(bd + i * 64 * 64) = rb[i]; } } while (0)
; template <int EPI>
; DI void gemm_phase(const u16* __restrict__ A, int lda, const u16* __restrict__ Bt, int K, int N, u16* outb, int ldo,
;                    const float* r0, const float* r1, float* outf, char* lds, int bid, int nb) {
;     ...
;     G_LOAD(0);
;     G_STORE(0);
;     __syncthreads();
;     for (int kt = 0; kt < nk; ++kt) {
;       const int cur = kt & 1;
;       if (kt + 1 < nk) G_LOAD(kt + 1);
;       G_MMA(cur, fo0);
;       G_MMA(cur, fo1);
;       if (kt + 1 < nk) G_STORE(cur ^ 1);
;       __syncthreads();
	v_mfma_f32_16x16x32_bf16 v[124:127], v[152:155], v[188:191], v[124:127]
	v_mfma_f32_16x16x32_bf16 v[120:123], v[156:159], v[188:191], v[120:123]
	v_mfma_f32_16x16x32_bf16 v[116:119], v[160:163], v[188:191], v[116:119]
	v_mfma_f32_16x16x32_bf16 v[112:115], v[164:167], v[188:191], v[112:115]
	ds_read_b128 v[188:191], v226 offset:0
	ds_read_b128 v[168:171], v228 offset:0
	v_mfma_f32_16x16x32_bf16 v[108:111], v[152:155], v[192:195], v[108:111]
	v_mfma_f32_16x16x32_bf16 v[104:107], v[156:159], v[192:195], v[104:107]
	v_mfma_f32_16x16x32_bf16 v[100:103], v[160:163], v[192:195], v[100:103]
	v_mfma_f32_16x16x32_bf16 v[96:99], v[164:167], v[192:195], v[96:99]
	ds_read_b128 v[192:195], v226 offset:2048
	ds_read_b128 v[176:179], v228 offset:2048
	v_mfma_f32_16x16x32_bf16 v[92:95], v[152:155], v[196:199], v[92:95]
	v_mfma_f32_16x16x32_bf16 v[88:91], v[156:159], v[196:199], v[88:91]
	v_mfma_f32_16x16x32_bf16 v[84:87], v[160:163], v[196:199], v[84:87]
	v_mfma_f32_16x16x32_bf16 v[80:83], v[164:167], v[196:199], v[80:83]
	ds_read_b128 v[196:199], v226 offset:4096
	ds_read_b128 v[180:183], v228 offset:4096
	v_mfma_f32_16x16x32_bf16 v[76:79], v[152:155], v[200:203], v[76:79]
	v_mfma_f32_16x16x32_bf16 v[72:75], v[156:159], v[200:203], v[72:75]
	v_mfma_f32_16x16x32_bf16 v[68:71], v[160:163], v[200:203], v[68:71]
	v_mfma_f32_16x16x32_bf16 v[64:67], v[164:167], v[200:203], v[64:67]
	ds_read_b128 v[200:203], v226 offset:6144
	ds_read_b128 v[184:187], v228 offset:6144
	s_waitcnt lgkmcnt(11)
	v_mfma_f32_16x16x32_bf16 v[60:63], v[152:155], v[204:207], v[60:63]
	v_mfma_f32_16x16x32_bf16 v[56:59], v[156:159], v[204:207], v[56:59]
	v_mfma_f32_16x16x32_bf16 v[52:55], v[160:163], v[204:207], v[52:55]
	v_mfma_f32_16x16x32_bf16 v[48:51], v[164:167], v[204:207], v[48:51]
	ds_read_b128 v[204:207], v226 offset:8192
	ds_read_b128 v[220:223], v226 offset:14336
	s_waitcnt lgkmcnt(11)
	v_mfma_f32_16x16x32_bf16 v[44:47], v[152:155], v[208:211], v[44:47]
	v_mfma_f32_16x16x32_bf16 v[40:43], v[156:159], v[208:211], v[40:43]
	v_mfma_f32_16x16x32_bf16 v[36:39], v[160:163], v[208:211], v[36:39]
	v_mfma_f32_16x16x32_bf16 v[32:35], v[164:167], v[208:211], v[32:35]
	ds_read_b128 v[208:211], v226 offset:10240
	s_waitcnt lgkmcnt(11)
	v_mfma_f32_16x16x32_bf16 v[28:31], v[152:155], v[212:215], v[28:31]
	v_mfma_f32_16x16x32_bf16 v[24:27], v[156:159], v[212:215], v[24:27]
	v_mfma_f32_16x16x32_bf16 v[20:23], v[160:163], v[212:215], v[20:23]
	v_mfma_f32_16x16x32_bf16 v[16:19], v[164:167], v[212:215], v[16:19]
	ds_read_b128 v[212:215], v226 offset:12288
	v_mfma_f32_16x16x32_bf16 v[12:15], v[152:155], v[216:219], v[12:15]
	v_mfma_f32_16x16x32_bf16 v[8:11], v[156:159], v[216:219], v[8:11]
	v_mfma_f32_16x16x32_bf16 v[4:7], v[160:163], v[216:219], v[4:7]
	v_mfma_f32_16x16x32_bf16 v[0:3], v[164:167], v[216:219], v[0:3]
	s_waitcnt vmcnt(0) lgkmcnt(0)
	s_barrier
; DI u16 f2bf(float a) { return (u16)(pk2(a, 0.f) & 0xffffu); }
; template <int EPI>
; DI void gemm_phase(const u16* __restrict__ A, int lda, const u16* __restrict__ Bt, int K, int N, u16* outb, int ldo,
;                    const float* r0, const float* r1, float* outf, char* lds, int bid, int nb) {
;     ...
;     if constexpr (EPI == EPI_BF16) {
;       const int col = tn * 256 + wc * 64 + l15;
; #pragma unroll
;       for (int i = 0; i < 8; ++i)
; #pragma unroll
;         for (int r = 0; r < 4; ++r) {
;           u16* o0 = outb + (size_t)(mrow + i * 16 + r) * ldo + col;
;           o0[0] = f2bf(acc[i][0][r]); o0[16] = f2bf(acc[i][1][r]); o0[32] = f2bf(acc[i][2][r]); o0[48] = f2bf(acc[i][3][r]);
;         }
	v_mfma_f32_16x16x32_bf16 v[124:127], v[168:171], v[188:191], v[124:127]
	v_mfma_f32_16x16x32_bf16 v[120:123], v[176:179], v[188:191], v[120:123]
	v_mfma_f32_16x16x32_bf16 v[116:119], v[180:183], v[188:191], v[116:119]
	v_mfma_f32_16x16x32_bf16 v[112:115], v[184:187], v[188:191], v[112:115]
	v_mfma_f32_16x16x32_bf16 v[108:111], v[168:171], v[192:195], v[108:111]
	v_mfma_f32_16x16x32_bf16 v[104:107], v[176:179], v[192:195], v[104:107]
	v_mfma_f32_16x16x32_bf16 v[100:103], v[180:183], v[192:195], v[100:103]
	v_mfma_f32_16x16x32_bf16 v[96:99], v[184:187], v[192:195], v[96:99]
	v_mfma_f32_16x16x32_bf16 v[92:95], v[168:171], v[196:199], v[92:95]
	v_mfma_f32_16x16x32_bf16 v[88:91], v[176:179], v[196:199], v[88:91]
	v_mfma_f32_16x16x32_bf16 v[84:87], v[180:183], v[196:199], v[84:87]
	v_mfma_f32_16x16x32_bf16 v[80:83], v[184:187], v[196:199], v[80:83]
	v_mfma_f32_16x16x32_bf16 v[76:79], v[168:171], v[200:203], v[76:79]
	v_mfma_f32_16x16x32_bf16 v[72:75], v[176:179], v[200:203], v[72:75]
	v_mfma_f32_16x16x32_bf16 v[68:71], v[180:183], v[200:203], v[68:71]
	v_mfma_f32_16x16x32_bf16 v[64:67], v[184:187], v[200:203], v[64:67]
	v_mfma_f32_16x16x32_bf16 v[60:63], v[168:171], v[204:207], v[60:63]
	v_mfma_f32_16x16x32_bf16 v[56:59], v[176:179], v[204:207], v[56:59]
	v_mfma_f32_16x16x32_bf16 v[52:55], v[180:183], v[204:207], v[52:55]
	v_mfma_f32_16x16x32_bf16 v[48:51], v[184:187], v[204:207], v[48:51]
	v_mfma_f32_16x16x32_bf16 v[44:47], v[168:171], v[208:211], v[44:47]
	v_mfma_f32_16x16x32_bf16 v[40:43], v[176:179], v[208:211], v[40:43]
	v_mfma_f32_16x16x32_bf16 v[36:39], v[180:183], v[208:211], v[36:39]
	v_mfma_f32_16x16x32_bf16 v[32:35], v[184:187], v[208:211], v[32:35]
	v_mfma_f32_16x16x32_bf16 v[28:31], v[168:171], v[212:215], v[28:31]
	v_mfma_f32_16x16x32_bf16 v[24:27], v[176:179], v[212:215], v[24:27]
	v_mfma_f32_16x16x32_bf16 v[20:23], v[180:183], v[212:215], v[20:23]
	v_mfma_f32_16x16x32_bf16 v[16:19], v[184:187], v[212:215], v[16:19]
	v_mfma_f32_16x16x32_bf16 v[12:15], v[168:171], v[220:223], v[12:15]
	v_mfma_f32_16x16x32_bf16 v[8:11], v[176:179], v[220:223], v[8:11]
	v_mfma_f32_16x16x32_bf16 v[4:7], v[180:183], v[220:223], v[4:7]
	v_mfma_f32_16x16x32_bf16 v[0:3], v[184:187], v[220:223], v[0:3]
	s_nop 7
	s_nop 3
	v_and_b32_e32 v225, 15, v174
	v_lshrrev_b32_e32 v226, 8, v174
	v_lshl_or_b32 v225, v226, 7, v225
	v_bfe_u32 v226, v174, 6, 2
	v_bfe_u32 v227, v174, 4, 2
	v_lshlrev_b32_e32 v227, 2, v227
	v_add_u32_e32 v225, s48, v225
	v_lshl_add_u32 v226, v226, 6, v227
	v_add_u32_e32 v226, s49, v226
	v_lshlrev_b32_e32 v226, 1, v226
	v_mov_b32_e32 v227, 0x600
	v_mad_u32_u24 v224, v225, v227, v226
	v_cvt_pk_bf16_f32 v188, v124, v125
	v_cvt_pk_bf16_f32 v189, v126, v127
	global_store_dwordx2 v224, v[188:189], s[8:9] offset:0
	v_cvt_pk_bf16_f32 v190, v120, v121
	v_cvt_pk_bf16_f32 v191, v122, v123
	global_store_dwordx2 v224, v[190:191], s[8:9] offset:32
	v_cvt_pk_bf16_f32 v192, v116, v117
	v_cvt_pk_bf16_f32 v193, v118, v119
	global_store_dwordx2 v224, v[192:193], s[8:9] offset:64
	v_cvt_pk_bf16_f32 v194, v112, v113
	v_cvt_pk_bf16_f32 v195, v114, v115
	global_store_dwordx2 v224, v[194:195], s[8:9] offset:96
	v_add_u32_e32 v224, 0x6000, v224
	v_cvt_pk_bf16_f32 v196, v108, v109
	v_cvt_pk_bf16_f32 v197, v110, v111
	global_store_dwordx2 v224, v[196:197], s[8:9] offset:0
	v_cvt_pk_bf16_f32 v198, v104, v105
	v_cvt_pk_bf16_f32 v199, v106, v107
	global_store_dwordx2 v224, v[198:199], s[8:9] offset:32
	v_cvt_pk_bf16_f32 v200, v100, v101
	v_cvt_pk_bf16_f32 v201, v102, v103
	global_store_dwordx2 v224, v[200:201], s[8:9] offset:64
	v_cvt_pk_bf16_f32 v202, v96, v97
	v_cvt_pk_bf16_f32 v203, v98, v99
	global_store_dwordx2 v224, v[202:203], s[8:9] offset:96
	v_add_u32_e32 v224, 0x6000, v224
	v_cvt_pk_bf16_f32 v204, v92, v93
	v_cvt_pk_bf16_f32 v205, v94, v95
	global_store_dwordx2 v224, v[204:205], s[8:9] offset:0
	v_cvt_pk_bf16_f32 v206, v88, v89
	v_cvt_pk_bf16_f32 v207, v90, v91
	global_store_dwordx2 v224, v[206:207], s[8:9] offset:32
	v_cvt_pk_bf16_f32 v208, v84, v85
	v_cvt_pk_bf16_f32 v209, v86, v87
	global_store_dwordx2 v224, v[208:209], s[8:9] offset:64
	v_cvt_pk_bf16_f32 v210, v80, v81
	v_cvt_pk_bf16_f32 v211, v82, v83
	global_store_dwordx2 v224, v[210:211], s[8:9] offset:96
	v_add_u32_e32 v224, 0x6000, v224
	v_cvt_pk_bf16_f32 v212, v76, v77
	v_cvt_pk_bf16_f32 v213, v78, v79
	global_store_dwordx2 v224, v[212:213], s[8:9] offset:0
	v_cvt_pk_bf16_f32 v214, v72, v73
	v_cvt_pk_bf16_f32 v215, v74, v75
	global_store_dwordx2 v224, v[214:215], s[8:9] offset:32
	v_cvt_pk_bf16_f32 v216, v68, v69
	v_cvt_pk_bf16_f32 v217, v70, v71
	global_store_dwordx2 v224, v[216:217], s[8:9] offset:64
	v_cvt_pk_bf16_f32 v218, v64, v65
	v_cvt_pk_bf16_f32 v219, v66, v67
	global_store_dwordx2 v224, v[218:219], s[8:9] offset:96
	v_add_u32_e32 v224, 0x6000, v224
	v_cvt_pk_bf16_f32 v188, v60, v61
	v_cvt_pk_bf16_f32 v189, v62, v63
	global_store_dwordx2 v224, v[188:189], s[8:9] offset:0
	v_cvt_pk_bf16_f32 v190, v56, v57
	v_cvt_pk_bf16_f32 v191, v58, v59
	global_store_dwordx2 v224, v[190:191], s[8:9] offset:32
	v_cvt_pk_bf16_f32 v192, v52, v53
	v_cvt_pk_bf16_f32 v193, v54, v55
	global_store_dwordx2 v224, v[192:193], s[8:9] offset:64
	v_cvt_pk_bf16_f32 v194, v48, v49
	v_cvt_pk_bf16_f32 v195, v50, v51
	global_store_dwordx2 v224, v[194:195], s[8:9] offset:96
	v_add_u32_e32 v224, 0x6000, v224
	v_cvt_pk_bf16_f32 v196, v44, v45
	v_cvt_pk_bf16_f32 v197, v46, v47
	global_store_dwordx2 v224, v[196:197], s[8:9] offset:0
	v_cvt_pk_bf16_f32 v198, v40, v41
	v_cvt_pk_bf16_f32 v199, v42, v43
	global_store_dwordx2 v224, v[198:199], s[8:9] offset:32
	v_cvt_pk_bf16_f32 v200, v36, v37
	v_cvt_pk_bf16_f32 v201, v38, v39
	global_store_dwordx2 v224, v[200:201], s[8:9] offset:64
	v_cvt_pk_bf16_f32 v202, v32, v33
	v_cvt_pk_bf16_f32 v203, v34, v35
	global_store_dwordx2 v224, v[202:203], s[8:9] offset:96
	v_add_u32_e32 v224, 0x6000, v224
	v_cvt_pk_bf16_f32 v204, v28, v29
	v_cvt_pk_bf16_f32 v205, v30, v31
	global_store_dwordx2 v224, v[204:205], s[8:9] offset:0
	v_cvt_pk_bf16_f32 v206, v24, v25
	v_cvt_pk_bf16_f32 v207, v26, v27
	global_store_dwordx2 v224, v[206:207], s[8:9] offset:32
	v_cvt_pk_bf16_f32 v208, v20, v21
	v_cvt_pk_bf16_f32 v209, v22, v23
	global_store_dwordx2 v224, v[208:209], s[8:9] offset:64
	v_cvt_pk_bf16_f32 v210, v16, v17
	v_cvt_pk_bf16_f32 v211, v18, v19
	global_store_dwordx2 v224, v[210:211], s[8:9] offset:96
	v_add_u32_e32 v224, 0x6000, v224
	v_cvt_pk_bf16_f32 v212, v12, v13
	v_cvt_pk_bf16_f32 v213, v14, v15
	global_store_dwordx2 v224, v[212:213], s[8:9] offset:0
	v_cvt_pk_bf16_f32 v214, v8, v9
	v_cvt_pk_bf16_f32 v215, v10, v11
	global_store_dwordx2 v224, v[214:215], s[8:9] offset:32
	v_cvt_pk_bf16_f32 v216, v4, v5
	v_cvt_pk_bf16_f32 v217, v6, v7
	global_store_dwordx2 v224, v[216:217], s[8:9] offset:64
	v_cvt_pk_bf16_f32 v218, v0, v1
	v_cvt_pk_bf16_f32 v219, v2, v3
	global_store_dwordx2 v224, v[218:219], s[8:9] offset:96
	s_add_i32 s18, s18, 1
	s_cmp_eq_u32 s18, s3
	s_cbranch_scc0 .LBB0_879

; #define G_LOAD(KT) do { _Pragma("unroll") for (int i = 0; i < 4; ++i) { ra[i] = *(const u32x4*)(Ag + (size_t)i * 64 * lda + (KT) * 64); rb[i] = *(const u32x4*)(Bg + (size_t)i * 64 * K + (KT) * 64); } } while (0)
; #define G_STORE(BUF) do { u16* ad = As + (BUF) * 256 * 64 + sto; u16* bd = Bs + (BUF) * 256 * 64 + sto; _Pragma("unroll") for (int i = 0; i < 4; ++i) { *(u32x4*)(ad + i * 64 * 64) = ra[i]; *(u32x4*)(bd + i * 64 * 64) = rb[i]; } } while (0)
; template <int EPI>
; DI void gemm_phase(const u16* __restrict__ A, int lda, const u16* __restrict__ Bt, int K, int N, u16* outb, int ldo,
;                    const float* r0, const float* r1, float* outf, char* lds, int bid, int nb) {
;     ...
;     G_LOAD(0);
;     G_STORE(0);
;     __syncthreads();
;     for (int kt = 0; kt < nk; ++kt) {
;       const int cur = kt & 1;
;       if (kt + 1 < nk) G_LOAD(kt + 1);
;       G_MMA(cur, fo0);
;       G_MMA(cur, fo1);
;       if (kt + 1 < nk) G_STORE(cur ^ 1);
;       __syncthreads();
;     }
.Lgm5_loop:
	s_waitcnt lgkmcnt(4)
	v_mfma_f32_16x16x32_bf16 v[124:127], v[152:155], v[188:191], v[124:127]
	v_mfma_f32_16x16x32_bf16 v[120:123], v[156:159], v[188:191], v[120:123]
	v_mfma_f32_16x16x32_bf16 v[116:119], v[160:163], v[188:191], v[116:119]
	v_mfma_f32_16x16x32_bf16 v[112:115], v[164:167], v[188:191], v[112:115]
	ds_read_b128 v[188:191], v226 offset:0
	ds_read_b128 v[168:171], v228 offset:0
	v_mfma_f32_16x16x32_bf16 v[108:111], v[152:155], v[192:195], v[108:111]
	v_mfma_f32_16x16x32_bf16 v[104:107], v[156:159], v[192:195], v[104:107]
	v_mfma_f32_16x16x32_bf16 v[100:103], v[160:163], v[192:195], v[100:103]
	v_mfma_f32_16x16x32_bf16 v[96:99], v[164:167], v[192:195], v[96:99]
	ds_read_b128 v[192:195], v226 offset:2048
	ds_read_b128 v[176:179], v228 offset:2048
	v_mfma_f32_16x16x32_bf16 v[92:95], v[152:155], v[196:199], v[92:95]
	v_mfma_f32_16x16x32_bf16 v[88:91], v[156:159], v[196:199], v[88:91]
	v_mfma_f32_16x16x32_bf16 v[84:87], v[160:163], v[196:199], v[84:87]
	v_mfma_f32_16x16x32_bf16 v[80:83], v[164:167], v[196:199], v[80:83]
	ds_read_b128 v[196:199], v226 offset:4096
	ds_read_b128 v[180:183], v228 offset:4096
	v_mfma_f32_16x16x32_bf16 v[76:79], v[152:155], v[200:203], v[76:79]
	v_mfma_f32_16x16x32_bf16 v[72:75], v[156:159], v[200:203], v[72:75]
	v_mfma_f32_16x16x32_bf16 v[68:71], v[160:163], v[200:203], v[68:71]
	v_mfma_f32_16x16x32_bf16 v[64:67], v[164:167], v[200:203], v[64:67]
	ds_read_b128 v[200:203], v226 offset:6144
	ds_read_b128 v[184:187], v228 offset:6144
	s_waitcnt lgkmcnt(11)
	v_mfma_f32_16x16x32_bf16 v[60:63], v[152:155], v[204:207], v[60:63]
	v_mfma_f32_16x16x32_bf16 v[56:59], v[156:159], v[204:207], v[56:59]
	v_mfma_f32_16x16x32_bf16 v[52:55], v[160:163], v[204:207], v[52:55]
	v_mfma_f32_16x16x32_bf16 v[48:51], v[164:167], v[204:207], v[48:51]
	ds_read_b128 v[204:207], v226 offset:8192
	ds_read_b128 v[220:223], v226 offset:14336
	s_waitcnt lgkmcnt(11)
	v_mfma_f32_16x16x32_bf16 v[44:47], v[152:155], v[208:211], v[44:47]
	v_mfma_f32_16x16x32_bf16 v[40:43], v[156:159], v[208:211], v[40:43]
	v_mfma_f32_16x16x32_bf16 v[36:39], v[160:163], v[208:211], v[36:39]
	v_mfma_f32_16x16x32_bf16 v[32:35], v[164:167], v[208:211], v[32:35]
	ds_read_b128 v[208:211], v226 offset:10240
	s_waitcnt lgkmcnt(11)
	v_mfma_f32_16x16x32_bf16 v[28:31], v[152:155], v[212:215], v[28:31]
	v_mfma_f32_16x16x32_bf16 v[24:27], v[156:159], v[212:215], v[24:27]
	v_mfma_f32_16x16x32_bf16 v[20:23], v[160:163], v[212:215], v[20:23]
	v_mfma_f32_16x16x32_bf16 v[16:19], v[164:167], v[212:215], v[16:19]
	ds_read_b128 v[212:215], v226 offset:12288
	v_mfma_f32_16x16x32_bf16 v[12:15], v[152:155], v[216:219], v[12:15]
	v_mfma_f32_16x16x32_bf16 v[8:11], v[156:159], v[216:219], v[8:11]
	v_mfma_f32_16x16x32_bf16 v[4:7], v[160:163], v[216:219], v[4:7]
	v_mfma_f32_16x16x32_bf16 v[0:3], v[164:167], v[216:219], v[0:3]
	s_waitcnt vmcnt(0) lgkmcnt(0)
	s_barrier
	v_mfma_f32_16x16x32_bf16 v[124:127], v[168:171], v[188:191], v[124:127]
	v_mfma_f32_16x16x32_bf16 v[120:123], v[176:179], v[188:191], v[120:123]
	v_mfma_f32_16x16x32_bf16 v[116:119], v[180:183], v[188:191], v[116:119]
	v_mfma_f32_16x16x32_bf16 v[112:115], v[184:187], v[188:191], v[112:115]
	ds_read_b128 v[188:191], v225 offset:0
	ds_read_b128 v[152:155], v227 offset:0
	s_add_u32 s8, s98, 0x0
	s_addc_u32 s9, s99, 0
	s_add_u32 m0, s97, 0x0
	s_nop 0
	global_load_lds_dwordx4 v224, s[8:9]
	v_mfma_f32_16x16x32_bf16 v[108:111], v[168:171], v[192:195], v[108:111]
	v_mfma_f32_16x16x32_bf16 v[104:107], v[176:179], v[192:195], v[104:107]
	v_mfma_f32_16x16x32_bf16 v[100:103], v[180:183], v[192:195], v[100:103]
	v_mfma_f32_16x16x32_bf16 v[96:99], v[184:187], v[192:195], v[96:99]
	ds_read_b128 v[192:195], v225 offset:2048
	ds_read_b128 v[156:159], v227 offset:2048
	s_add_u32 s8, s100, 0x0
	s_addc_u32 s9, s101, 0
	s_add_u32 m0, s97, 0x10000
	s_nop 0
	global_load_lds_dwordx4 v224, s[8:9]
	v_mfma_f32_16x16x32_bf16 v[92:95], v[168:171], v[196:199], v[92:95]
	v_mfma_f32_16x16x32_bf16 v[88:91], v[176:179], v[196:199], v[88:91]
	v_mfma_f32_16x16x32_bf16 v[84:87], v[180:183], v[196:199], v[84:87]
	v_mfma_f32_16x16x32_bf16 v[80:83], v[184:187], v[196:199], v[80:83]
	ds_read_b128 v[196:199], v225 offset:4096
	ds_read_b128 v[160:163], v227 offset:4096
	s_add_u32 s8, s98, 0x20000
	s_addc_u32 s9, s99, 0
	s_add_u32 m0, s97, 0x2000
	s_nop 0
	global_load_lds_dwordx4 v224, s[8:9]
	v_mfma_f32_16x16x32_bf16 v[76:79], v[168:171], v[200:203], v[76:79]
	v_mfma_f32_16x16x32_bf16 v[72:75], v[176:179], v[200:203], v[72:75]
	v_mfma_f32_16x16x32_bf16 v[68:71], v[180:183], v[200:203], v[68:71]
	v_mfma_f32_16x16x32_bf16 v[64:67], v[184:187], v[200:203], v[64:67]
	ds_read_b128 v[200:203], v225 offset:6144
	ds_read_b128 v[164:167], v227 offset:6144
	s_add_u32 s8, s100, 0x20000
	s_addc_u32 s9, s101, 0
	s_add_u32 m0, s97, 0x12000
	s_nop 0
	global_load_lds_dwordx4 v224, s[8:9]
	v_mfma_f32_16x16x32_bf16 v[60:63], v[168:171], v[204:207], v[60:63]
	v_mfma_f32_16x16x32_bf16 v[56:59], v[176:179], v[204:207], v[56:59]
	v_mfma_f32_16x16x32_bf16 v[52:55], v[180:183], v[204:207], v[52:55]
	v_mfma_f32_16x16x32_bf16 v[48:51], v[184:187], v[204:207], v[48:51]
	ds_read_b128 v[204:207], v225 offset:8192
	ds_read_b128 v[216:219], v225 offset:14336
	s_add_u32 s8, s98, 0x40000
	s_addc_u32 s9, s99, 0
	s_add_u32 m0, s97, 0x4000
	s_nop 0
	global_load_lds_dwordx4 v224, s[8:9]
	v_mfma_f32_16x16x32_bf16 v[44:47], v[168:171], v[208:211], v[44:47]
	v_mfma_f32_16x16x32_bf16 v[40:43], v[176:179], v[208:211], v[40:43]
	v_mfma_f32_16x16x32_bf16 v[36:39], v[180:183], v[208:211], v[36:39]
	v_mfma_f32_16x16x32_bf16 v[32:35], v[184:187], v[208:211], v[32:35]
	ds_read_b128 v[208:211], v225 offset:10240
	s_add_u32 s8, s100, 0x40000
	s_addc_u32 s9, s101, 0
	s_add_u32 m0, s97, 0x14000
	s_nop 0
	global_load_lds_dwordx4 v224, s[8:9]
	v_mfma_f32_16x16x32_bf16 v[28:31], v[168:171], v[212:215], v[28:31]
	v_mfma_f32_16x16x32_bf16 v[24:27], v[176:179], v[212:215], v[24:27]
	v_mfma_f32_16x16x32_bf16 v[20:23], v[180:183], v[212:215], v[20:23]
	v_mfma_f32_16x16x32_bf16 v[16:19], v[184:187], v[212:215], v[16:19]
	ds_read_b128 v[212:215], v225 offset:12288
	s_add_u32 s8, s98, 0x60000
	s_addc_u32 s9, s99, 0
	s_add_u32 m0, s97, 0x6000
	s_nop 0
	global_load_lds_dwordx4 v224, s[8:9]
	v_mfma_f32_16x16x32_bf16 v[12:15], v[168:171], v[220:223], v[12:15]
	v_mfma_f32_16x16x32_bf16 v[8:11], v[176:179], v[220:223], v[8:11]
	v_mfma_f32_16x16x32_bf16 v[4:7], v[180:183], v[220:223], v[4:7]
	v_mfma_f32_16x16x32_bf16 v[0:3], v[184:187], v[220:223], v[0:3]
	s_add_u32 s8, s100, 0x60000
	s_addc_u32 s9, s101, 0
	s_add_u32 m0, s97, 0x16000
	s_nop 0
	global_load_lds_dwordx4 v224, s[8:9]
	v_xor_b32_e32 v225, 0x8000, v225
	v_xor_b32_e32 v227, 0x8000, v227
	v_xor_b32_e32 v226, 0x8000, v226
	v_xor_b32_e32 v228, 0x8000, v228
	s_xor_b32 s97, s97, 0x8000
	s_add_u32 s98, s98, 0x80
	s_addc_u32 s99, s99, 0
	s_add_u32 s100, s100, 0x80
	s_addc_u32 s101, s101, 0
	s_sub_u32 s28, s28, 1
	s_cmp_lg_u32 s28, 0
	s_cbranch_scc1 .Lgm5_loop
; #define G_LOAD(KT) do { _Pragma("unroll") for (int i = 0; i < 4; ++i) { ra[i] = *(const u32x4*)(Ag + (size_t)i * 64 * lda + (KT) * 64); rb[i] = *(const u32x4*)(Bg + (size_t)i * 64 * K + (KT) * 64); } } while (0)
; #define G_STORE(BUF) do { u16* ad = As + (BUF) * 256 * 64 + sto; u16* bd = Bs + (BUF) * 256 * 64 + sto; _Pragma("unroll") for (int i = 0; i < 4; ++i) { *(u32x4*)(ad + i * 64 * 64) = ra[i]; *(u32x4*)(bd + i * 64 * 64) = rb[i]; } } while (0)
; template <int EPI>
; DI void gemm_phase(const u16* __restrict__ A, int lda, const u16* __restrict__ Bt, int K, int N, u16* outb, int ldo,
;                    const float* r0, const float* r1, float* outf, char* lds, int bid, int nb) {
;     ...
;     G_LOAD(0);
;     G_STORE(0);
;     __syncthreads();
;     for (int kt = 0; kt < nk; ++kt) {
;       const int cur = kt & 1;
;       if (kt + 1 < nk) G_LOAD(kt + 1);
;       G_MMA(cur, fo0);
;       G_MMA(cur, fo1);
;       if (kt + 1 < nk) G_STORE(cur ^ 1);
;       __syncthreads();
	s_waitcnt lgkmcnt(4)
	v_mfma_f32_16x16x32_bf16 v[124:127], v[152:155], v[188:191], v[124:127]
	v_mfma_f32_16x16x32_bf16 v[120:123], v[156:159], v[188:191], v[120:123]
	v_mfma_f32_16x16x32_bf16 v[116:119], v[160:163], v[188:191], v[116:119]
	v_mfma_f32_16x16x32_bf16 v[112:115], v[164:167], v[188:191], v[112:115]
	ds_read_b128 v[188:191], v226 offset:0
	ds_read_b128 v[168:171], v228 offset:0
	v_mfma_f32_16x16x32_bf16 v[108:111], v[152:155], v[192:195], v[108:111]
	v_mfma_f32_16x16x32_bf16 v[104:107], v[156:159], v[192:195], v[104:107]
	v_mfma_f32_16x16x32_bf16 v[100:103], v[160:163], v[192:195], v[100:103]
	v_mfma_f32_16x16x32_bf16 v[96:99], v[164:167], v[192:195], v[96:99]
	ds_read_b128 v[192:195], v226 offset:2048
	ds_read_b128 v[176:179], v228 offset:2048
	v_mfma_f32_16x16x32_bf16 v[92:95], v[152:155], v[196:199], v[92:95]
	v_mfma_f32_16x16x32_bf16 v[88:91], v[156:159], v[196:199], v[88:91]
	v_mfma_f32_16x16x32_bf16 v[84:87], v[160:163], v[196:199], v[84:87]
	v_mfma_f32_16x16x32_bf16 v[80:83], v[164:167], v[196:199], v[80:83]
	ds_read_b128 v[196:199], v226 offset:4096
	ds_read_b128 v[180:183], v228 offset:4096
	v_mfma_f32_16x16x32_bf16 v[76:79], v[152:155], v[200:203], v[76:79]
	v_mfma_f32_16x16x32_bf16 v[72:75], v[156:159], v[200:203], v[72:75]
	v_mfma_f32_16x16x32_bf16 v[68:71], v[160:163], v[200:203], v[68:71]
	v_mfma_f32_16x16x32_bf16 v[64:67], v[164:167], v[200:203], v[64:67]
	ds_read_b128 v[200:203], v226 offset:6144
	ds_read_b128 v[184:187], v228 offset:6144
	s_waitcnt lgkmcnt(11)
	v_mfma_f32_16x16x32_bf16 v[60:63], v[152:155], v[204:207], v[60:63]
	v_mfma_f32_16x16x32_bf16 v[56:59], v[156:159], v[204:207], v[56:59]
	v_mfma_f32_16x16x32_bf16 v[52:55], v[160:163], v[204:207], v[52:55]
	v_mfma_f32_16x16x32_bf16 v[48:51], v[164:167], v[204:207], v[48:51]
	ds_read_b128 v[204:207], v226 offset:8192
	ds_read_b128 v[220:223], v226 offset:14336
	s_waitcnt lgkmcnt(11)
	v_mfma_f32_16x16x32_bf16 v[44:47], v[152:155], v[208:211], v[44:47]
	v_mfma_f32_16x16x32_bf16 v[40:43], v[156:159], v[208:211], v[40:43]
	v_mfma_f32_16x16x32_bf16 v[36:39], v[160:163], v[208:211], v[36:39]
	v_mfma_f32_16x16x32_bf16 v[32:35], v[164:167], v[208:211], v[32:35]
	ds_read_b128 v[208:211], v226 offset:10240
	s_waitcnt lgkmcnt(11)
	v_mfma_f32_16x16x32_bf16 v[28:31], v[152:155], v[212:215], v[28:31]
	v_mfma_f32_16x16x32_bf16 v[24:27], v[156:159], v[212:215], v[24:27]
	v_mfma_f32_16x16x32_bf16 v[20:23], v[160:163], v[212:215], v[20:23]
	v_mfma_f32_16x16x32_bf16 v[16:19], v[164:167], v[212:215], v[16:19]
	ds_read_b128 v[212:215], v226 offset:12288
	v_mfma_f32_16x16x32_bf16 v[12:15], v[152:155], v[216:219], v[12:15]
	v_mfma_f32_16x16x32_bf16 v[8:11], v[156:159], v[216:219], v[8:11]
	v_mfma_f32_16x16x32_bf16 v[4:7], v[160:163], v[216:219], v[4:7]
	v_mfma_f32_16x16x32_bf16 v[0:3], v[164:167], v[216:219], v[0:3]
	s_waitcnt vmcnt(0) lgkmcnt(0)
	s_barrier
	v_mfma_f32_16x16x32_bf16 v[124:127], v[168:171], v[188:191], v[124:127]
	v_mfma_f32_16x16x32_bf16 v[120:123], v[176:179], v[188:191], v[120:123]
	v_mfma_f32_16x16x32_bf16 v[116:119], v[180:183], v[188:191], v[116:119]
	v_mfma_f32_16x16x32_bf16 v[112:115], v[184:187], v[188:191], v[112:115]
	ds_read_b128 v[188:191], v225 offset:0
	ds_read_b128 v[152:155], v227 offset:0
	v_mfma_f32_16x16x32_bf16 v[108:111], v[168:171], v[192:195], v[108:111]
	v_mfma_f32_16x16x32_bf16 v[104:107], v[176:179], v[192:195], v[104:107]
	v_mfma_f32_16x16x32_bf16 v[100:103], v[180:183], v[192:195], v[100:103]
	v_mfma_f32_16x16x32_bf16 v[96:99], v[184:187], v[192:195], v[96:99]
	ds_read_b128 v[192:195], v225 offset:2048
	ds_read_b128 v[156:159], v227 offset:2048
	v_mfma_f32_16x16x32_bf16 v[92:95], v[168:171], v[196:199], v[92:95]
	v_mfma_f32_16x16x32_bf16 v[88:91], v[176:179], v[196:199], v[88:91]
	v_mfma_f32_16x16x32_bf16 v[84:87], v[180:183], v[196:199], v[84:87]
	v_mfma_f32_16x16x32_bf16 v[80:83], v[184:187], v[196:199], v[80:83]
	ds_read_b128 v[196:199], v225 offset:4096
	ds_read_b128 v[160:163], v227 offset:4096
	v_mfma_f32_16x16x32_bf16 v[76:79], v[168:171], v[200:203], v[76:79]
	v_mfma_f32_16x16x32_bf16 v[72:75], v[176:179], v[200:203], v[72:75]
	v_mfma_f32_16x16x32_bf16 v[68:71], v[180:183], v[200:203], v[68:71]
	v_mfma_f32_16x16x32_bf16 v[64:67], v[184:187], v[200:203], v[64:67]
	ds_read_b128 v[200:203], v225 offset:6144
	ds_read_b128 v[164:167], v227 offset:6144
	v_mfma_f32_16x16x32_bf16 v[60:63], v[168:171], v[204:207], v[60:63]
	v_mfma_f32_16x16x32_bf16 v[56:59], v[176:179], v[204:207], v[56:59]
	v_mfma_f32_16x16x32_bf16 v[52:55], v[180:183], v[204:207], v[52:55]
	v_mfma_f32_16x16x32_bf16 v[48:51], v[184:187], v[204:207], v[48:51]
	ds_read_b128 v[204:207], v225 offset:8192
	ds_read_b128 v[216:219], v225 offset:14336
	v_mfma_f32_16x16x32_bf16 v[44:47], v[168:171], v[208:211], v[44:47]
	v_mfma_f32_16x16x32_bf16 v[40:43], v[176:179], v[208:211], v[40:43]
	v_mfma_f32_16x16x32_bf16 v[36:39], v[180:183], v[208:211], v[36:39]
	v_mfma_f32_16x16x32_bf16 v[32:35], v[184:187], v[208:211], v[32:35]
	ds_read_b128 v[208:211], v225 offset:10240
	v_mfma_f32_16x16x32_bf16 v[28:31], v[168:171], v[212:215], v[28:31]
	v_mfma_f32_16x16x32_bf16 v[24:27], v[176:179], v[212:215], v[24:27]
	v_mfma_f32_16x16x32_bf16 v[20:23], v[180:183], v[212:215], v[20:23]
	v_mfma_f32_16x16x32_bf16 v[16:19], v[184:187], v[212:215], v[16:19]
	ds_read_b128 v[212:215], v225 offset:12288
	v_mfma_f32_16x16x32_bf16 v[12:15], v[168:171], v[220:223], v[12:15]
	v_mfma_f32_16x16x32_bf16 v[8:11], v[176:179], v[220:223], v[8:11]
	v_mfma_f32_16x16x32_bf16 v[4:7], v[180:183], v[220:223], v[4:7]
	v_mfma_f32_16x16x32_bf16 v[0:3], v[184:187], v[220:223], v[0:3]
	v_xor_b32_e32 v226, 0x8000, v226
	v_xor_b32_e32 v228, 0x8000, v228
	s_waitcnt lgkmcnt(4)
; #define G_LOAD(KT) do { _Pragma("unroll") for (int i = 0; i < 4; ++i) { ra[i] = *(const u32x4*)(Ag + (size_t)i * 64 * lda + (KT) * 64); rb[i] = *(const u32x4*)(Bg + (size_t)i * 64 * K + (KT) * 64); } } while (0)
; #define G_STORE(BUF) do { u16* ad = As + (BUF) * 256 * 64 + sto; u16* bd = Bs + (BUF) * 256 * 64 + sto; _Pragma("unroll") for (int i = 0; i < 4; ++i) { *(u32x4*)(ad + i * 64 * 64) = ra[i]; *(u32x4*)(bd + i * 64 * 64) = rb[i]; } } while (0)
; template <int EPI>
; DI void gemm_phase(const u16* __restrict__ A, int lda, const u16* __restrict__ Bt, int K, int N, u16* outb, int ldo,
;                    const float* r0, const float* r1, float* outf, char* lds, int bid, int nb) {
;     ...
;     G_LOAD(0);
;     G_STORE(0);
;     __syncthreads();
;     for (int kt = 0; kt < nk; ++kt) {
;       const int cur = kt & 1;
;       if (kt + 1 < nk) G_LOAD(kt + 1);
;       G_MMA(cur, fo0);
;       G_MMA(cur, fo1);
;       if (kt + 1 < nk) G_STORE(cur ^ 1);
;       __syncthreads();
;     }
;     ...
;     } else if constexpr (EPI == EPI_RESID) {
;       const int col = tn * 256 + wc * 64 + l15;
;       const float* rb_ = (tm * 256 < M_P) ? r0 : (r1 - (size_t)M_P * DM);
; #pragma unroll
;       for (int i = 0; i < 8; ++i)
; #pragma unroll
;         for (int r = 0; r < 4; ++r) {
;           const size_t i0 = (size_t)(mrow + i * 16 + r) * DM + col;
;           const float x0 = rb_[i0], x1 = rb_[i0 + 16], x2 = rb_[i0 + 32], x3 = rb_[i0 + 48];
	v_mfma_f32_16x16x32_bf16 v[124:127], v[152:155], v[188:191], v[124:127]
	v_mfma_f32_16x16x32_bf16 v[120:123], v[156:159], v[188:191], v[120:123]
	v_mfma_f32_16x16x32_bf16 v[116:119], v[160:163], v[188:191], v[116:119]
	v_mfma_f32_16x16x32_bf16 v[112:115], v[164:167], v[188:191], v[112:115]
	ds_read_b128 v[188:191], v226 offset:0
	ds_read_b128 v[168:171], v228 offset:0
	v_mfma_f32_16x16x32_bf16 v[108:111], v[152:155], v[192:195], v[108:111]
	v_mfma_f32_16x16x32_bf16 v[104:107], v[156:159], v[192:195], v[104:107]
	v_mfma_f32_16x16x32_bf16 v[100:103], v[160:163], v[192:195], v[100:103]
	v_mfma_f32_16x16x32_bf16 v[96:99], v[164:167], v[192:195], v[96:99]
	ds_read_b128 v[192:195], v226 offset:2048
	ds_read_b128 v[176:179], v228 offset:2048
	v_mfma_f32_16x16x32_bf16 v[92:95], v[152:155], v[196:199], v[92:95]
	v_mfma_f32_16x16x32_bf16 v[88:91], v[156:159], v[196:199], v[88:91]
	v_mfma_f32_16x16x32_bf16 v[84:87], v[160:163], v[196:199], v[84:87]
	v_mfma_f32_16x16x32_bf16 v[80:83], v[164:167], v[196:199], v[80:83]
	ds_read_b128 v[196:199], v226 offset:4096
	ds_read_b128 v[180:183], v228 offset:4096
	v_mfma_f32_16x16x32_bf16 v[76:79], v[152:155], v[200:203], v[76:79]
	v_mfma_f32_16x16x32_bf16 v[72:75], v[156:159], v[200:203], v[72:75]
	v_mfma_f32_16x16x32_bf16 v[68:71], v[160:163], v[200:203], v[68:71]
	v_mfma_f32_16x16x32_bf16 v[64:67], v[164:167], v[200:203], v[64:67]
	ds_read_b128 v[200:203], v226 offset:6144
	ds_read_b128 v[184:187], v228 offset:6144
	s_waitcnt lgkmcnt(11)
	v_mfma_f32_16x16x32_bf16 v[60:63], v[152:155], v[204:207], v[60:63]
	v_mfma_f32_16x16x32_bf16 v[56:59], v[156:159], v[204:207], v[56:59]
	v_mfma_f32_16x16x32_bf16 v[52:55], v[160:163], v[204:207], v[52:55]
	v_mfma_f32_16x16x32_bf16 v[48:51], v[164:167], v[204:207], v[48:51]
	ds_read_b128 v[204:207], v226 offset:8192
	ds_read_b128 v[220:223], v226 offset:14336
	s_waitcnt lgkmcnt(11)
	v_mfma_f32_16x16x32_bf16 v[44:47], v[152:155], v[208:211], v[44:47]
	v_mfma_f32_16x16x32_bf16 v[40:43], v[156:159], v[208:211], v[40:43]
	v_mfma_f32_16x16x32_bf16 v[36:39], v[160:163], v[208:211], v[36:39]
	v_mfma_f32_16x16x32_bf16 v[32:35], v[164:167], v[208:211], v[32:35]
	ds_read_b128 v[208:211], v226 offset:10240
	s_waitcnt lgkmcnt(11)
	v_mfma_f32_16x16x32_bf16 v[28:31], v[152:155], v[212:215], v[28:31]
	v_mfma_f32_16x16x32_bf16 v[24:27], v[156:159], v[212:215], v[24:27]
	v_mfma_f32_16x16x32_bf16 v[20:23], v[160:163], v[212:215], v[20:23]
	v_mfma_f32_16x16x32_bf16 v[16:19], v[164:167], v[212:215], v[16:19]
	ds_read_b128 v[212:215], v226 offset:12288
	v_mfma_f32_16x16x32_bf16 v[12:15], v[152:155], v[216:219], v[12:15]
	v_mfma_f32_16x16x32_bf16 v[8:11], v[156:159], v[216:219], v[8:11]
	v_mfma_f32_16x16x32_bf16 v[4:7], v[160:163], v[216:219], v[4:7]
	v_mfma_f32_16x16x32_bf16 v[0:3], v[164:167], v[216:219], v[0:3]
	s_waitcnt vmcnt(0) lgkmcnt(0)
	s_barrier
	v_mfma_f32_16x16x32_bf16 v[124:127], v[168:171], v[188:191], v[124:127]
	v_mfma_f32_16x16x32_bf16 v[120:123], v[176:179], v[188:191], v[120:123]
	v_mfma_f32_16x16x32_bf16 v[116:119], v[180:183], v[188:191], v[116:119]
	v_mfma_f32_16x16x32_bf16 v[112:115], v[184:187], v[188:191], v[112:115]
	v_mfma_f32_16x16x32_bf16 v[108:111], v[168:171], v[192:195], v[108:111]
	v_mfma_f32_16x16x32_bf16 v[104:107], v[176:179], v[192:195], v[104:107]
	v_mfma_f32_16x16x32_bf16 v[100:103], v[180:183], v[192:195], v[100:103]
	v_mfma_f32_16x16x32_bf16 v[96:99], v[184:187], v[192:195], v[96:99]
	v_mfma_f32_16x16x32_bf16 v[92:95], v[168:171], v[196:199], v[92:95]
	v_mfma_f32_16x16x32_bf16 v[88:91], v[176:179], v[196:199], v[88:91]
	v_mfma_f32_16x16x32_bf16 v[84:87], v[180:183], v[196:199], v[84:87]
	v_mfma_f32_16x16x32_bf16 v[80:83], v[184:187], v[196:199], v[80:83]
	v_mfma_f32_16x16x32_bf16 v[76:79], v[168:171], v[200:203], v[76:79]
	v_mfma_f32_16x16x32_bf16 v[72:75], v[176:179], v[200:203], v[72:75]
	v_mfma_f32_16x16x32_bf16 v[68:71], v[180:183], v[200:203], v[68:71]
	v_mfma_f32_16x16x32_bf16 v[64:67], v[184:187], v[200:203], v[64:67]
	v_mfma_f32_16x16x32_bf16 v[60:63], v[168:171], v[204:207], v[60:63]
	v_mfma_f32_16x16x32_bf16 v[56:59], v[176:179], v[204:207], v[56:59]
	v_mfma_f32_16x16x32_bf16 v[52:55], v[180:183], v[204:207], v[52:55]
	v_mfma_f32_16x16x32_bf16 v[48:51], v[184:187], v[204:207], v[48:51]
	v_mfma_f32_16x16x32_bf16 v[44:47], v[168:171], v[208:211], v[44:47]
	v_mfma_f32_16x16x32_bf16 v[40:43], v[176:179], v[208:211], v[40:43]
	v_mfma_f32_16x16x32_bf16 v[36:39], v[180:183], v[208:211], v[36:39]
	v_mfma_f32_16x16x32_bf16 v[32:35], v[184:187], v[208:211], v[32:35]
	v_mfma_f32_16x16x32_bf16 v[28:31], v[168:171], v[212:215], v[28:31]
	v_mfma_f32_16x16x32_bf16 v[24:27], v[176:179], v[212:215], v[24:27]
	v_mfma_f32_16x16x32_bf16 v[20:23], v[180:183], v[212:215], v[20:23]
	v_mfma_f32_16x16x32_bf16 v[16:19], v[184:187], v[212:215], v[16:19]
	v_mfma_f32_16x16x32_bf16 v[12:15], v[168:171], v[220:223], v[12:15]
	v_mfma_f32_16x16x32_bf16 v[8:11], v[176:179], v[220:223], v[8:11]
	v_mfma_f32_16x16x32_bf16 v[4:7], v[180:183], v[220:223], v[4:7]
	v_mfma_f32_16x16x32_bf16 v[0:3], v[184:187], v[220:223], v[0:3]
	s_nop 7
	s_nop 3
	v_and_b32_e32 v225, 15, v174
	v_lshrrev_b32_e32 v226, 8, v174
	v_lshl_or_b32 v225, v226, 7, v225
	v_bfe_u32 v226, v174, 6, 2
	v_bfe_u32 v227, v174, 4, 2
	v_lshlrev_b32_e32 v227, 2, v227
	v_add_u32_e32 v225, s39, v225
	v_lshl_add_u32 v226, v226, 6, v227
	v_add_u32_e32 v226, s40, v226
	v_lshlrev_b32_e32 v226, 2, v226
	v_lshl_add_u32 v224, v225, 12, v226
	v_mov_b32_e32 v229, v224
	v_add_u32_e32 v224, 0x0, v229
	global_load_dwordx4 v[152:155], v224, s[22:23] offset:0
	global_load_dwordx4 v[156:159], v224, s[22:23] offset:64
	global_load_dwordx4 v[160:163], v224, s[22:23] offset:128
	global_load_dwordx4 v[164:167], v224, s[22:23] offset:192
	v_add_u32_e32 v228, 0x10000, v229
	global_load_dwordx4 v[168:171], v228, s[22:23] offset:0
	global_load_dwordx4 v[176:179], v228, s[22:23] offset:64
	global_load_dwordx4 v[180:183], v228, s[22:23] offset:128
	global_load_dwordx4 v[184:187], v228, s[22:23] offset:192
	s_waitcnt vmcnt(4)
; template <int EPI>
; DI void gemm_phase(const u16* __restrict__ A, int lda, const u16* __restrict__ Bt, int K, int N, u16* outb, int ldo,
;                    const float* r0, const float* r1, float* outf, char* lds, int bid, int nb) {
;     ...
;     } else if constexpr (EPI == EPI_RESID) {
;       const int col = tn * 256 + wc * 64 + l15;
;       const float* rb_ = (tm * 256 < M_P) ? r0 : (r1 - (size_t)M_P * DM);
; #pragma unroll
;       for (int i = 0; i < 8; ++i)
; #pragma unroll
;         for (int r = 0; r < 4; ++r) {
;           const size_t i0 = (size_t)(mrow + i * 16 + r) * DM + col;
;           const float x0 = rb_[i0], x1 = rb_[i0 + 16], x2 = rb_[i0 + 32], x3 = rb_[i0 + 48];
;           outf[i0] = x0 + acc[i][0][r]; outf[i0 + 16] = x1 + acc[i][1][r]; outf[i0 + 32] = x2 + acc[i][2][r]; outf[i0 + 48] = x3 + acc[i][3][r];
;         }
	v_add_f32_e32 v152, v124, v152
	v_add_f32_e32 v153, v125, v153
	v_add_f32_e32 v154, v126, v154
	v_add_f32_e32 v155, v127, v155
	v_add_f32_e32 v156, v120, v156
	v_add_f32_e32 v157, v121, v157
	v_add_f32_e32 v158, v122, v158
	v_add_f32_e32 v159, v123, v159
	v_add_f32_e32 v160, v116, v160
	v_add_f32_e32 v161, v117, v161
	v_add_f32_e32 v162, v118, v162
	v_add_f32_e32 v163, v119, v163
	v_add_f32_e32 v164, v112, v164
	v_add_f32_e32 v165, v113, v165
	v_add_f32_e32 v166, v114, v166
	v_add_f32_e32 v167, v115, v167
	global_store_dwordx4 v224, v[152:155], s[22:23] offset:0
	global_store_dwordx4 v224, v[156:159], s[22:23] offset:64
	global_store_dwordx4 v224, v[160:163], s[22:23] offset:128
	global_store_dwordx4 v224, v[164:167], s[22:23] offset:192
	s_nop 1
	v_add_u32_e32 v224, 0x20000, v229
	global_load_dwordx4 v[152:155], v224, s[22:23] offset:0
	global_load_dwordx4 v[156:159], v224, s[22:23] offset:64
	global_load_dwordx4 v[160:163], v224, s[22:23] offset:128
	global_load_dwordx4 v[164:167], v224, s[22:23] offset:192
	s_waitcnt vmcnt(8)
	v_add_f32_e32 v168, v108, v168
	v_add_f32_e32 v169, v109, v169
	v_add_f32_e32 v170, v110, v170
	v_add_f32_e32 v171, v111, v171
	v_add_f32_e32 v176, v104, v176
	v_add_f32_e32 v177, v105, v177
	v_add_f32_e32 v178, v106, v178
	v_add_f32_e32 v179, v107, v179
	v_add_f32_e32 v180, v100, v180
	v_add_f32_e32 v181, v101, v181
	v_add_f32_e32 v182, v102, v182
	v_add_f32_e32 v183, v103, v183
	v_add_f32_e32 v184, v96, v184
	v_add_f32_e32 v185, v97, v185
	v_add_f32_e32 v186, v98, v186
	v_add_f32_e32 v187, v99, v187
	global_store_dwordx4 v228, v[168:171], s[22:23] offset:0
	global_store_dwordx4 v228, v[176:179], s[22:23] offset:64
	global_store_dwordx4 v228, v[180:183], s[22:23] offset:128
	global_store_dwordx4 v228, v[184:187], s[22:23] offset:192
	s_nop 1
	v_add_u32_e32 v228, 0x30000, v229
	global_load_dwordx4 v[168:171], v228, s[22:23] offset:0
	global_load_dwordx4 v[176:179], v228, s[22:23] offset:64
	global_load_dwordx4 v[180:183], v228, s[22:23] offset:128
	global_load_dwordx4 v[184:187], v228, s[22:23] offset:192
	s_waitcnt vmcnt(8)
	v_add_f32_e32 v152, v92, v152
	v_add_f32_e32 v153, v93, v153
	v_add_f32_e32 v154, v94, v154
	v_add_f32_e32 v155, v95, v155
	v_add_f32_e32 v156, v88, v156
	v_add_f32_e32 v157, v89, v157
	v_add_f32_e32 v158, v90, v158
	v_add_f32_e32 v159, v91, v159
	v_add_f32_e32 v160, v84, v160
	v_add_f32_e32 v161, v85, v161
	v_add_f32_e32 v162, v86, v162
	v_add_f32_e32 v163, v87, v163
	v_add_f32_e32 v164, v80, v164
	v_add_f32_e32 v165, v81, v165
	v_add_f32_e32 v166, v82, v166
	v_add_f32_e32 v167, v83, v167
	global_store_dwordx4 v224, v[152:155], s[22:23] offset:0
	global_store_dwordx4 v224, v[156:159], s[22:23] offset:64
	global_store_dwordx4 v224, v[160:163], s[22:23] offset:128
	global_store_dwordx4 v224, v[164:167], s[22:23] offset:192
	s_nop 1
	v_add_u32_e32 v224, 0x40000, v229
	global_load_dwordx4 v[152:155], v224, s[22:23] offset:0
	global_load_dwordx4 v[156:159], v224, s[22:23] offset:64
	global_load_dwordx4 v[160:163], v224, s[22:23] offset:128
	global_load_dwordx4 v[164:167], v224, s[22:23] offset:192
	s_waitcnt vmcnt(8)
	v_add_f32_e32 v168, v76, v168
	v_add_f32_e32 v169, v77, v169
	v_add_f32_e32 v170, v78, v170
	v_add_f32_e32 v171, v79, v171
	v_add_f32_e32 v176, v72, v176
	v_add_f32_e32 v177, v73, v177
	v_add_f32_e32 v178, v74, v178
	v_add_f32_e32 v179, v75, v179
	v_add_f32_e32 v180, v68, v180
	v_add_f32_e32 v181, v69, v181
	v_add_f32_e32 v182, v70, v182
	v_add_f32_e32 v183, v71, v183
	v_add_f32_e32 v184, v64, v184
	v_add_f32_e32 v185, v65, v185
	v_add_f32_e32 v186, v66, v186
	v_add_f32_e32 v187, v67, v187
	global_store_dwordx4 v228, v[168:171], s[22:23] offset:0
	global_store_dwordx4 v228, v[176:179], s[22:23] offset:64
	global_store_dwordx4 v228, v[180:183], s[22:23] offset:128
	global_store_dwordx4 v228, v[184:187], s[22:23] offset:192
	s_nop 1
	v_add_u32_e32 v228, 0x50000, v229
	global_load_dwordx4 v[168:171], v228, s[22:23] offset:0
	global_load_dwordx4 v[176:179], v228, s[22:23] offset:64
	global_load_dwordx4 v[180:183], v228, s[22:23] offset:128
	global_load_dwordx4 v[184:187], v228, s[22:23] offset:192
	s_waitcnt vmcnt(8)
; template <int EPI>
; DI void gemm_phase(const u16* __restrict__ A, int lda, const u16* __restrict__ Bt, int K, int N, u16* outb, int ldo,
;                    const float* r0, const float* r1, float* outf, char* lds, int bid, int nb) {
;     ...
;     } else if constexpr (EPI == EPI_RESID) {
;       const int col = tn * 256 + wc * 64 + l15;
;       const float* rb_ = (tm * 256 < M_P) ? r0 : (r1 - (size_t)M_P * DM);
; #pragma unroll
;       for (int i = 0; i < 8; ++i)
; #pragma unroll
;         for (int r = 0; r < 4; ++r) {
;           const size_t i0 = (size_t)(mrow + i * 16 + r) * DM + col;
;           const float x0 = rb_[i0], x1 = rb_[i0 + 16], x2 = rb_[i0 + 32], x3 = rb_[i0 + 48];
;           outf[i0] = x0 + acc[i][0][r]; outf[i0 + 16] = x1 + acc[i][1][r]; outf[i0 + 32] = x2 + acc[i][2][r]; outf[i0 + 48] = x3 + acc[i][3][r];
;         }
	v_add_f32_e32 v152, v60, v152
	v_add_f32_e32 v153, v61, v153
	v_add_f32_e32 v154, v62, v154
	v_add_f32_e32 v155, v63, v155
	v_add_f32_e32 v156, v56, v156
	v_add_f32_e32 v157, v57, v157
	v_add_f32_e32 v158, v58, v158
	v_add_f32_e32 v159, v59, v159
	v_add_f32_e32 v160, v52, v160
	v_add_f32_e32 v161, v53, v161
	v_add_f32_e32 v162, v54, v162
	v_add_f32_e32 v163, v55, v163
	v_add_f32_e32 v164, v48, v164
	v_add_f32_e32 v165, v49, v165
	v_add_f32_e32 v166, v50, v166
	v_add_f32_e32 v167, v51, v167
	global_store_dwordx4 v224, v[152:155], s[22:23] offset:0
	global_store_dwordx4 v224, v[156:159], s[22:23] offset:64
	global_store_dwordx4 v224, v[160:163], s[22:23] offset:128
	global_store_dwordx4 v224, v[164:167], s[22:23] offset:192
	s_nop 1
	v_add_u32_e32 v224, 0x60000, v229
	global_load_dwordx4 v[152:155], v224, s[22:23] offset:0
	global_load_dwordx4 v[156:159], v224, s[22:23] offset:64
	global_load_dwordx4 v[160:163], v224, s[22:23] offset:128
	global_load_dwordx4 v[164:167], v224, s[22:23] offset:192
	s_waitcnt vmcnt(8)
	v_add_f32_e32 v168, v44, v168
	v_add_f32_e32 v169, v45, v169
	v_add_f32_e32 v170, v46, v170
	v_add_f32_e32 v171, v47, v171
	v_add_f32_e32 v176, v40, v176
	v_add_f32_e32 v177, v41, v177
	v_add_f32_e32 v178, v42, v178
	v_add_f32_e32 v179, v43, v179
	v_add_f32_e32 v180, v36, v180
	v_add_f32_e32 v181, v37, v181
	v_add_f32_e32 v182, v38, v182
	v_add_f32_e32 v183, v39, v183
	v_add_f32_e32 v184, v32, v184
	v_add_f32_e32 v185, v33, v185
	v_add_f32_e32 v186, v34, v186
	v_add_f32_e32 v187, v35, v187
	global_store_dwordx4 v228, v[168:171], s[22:23] offset:0
	global_store_dwordx4 v228, v[176:179], s[22:23] offset:64
	global_store_dwordx4 v228, v[180:183], s[22:23] offset:128
	global_store_dwordx4 v228, v[184:187], s[22:23] offset:192
	s_nop 1
	v_add_u32_e32 v228, 0x70000, v229
	global_load_dwordx4 v[168:171], v228, s[22:23] offset:0
	global_load_dwordx4 v[176:179], v228, s[22:23] offset:64
	global_load_dwordx4 v[180:183], v228, s[22:23] offset:128
	global_load_dwordx4 v[184:187], v228, s[22:23] offset:192
	s_waitcnt vmcnt(8)
	v_add_f32_e32 v152, v28, v152
	v_add_f32_e32 v153, v29, v153
	v_add_f32_e32 v154, v30, v154
	v_add_f32_e32 v155, v31, v155
	v_add_f32_e32 v156, v24, v156
	v_add_f32_e32 v157, v25, v157
	v_add_f32_e32 v158, v26, v158
	v_add_f32_e32 v159, v27, v159
	v_add_f32_e32 v160, v20, v160
	v_add_f32_e32 v161, v21, v161
	v_add_f32_e32 v162, v22, v162
	v_add_f32_e32 v163, v23, v163
	v_add_f32_e32 v164, v16, v164
	v_add_f32_e32 v165, v17, v165
	v_add_f32_e32 v166, v18, v166
	v_add_f32_e32 v167, v19, v167
	global_store_dwordx4 v224, v[152:155], s[22:23] offset:0
	global_store_dwordx4 v224, v[156:159], s[22:23] offset:64
	global_store_dwordx4 v224, v[160:163], s[22:23] offset:128
	global_store_dwordx4 v224, v[164:167], s[22:23] offset:192
	s_waitcnt vmcnt(4)
	v_add_f32_e32 v168, v12, v168
	v_add_f32_e32 v169, v13, v169
	v_add_f32_e32 v170, v14, v170
	v_add_f32_e32 v171, v15, v171
	v_add_f32_e32 v176, v8, v176
	v_add_f32_e32 v177, v9, v177
	v_add_f32_e32 v178, v10, v178
	v_add_f32_e32 v179, v11, v179
	v_add_f32_e32 v180, v4, v180
	v_add_f32_e32 v181, v5, v181
	v_add_f32_e32 v182, v6, v182
	v_add_f32_e32 v183, v7, v183
	v_add_f32_e32 v184, v0, v184
	v_add_f32_e32 v185, v1, v185
	v_add_f32_e32 v186, v2, v186
	v_add_f32_e32 v187, v3, v187
	global_store_dwordx4 v228, v[168:171], s[22:23] offset:0
	global_store_dwordx4 v228, v[176:179], s[22:23] offset:64
	global_store_dwordx4 v228, v[180:183], s[22:23] offset:128
	global_store_dwordx4 v228, v[184:187], s[22:23] offset:192
	s_add_i32 s14, s14, 1
	s_cmp_eq_u32 s14, s3
	s_cbranch_scc0 .LBB0_1177

; #define G_LOAD(KT) do { _Pragma("unroll") for (int i = 0; i < 4; ++i) { ra[i] = *(const u32x4*)(Ag + (size_t)i * 64 * lda + (KT) * 64); rb[i] = *(const u32x4*)(Bg + (size_t)i * 64 * K + (KT) * 64); } } while (0)
; #define G_STORE(BUF) do { u16* ad = As + (BUF) * 256 * 64 + sto; u16* bd = Bs + (BUF) * 256 * 64 + sto; _Pragma("unroll") for (int i = 0; i < 4; ++i) { *(u32x4*)(ad + i * 64 * 64) = ra[i]; *(u32x4*)(bd + i * 64 * 64) = rb[i]; } } while (0)
; template <int EPI>
; DI void gemm_phase(const u16* __restrict__ A, int lda, const u16* __restrict__ Bt, int K, int N, u16* outb, int ldo,
;                    const float* r0, const float* r1, float* outf, char* lds, int bid, int nb) {
;     ...
;     G_LOAD(0);
;     G_STORE(0);
;     __syncthreads();
;     for (int kt = 0; kt < nk; ++kt) {
;       const int cur = kt & 1;
;       if (kt + 1 < nk) G_LOAD(kt + 1);
;       G_MMA(cur, fo0);
;       G_MMA(cur, fo1);
;       if (kt + 1 < nk) G_STORE(cur ^ 1);
;       __syncthreads();
;     }
.Lgm6_loop:
	s_waitcnt lgkmcnt(4)
	v_mfma_f32_16x16x32_bf16 v[124:127], v[152:155], v[188:191], v[124:127]
	v_mfma_f32_16x16x32_bf16 v[120:123], v[156:159], v[188:191], v[120:123]
	v_mfma_f32_16x16x32_bf16 v[116:119], v[160:163], v[188:191], v[116:119]
	v_mfma_f32_16x16x32_bf16 v[112:115], v[164:167], v[188:191], v[112:115]
	ds_read_b128 v[188:191], v226 offset:0
	ds_read_b128 v[168:171], v228 offset:0
	v_mfma_f32_16x16x32_bf16 v[108:111], v[152:155], v[192:195], v[108:111]
	v_mfma_f32_16x16x32_bf16 v[104:107], v[156:159], v[192:195], v[104:107]
	v_mfma_f32_16x16x32_bf16 v[100:103], v[160:163], v[192:195], v[100:103]
	v_mfma_f32_16x16x32_bf16 v[96:99], v[164:167], v[192:195], v[96:99]
	ds_read_b128 v[192:195], v226 offset:2048
	ds_read_b128 v[176:179], v228 offset:2048
	v_mfma_f32_16x16x32_bf16 v[92:95], v[152:155], v[196:199], v[92:95]
	v_mfma_f32_16x16x32_bf16 v[88:91], v[156:159], v[196:199], v[88:91]
	v_mfma_f32_16x16x32_bf16 v[84:87], v[160:163], v[196:199], v[84:87]
	v_mfma_f32_16x16x32_bf16 v[80:83], v[164:167], v[196:199], v[80:83]
	ds_read_b128 v[196:199], v226 offset:4096
	ds_read_b128 v[180:183], v228 offset:4096
	v_mfma_f32_16x16x32_bf16 v[76:79], v[152:155], v[200:203], v[76:79]
	v_mfma_f32_16x16x32_bf16 v[72:75], v[156:159], v[200:203], v[72:75]
	v_mfma_f32_16x16x32_bf16 v[68:71], v[160:163], v[200:203], v[68:71]
	v_mfma_f32_16x16x32_bf16 v[64:67], v[164:167], v[200:203], v[64:67]
	ds_read_b128 v[200:203], v226 offset:6144
	ds_read_b128 v[184:187], v228 offset:6144
	s_waitcnt lgkmcnt(11)
	v_mfma_f32_16x16x32_bf16 v[60:63], v[152:155], v[204:207], v[60:63]
	v_mfma_f32_16x16x32_bf16 v[56:59], v[156:159], v[204:207], v[56:59]
	v_mfma_f32_16x16x32_bf16 v[52:55], v[160:163], v[204:207], v[52:55]
	v_mfma_f32_16x16x32_bf16 v[48:51], v[164:167], v[204:207], v[48:51]
	ds_read_b128 v[204:207], v226 offset:8192
	ds_read_b128 v[220:223], v226 offset:14336
	s_waitcnt lgkmcnt(11)
	v_mfma_f32_16x16x32_bf16 v[44:47], v[152:155], v[208:211], v[44:47]
	v_mfma_f32_16x16x32_bf16 v[40:43], v[156:159], v[208:211], v[40:43]
	v_mfma_f32_16x16x32_bf16 v[36:39], v[160:163], v[208:211], v[36:39]
	v_mfma_f32_16x16x32_bf16 v[32:35], v[164:167], v[208:211], v[32:35]
	ds_read_b128 v[208:211], v226 offset:10240
	s_waitcnt lgkmcnt(11)
	v_mfma_f32_16x16x32_bf16 v[28:31], v[152:155], v[212:215], v[28:31]
	v_mfma_f32_16x16x32_bf16 v[24:27], v[156:159], v[212:215], v[24:27]
	v_mfma_f32_16x16x32_bf16 v[20:23], v[160:163], v[212:215], v[20:23]
	v_mfma_f32_16x16x32_bf16 v[16:19], v[164:167], v[212:215], v[16:19]
	ds_read_b128 v[212:215], v226 offset:12288
	v_mfma_f32_16x16x32_bf16 v[12:15], v[152:155], v[216:219], v[12:15]
	v_mfma_f32_16x16x32_bf16 v[8:11], v[156:159], v[216:219], v[8:11]
	v_mfma_f32_16x16x32_bf16 v[4:7], v[160:163], v[216:219], v[4:7]
	v_mfma_f32_16x16x32_bf16 v[0:3], v[164:167], v[216:219], v[0:3]
	s_waitcnt vmcnt(0) lgkmcnt(0)
	s_barrier
	v_mfma_f32_16x16x32_bf16 v[124:127], v[168:171], v[188:191], v[124:127]
	v_mfma_f32_16x16x32_bf16 v[120:123], v[176:179], v[188:191], v[120:123]
	v_mfma_f32_16x16x32_bf16 v[116:119], v[180:183], v[188:191], v[116:119]
	v_mfma_f32_16x16x32_bf16 v[112:115], v[184:187], v[188:191], v[112:115]
	ds_read_b128 v[188:191], v225 offset:0
	ds_read_b128 v[152:155], v227 offset:0
	s_add_u32 s10, s98, 0x0
	s_addc_u32 s11, s99, 0
	s_add_u32 m0, s97, 0x0
	s_nop 0
	global_load_lds_dwordx4 v224, s[10:11]
	v_mfma_f32_16x16x32_bf16 v[108:111], v[168:171], v[192:195], v[108:111]
	v_mfma_f32_16x16x32_bf16 v[104:107], v[176:179], v[192:195], v[104:107]
	v_mfma_f32_16x16x32_bf16 v[100:103], v[180:183], v[192:195], v[100:103]
	v_mfma_f32_16x16x32_bf16 v[96:99], v[184:187], v[192:195], v[96:99]
	ds_read_b128 v[192:195], v225 offset:2048
	ds_read_b128 v[156:159], v227 offset:2048
	s_add_u32 s10, s100, 0x0
	s_addc_u32 s11, s101, 0
	s_add_u32 m0, s97, 0x10000
	s_nop 0
	global_load_lds_dwordx4 v224, s[10:11]
	v_mfma_f32_16x16x32_bf16 v[92:95], v[168:171], v[196:199], v[92:95]
	v_mfma_f32_16x16x32_bf16 v[88:91], v[176:179], v[196:199], v[88:91]
	v_mfma_f32_16x16x32_bf16 v[84:87], v[180:183], v[196:199], v[84:87]
	v_mfma_f32_16x16x32_bf16 v[80:83], v[184:187], v[196:199], v[80:83]
	ds_read_b128 v[196:199], v225 offset:4096
	ds_read_b128 v[160:163], v227 offset:4096
	s_add_u32 s10, s98, 0x20000
	s_addc_u32 s11, s99, 0
	s_add_u32 m0, s97, 0x2000
	s_nop 0
	global_load_lds_dwordx4 v224, s[10:11]
	v_mfma_f32_16x16x32_bf16 v[76:79], v[168:171], v[200:203], v[76:79]
	v_mfma_f32_16x16x32_bf16 v[72:75], v[176:179], v[200:203], v[72:75]
	v_mfma_f32_16x16x32_bf16 v[68:71], v[180:183], v[200:203], v[68:71]
	v_mfma_f32_16x16x32_bf16 v[64:67], v[184:187], v[200:203], v[64:67]
	ds_read_b128 v[200:203], v225 offset:6144
	ds_read_b128 v[164:167], v227 offset:6144
	s_add_u32 s10, s100, 0x20000
	s_addc_u32 s11, s101, 0
	s_add_u32 m0, s97, 0x12000
	s_nop 0
	global_load_lds_dwordx4 v224, s[10:11]
	v_mfma_f32_16x16x32_bf16 v[60:63], v[168:171], v[204:207], v[60:63]
	v_mfma_f32_16x16x32_bf16 v[56:59], v[176:179], v[204:207], v[56:59]
	v_mfma_f32_16x16x32_bf16 v[52:55], v[180:183], v[204:207], v[52:55]
	v_mfma_f32_16x16x32_bf16 v[48:51], v[184:187], v[204:207], v[48:51]
	ds_read_b128 v[204:207], v225 offset:8192
	ds_read_b128 v[216:219], v225 offset:14336
	s_add_u32 s10, s98, 0x40000
	s_addc_u32 s11, s99, 0
	s_add_u32 m0, s97, 0x4000
	s_nop 0
	global_load_lds_dwordx4 v224, s[10:11]
	v_mfma_f32_16x16x32_bf16 v[44:47], v[168:171], v[208:211], v[44:47]
	v_mfma_f32_16x16x32_bf16 v[40:43], v[176:179], v[208:211], v[40:43]
	v_mfma_f32_16x16x32_bf16 v[36:39], v[180:183], v[208:211], v[36:39]
	v_mfma_f32_16x16x32_bf16 v[32:35], v[184:187], v[208:211], v[32:35]
	ds_read_b128 v[208:211], v225 offset:10240
	s_add_u32 s10, s100, 0x40000
	s_addc_u32 s11, s101, 0
	s_add_u32 m0, s97, 0x14000
	s_nop 0
	global_load_lds_dwordx4 v224, s[10:11]
	v_mfma_f32_16x16x32_bf16 v[28:31], v[168:171], v[212:215], v[28:31]
	v_mfma_f32_16x16x32_bf16 v[24:27], v[176:179], v[212:215], v[24:27]
	v_mfma_f32_16x16x32_bf16 v[20:23], v[180:183], v[212:215], v[20:23]
	v_mfma_f32_16x16x32_bf16 v[16:19], v[184:187], v[212:215], v[16:19]
	ds_read_b128 v[212:215], v225 offset:12288
	s_add_u32 s10, s98, 0x60000
	s_addc_u32 s11, s99, 0
	s_add_u32 m0, s97, 0x6000
	s_nop 0
	global_load_lds_dwordx4 v224, s[10:11]
	v_mfma_f32_16x16x32_bf16 v[12:15], v[168:171], v[220:223], v[12:15]
	v_mfma_f32_16x16x32_bf16 v[8:11], v[176:179], v[220:223], v[8:11]
	v_mfma_f32_16x16x32_bf16 v[4:7], v[180:183], v[220:223], v[4:7]
	v_mfma_f32_16x16x32_bf16 v[0:3], v[184:187], v[220:223], v[0:3]
	s_add_u32 s10, s100, 0x60000
	s_addc_u32 s11, s101, 0
	s_add_u32 m0, s97, 0x16000
	s_nop 0
	global_load_lds_dwordx4 v224, s[10:11]
	v_xor_b32_e32 v225, 0x8000, v225
	v_xor_b32_e32 v227, 0x8000, v227
	v_xor_b32_e32 v226, 0x8000, v226
	v_xor_b32_e32 v228, 0x8000, v228
	s_xor_b32 s97, s97, 0x8000
	s_add_u32 s98, s98, 0x80
	s_addc_u32 s99, s99, 0
	s_add_u32 s100, s100, 0x80
	s_addc_u32 s101, s101, 0
	s_sub_u32 s28, s28, 1
	s_cmp_lg_u32 s28, 0
	s_cbranch_scc1 .Lgm6_loop
; #define G_LOAD(KT) do { _Pragma("unroll") for (int i = 0; i < 4; ++i) { ra[i] = *(const u32x4*)(Ag + (size_t)i * 64 * lda + (KT) * 64); rb[i] = *(const u32x4*)(Bg + (size_t)i * 64 * K + (KT) * 64); } } while (0)
; #define G_STORE(BUF) do { u16* ad = As + (BUF) * 256 * 64 + sto; u16* bd = Bs + (BUF) * 256 * 64 + sto; _Pragma("unroll") for (int i = 0; i < 4; ++i) { *(u32x4*)(ad + i * 64 * 64) = ra[i]; *(u32x4*)(bd + i * 64 * 64) = rb[i]; } } while (0)
; template <int EPI>
; DI void gemm_phase(const u16* __restrict__ A, int lda, const u16* __restrict__ Bt, int K, int N, u16* outb, int ldo,
;                    const float* r0, const float* r1, float* outf, char* lds, int bid, int nb) {
;     ...
;     G_LOAD(0);
;     G_STORE(0);
;     __syncthreads();
;     for (int kt = 0; kt < nk; ++kt) {
;       const int cur = kt & 1;
;       if (kt + 1 < nk) G_LOAD(kt + 1);
;       G_MMA(cur, fo0);
;       G_MMA(cur, fo1);
;       if (kt + 1 < nk) G_STORE(cur ^ 1);
;       __syncthreads();
	s_waitcnt lgkmcnt(4)
	v_mfma_f32_16x16x32_bf16 v[124:127], v[152:155], v[188:191], v[124:127]
	v_mfma_f32_16x16x32_bf16 v[120:123], v[156:159], v[188:191], v[120:123]
	v_mfma_f32_16x16x32_bf16 v[116:119], v[160:163], v[188:191], v[116:119]
	v_mfma_f32_16x16x32_bf16 v[112:115], v[164:167], v[188:191], v[112:115]
	ds_read_b128 v[188:191], v226 offset:0
	ds_read_b128 v[168:171], v228 offset:0
	v_mfma_f32_16x16x32_bf16 v[108:111], v[152:155], v[192:195], v[108:111]
	v_mfma_f32_16x16x32_bf16 v[104:107], v[156:159], v[192:195], v[104:107]
	v_mfma_f32_16x16x32_bf16 v[100:103], v[160:163], v[192:195], v[100:103]
	v_mfma_f32_16x16x32_bf16 v[96:99], v[164:167], v[192:195], v[96:99]
	ds_read_b128 v[192:195], v226 offset:2048
	ds_read_b128 v[176:179], v228 offset:2048
	v_mfma_f32_16x16x32_bf16 v[92:95], v[152:155], v[196:199], v[92:95]
	v_mfma_f32_16x16x32_bf16 v[88:91], v[156:159], v[196:199], v[88:91]
	v_mfma_f32_16x16x32_bf16 v[84:87], v[160:163], v[196:199], v[84:87]
	v_mfma_f32_16x16x32_bf16 v[80:83], v[164:167], v[196:199], v[80:83]
	ds_read_b128 v[196:199], v226 offset:4096
	ds_read_b128 v[180:183], v228 offset:4096
	v_mfma_f32_16x16x32_bf16 v[76:79], v[152:155], v[200:203], v[76:79]
	v_mfma_f32_16x16x32_bf16 v[72:75], v[156:159], v[200:203], v[72:75]
	v_mfma_f32_16x16x32_bf16 v[68:71], v[160:163], v[200:203], v[68:71]
	v_mfma_f32_16x16x32_bf16 v[64:67], v[164:167], v[200:203], v[64:67]
	ds_read_b128 v[200:203], v226 offset:6144
	ds_read_b128 v[184:187], v228 offset:6144
	s_waitcnt lgkmcnt(11)
	v_mfma_f32_16x16x32_bf16 v[60:63], v[152:155], v[204:207], v[60:63]
	v_mfma_f32_16x16x32_bf16 v[56:59], v[156:159], v[204:207], v[56:59]
	v_mfma_f32_16x16x32_bf16 v[52:55], v[160:163], v[204:207], v[52:55]
	v_mfma_f32_16x16x32_bf16 v[48:51], v[164:167], v[204:207], v[48:51]
	ds_read_b128 v[204:207], v226 offset:8192
	ds_read_b128 v[220:223], v226 offset:14336
	s_waitcnt lgkmcnt(11)
	v_mfma_f32_16x16x32_bf16 v[44:47], v[152:155], v[208:211], v[44:47]
	v_mfma_f32_16x16x32_bf16 v[40:43], v[156:159], v[208:211], v[40:43]
	v_mfma_f32_16x16x32_bf16 v[36:39], v[160:163], v[208:211], v[36:39]
	v_mfma_f32_16x16x32_bf16 v[32:35], v[164:167], v[208:211], v[32:35]
	ds_read_b128 v[208:211], v226 offset:10240
	s_waitcnt lgkmcnt(11)
	v_mfma_f32_16x16x32_bf16 v[28:31], v[152:155], v[212:215], v[28:31]
	v_mfma_f32_16x16x32_bf16 v[24:27], v[156:159], v[212:215], v[24:27]
	v_mfma_f32_16x16x32_bf16 v[20:23], v[160:163], v[212:215], v[20:23]
	v_mfma_f32_16x16x32_bf16 v[16:19], v[164:167], v[212:215], v[16:19]
	ds_read_b128 v[212:215], v226 offset:12288
	v_mfma_f32_16x16x32_bf16 v[12:15], v[152:155], v[216:219], v[12:15]
	v_mfma_f32_16x16x32_bf16 v[8:11], v[156:159], v[216:219], v[8:11]
	v_mfma_f32_16x16x32_bf16 v[4:7], v[160:163], v[216:219], v[4:7]
	v_mfma_f32_16x16x32_bf16 v[0:3], v[164:167], v[216:219], v[0:3]
	s_waitcnt vmcnt(0) lgkmcnt(0)
	s_barrier
	v_mfma_f32_16x16x32_bf16 v[124:127], v[168:171], v[188:191], v[124:127]
	v_mfma_f32_16x16x32_bf16 v[120:123], v[176:179], v[188:191], v[120:123]
	v_mfma_f32_16x16x32_bf16 v[116:119], v[180:183], v[188:191], v[116:119]
	v_mfma_f32_16x16x32_bf16 v[112:115], v[184:187], v[188:191], v[112:115]
	ds_read_b128 v[188:191], v225 offset:0
	ds_read_b128 v[152:155], v227 offset:0
	v_mfma_f32_16x16x32_bf16 v[108:111], v[168:171], v[192:195], v[108:111]
	v_mfma_f32_16x16x32_bf16 v[104:107], v[176:179], v[192:195], v[104:107]
	v_mfma_f32_16x16x32_bf16 v[100:103], v[180:183], v[192:195], v[100:103]
	v_mfma_f32_16x16x32_bf16 v[96:99], v[184:187], v[192:195], v[96:99]
	ds_read_b128 v[192:195], v225 offset:2048
	ds_read_b128 v[156:159], v227 offset:2048
	v_mfma_f32_16x16x32_bf16 v[92:95], v[168:171], v[196:199], v[92:95]
	v_mfma_f32_16x16x32_bf16 v[88:91], v[176:179], v[196:199], v[88:91]
	v_mfma_f32_16x16x32_bf16 v[84:87], v[180:183], v[196:199], v[84:87]
	v_mfma_f32_16x16x32_bf16 v[80:83], v[184:187], v[196:199], v[80:83]
	ds_read_b128 v[196:199], v225 offset:4096
	ds_read_b128 v[160:163], v227 offset:4096
	v_mfma_f32_16x16x32_bf16 v[76:79], v[168:171], v[200:203], v[76:79]
	v_mfma_f32_16x16x32_bf16 v[72:75], v[176:179], v[200:203], v[72:75]
	v_mfma_f32_16x16x32_bf16 v[68:71], v[180:183], v[200:203], v[68:71]
	v_mfma_f32_16x16x32_bf16 v[64:67], v[184:187], v[200:203], v[64:67]
	ds_read_b128 v[200:203], v225 offset:6144
	ds_read_b128 v[164:167], v227 offset:6144
	v_mfma_f32_16x16x32_bf16 v[60:63], v[168:171], v[204:207], v[60:63]
	v_mfma_f32_16x16x32_bf16 v[56:59], v[176:179], v[204:207], v[56:59]
	v_mfma_f32_16x16x32_bf16 v[52:55], v[180:183], v[204:207], v[52:55]
	v_mfma_f32_16x16x32_bf16 v[48:51], v[184:187], v[204:207], v[48:51]
	ds_read_b128 v[204:207], v225 offset:8192
	ds_read_b128 v[216:219], v225 offset:14336
	v_mfma_f32_16x16x32_bf16 v[44:47], v[168:171], v[208:211], v[44:47]
	v_mfma_f32_16x16x32_bf16 v[40:43], v[176:179], v[208:211], v[40:43]
	v_mfma_f32_16x16x32_bf16 v[36:39], v[180:183], v[208:211], v[36:39]
	v_mfma_f32_16x16x32_bf16 v[32:35], v[184:187], v[208:211], v[32:35]
	ds_read_b128 v[208:211], v225 offset:10240
	v_mfma_f32_16x16x32_bf16 v[28:31], v[168:171], v[212:215], v[28:31]
	v_mfma_f32_16x16x32_bf16 v[24:27], v[176:179], v[212:215], v[24:27]
	v_mfma_f32_16x16x32_bf16 v[20:23], v[180:183], v[212:215], v[20:23]
	v_mfma_f32_16x16x32_bf16 v[16:19], v[184:187], v[212:215], v[16:19]
	ds_read_b128 v[212:215], v225 offset:12288
	v_mfma_f32_16x16x32_bf16 v[12:15], v[168:171], v[220:223], v[12:15]
	v_mfma_f32_16x16x32_bf16 v[8:11], v[176:179], v[220:223], v[8:11]
	v_mfma_f32_16x16x32_bf16 v[4:7], v[180:183], v[220:223], v[4:7]
	v_mfma_f32_16x16x32_bf16 v[0:3], v[184:187], v[220:223], v[0:3]
	v_xor_b32_e32 v226, 0x8000, v226
	v_xor_b32_e32 v228, 0x8000, v228
	s_waitcnt lgkmcnt(4)
; DI u16 f2bf(float a) { return (u16)(pk2(a, 0.f) & 0xffffu); }
; DI float sigmoidf_(float x) { return __builtin_amdgcn_rcpf(1.f + __builtin_amdgcn_exp2f(-1.4426950408889634f * x)); }
; #define G_LOAD(KT) do { _Pragma("unroll") for (int i = 0; i < 4; ++i) { ra[i] = *(const u32x4*)(Ag + (size_t)i * 64 * lda + (KT) * 64); rb[i] = *(const u32x4*)(Bg + (size_t)i * 64 * K + (KT) * 64); } } while (0)
; #define G_STORE(BUF) do { u16* ad = As + (BUF) * 256 * 64 + sto; u16* bd = Bs + (BUF) * 256 * 64 + sto; _Pragma("unroll") for (int i = 0; i < 4; ++i) { *(u32x4*)(ad + i * 64 * 64) = ra[i]; *(u32x4*)(bd + i * 64 * 64) = rb[i]; } } while (0)
; template <int EPI>
; DI void gemm_phase(const u16* __restrict__ A, int lda, const u16* __restrict__ Bt, int K, int N, u16* outb, int ldo,
;                    const float* r0, const float* r1, float* outf, char* lds, int bid, int nb) {
;     ...
;     G_LOAD(0);
;     G_STORE(0);
;     __syncthreads();
;     for (int kt = 0; kt < nk; ++kt) {
;       const int cur = kt & 1;
;       if (kt + 1 < nk) G_LOAD(kt + 1);
;       G_MMA(cur, fo0);
;       G_MMA(cur, fo1);
;     ...
;     } else {
;       const int col = (tn * 4 + wc) * 32 + l15;
; #pragma unroll
;       for (int i = 0; i < 8; ++i)
; #pragma unroll
;         for (int r = 0; r < 4; ++r) {
;           const float g0 = acc[i][0][r], u0 = acc[i][2][r], g1 = acc[i][1][r], u1 = acc[i][3][r];
;           u16* o0 = outb + (size_t)(mrow + i * 16 + r) * ldo + col;
;           o0[0] = f2bf(g0 * sigmoidf_(g0) * u0); o0[16] = f2bf(g1 * sigmoidf_(g1) * u1);
;         }
	v_mfma_f32_16x16x32_bf16 v[124:127], v[152:155], v[188:191], v[124:127]
	v_mfma_f32_16x16x32_bf16 v[120:123], v[156:159], v[188:191], v[120:123]
	v_mfma_f32_16x16x32_bf16 v[116:119], v[160:163], v[188:191], v[116:119]
	v_mfma_f32_16x16x32_bf16 v[112:115], v[164:167], v[188:191], v[112:115]
	ds_read_b128 v[188:191], v226 offset:0
	ds_read_b128 v[168:171], v228 offset:0
	v_mfma_f32_16x16x32_bf16 v[108:111], v[152:155], v[192:195], v[108:111]
	v_mfma_f32_16x16x32_bf16 v[104:107], v[156:159], v[192:195], v[104:107]
	v_mfma_f32_16x16x32_bf16 v[100:103], v[160:163], v[192:195], v[100:103]
	v_mfma_f32_16x16x32_bf16 v[96:99], v[164:167], v[192:195], v[96:99]
	ds_read_b128 v[192:195], v226 offset:2048
	ds_read_b128 v[176:179], v228 offset:2048
	v_mfma_f32_16x16x32_bf16 v[92:95], v[152:155], v[196:199], v[92:95]
	v_mfma_f32_16x16x32_bf16 v[88:91], v[156:159], v[196:199], v[88:91]
	v_mfma_f32_16x16x32_bf16 v[84:87], v[160:163], v[196:199], v[84:87]
	v_mfma_f32_16x16x32_bf16 v[80:83], v[164:167], v[196:199], v[80:83]
	ds_read_b128 v[196:199], v226 offset:4096
	ds_read_b128 v[180:183], v228 offset:4096
	v_mfma_f32_16x16x32_bf16 v[76:79], v[152:155], v[200:203], v[76:79]
	v_mfma_f32_16x16x32_bf16 v[72:75], v[156:159], v[200:203], v[72:75]
	v_mfma_f32_16x16x32_bf16 v[68:71], v[160:163], v[200:203], v[68:71]
	v_mfma_f32_16x16x32_bf16 v[64:67], v[164:167], v[200:203], v[64:67]
	ds_read_b128 v[200:203], v226 offset:6144
	ds_read_b128 v[184:187], v228 offset:6144
	s_waitcnt lgkmcnt(11)
	v_mfma_f32_16x16x32_bf16 v[60:63], v[152:155], v[204:207], v[60:63]
	v_mfma_f32_16x16x32_bf16 v[56:59], v[156:159], v[204:207], v[56:59]
	v_mfma_f32_16x16x32_bf16 v[52:55], v[160:163], v[204:207], v[52:55]
	v_mfma_f32_16x16x32_bf16 v[48:51], v[164:167], v[204:207], v[48:51]
	ds_read_b128 v[204:207], v226 offset:8192
	ds_read_b128 v[220:223], v226 offset:14336
	s_waitcnt lgkmcnt(11)
	v_mfma_f32_16x16x32_bf16 v[44:47], v[152:155], v[208:211], v[44:47]
	v_mfma_f32_16x16x32_bf16 v[40:43], v[156:159], v[208:211], v[40:43]
	v_mfma_f32_16x16x32_bf16 v[36:39], v[160:163], v[208:211], v[36:39]
	v_mfma_f32_16x16x32_bf16 v[32:35], v[164:167], v[208:211], v[32:35]
	ds_read_b128 v[208:211], v226 offset:10240
	s_waitcnt lgkmcnt(11)
	v_mfma_f32_16x16x32_bf16 v[28:31], v[152:155], v[212:215], v[28:31]
	v_mfma_f32_16x16x32_bf16 v[24:27], v[156:159], v[212:215], v[24:27]
	v_mfma_f32_16x16x32_bf16 v[20:23], v[160:163], v[212:215], v[20:23]
	v_mfma_f32_16x16x32_bf16 v[16:19], v[164:167], v[212:215], v[16:19]
	ds_read_b128 v[212:215], v226 offset:12288
	v_mfma_f32_16x16x32_bf16 v[12:15], v[152:155], v[216:219], v[12:15]
	v_mfma_f32_16x16x32_bf16 v[8:11], v[156:159], v[216:219], v[8:11]
	v_mfma_f32_16x16x32_bf16 v[4:7], v[160:163], v[216:219], v[4:7]
	v_mfma_f32_16x16x32_bf16 v[0:3], v[164:167], v[216:219], v[0:3]
	s_waitcnt vmcnt(0) lgkmcnt(0)
	s_barrier
	v_mfma_f32_16x16x32_bf16 v[124:127], v[168:171], v[188:191], v[124:127]
	v_mfma_f32_16x16x32_bf16 v[120:123], v[176:179], v[188:191], v[120:123]
	v_mfma_f32_16x16x32_bf16 v[116:119], v[180:183], v[188:191], v[116:119]
	v_mfma_f32_16x16x32_bf16 v[112:115], v[184:187], v[188:191], v[112:115]
	v_mfma_f32_16x16x32_bf16 v[108:111], v[168:171], v[192:195], v[108:111]
	v_mfma_f32_16x16x32_bf16 v[104:107], v[176:179], v[192:195], v[104:107]
	v_mfma_f32_16x16x32_bf16 v[100:103], v[180:183], v[192:195], v[100:103]
	v_mfma_f32_16x16x32_bf16 v[96:99], v[184:187], v[192:195], v[96:99]
	v_mfma_f32_16x16x32_bf16 v[92:95], v[168:171], v[196:199], v[92:95]
	v_mfma_f32_16x16x32_bf16 v[88:91], v[176:179], v[196:199], v[88:91]
	v_mfma_f32_16x16x32_bf16 v[84:87], v[180:183], v[196:199], v[84:87]
	v_mfma_f32_16x16x32_bf16 v[80:83], v[184:187], v[196:199], v[80:83]
	v_mfma_f32_16x16x32_bf16 v[76:79], v[168:171], v[200:203], v[76:79]
	v_mfma_f32_16x16x32_bf16 v[72:75], v[176:179], v[200:203], v[72:75]
	v_mfma_f32_16x16x32_bf16 v[68:71], v[180:183], v[200:203], v[68:71]
	v_mfma_f32_16x16x32_bf16 v[64:67], v[184:187], v[200:203], v[64:67]
	v_mfma_f32_16x16x32_bf16 v[60:63], v[168:171], v[204:207], v[60:63]
	v_mfma_f32_16x16x32_bf16 v[56:59], v[176:179], v[204:207], v[56:59]
	v_mfma_f32_16x16x32_bf16 v[52:55], v[180:183], v[204:207], v[52:55]
	v_mfma_f32_16x16x32_bf16 v[48:51], v[184:187], v[204:207], v[48:51]
	v_mfma_f32_16x16x32_bf16 v[44:47], v[168:171], v[208:211], v[44:47]
	v_mfma_f32_16x16x32_bf16 v[40:43], v[176:179], v[208:211], v[40:43]
	v_mfma_f32_16x16x32_bf16 v[36:39], v[180:183], v[208:211], v[36:39]
	v_mfma_f32_16x16x32_bf16 v[32:35], v[184:187], v[208:211], v[32:35]
	v_mfma_f32_16x16x32_bf16 v[28:31], v[168:171], v[212:215], v[28:31]
	v_mfma_f32_16x16x32_bf16 v[24:27], v[176:179], v[212:215], v[24:27]
	v_mfma_f32_16x16x32_bf16 v[20:23], v[180:183], v[212:215], v[20:23]
	v_mfma_f32_16x16x32_bf16 v[16:19], v[184:187], v[212:215], v[16:19]
	v_mfma_f32_16x16x32_bf16 v[12:15], v[168:171], v[220:223], v[12:15]
	v_mfma_f32_16x16x32_bf16 v[8:11], v[176:179], v[220:223], v[8:11]
	v_mfma_f32_16x16x32_bf16 v[4:7], v[180:183], v[220:223], v[4:7]
	v_mfma_f32_16x16x32_bf16 v[0:3], v[184:187], v[220:223], v[0:3]
	s_nop 7
	s_nop 3
	v_and_b32_e32 v225, 15, v174
	v_lshrrev_b32_e32 v226, 8, v174
	v_lshl_or_b32 v225, v226, 7, v225
	v_bfe_u32 v226, v174, 6, 2
	v_bfe_u32 v227, v174, 4, 2
	v_lshlrev_b32_e32 v227, 2, v227
	v_add_u32_e32 v225, s41, v225
	v_lshl_add_u32 v226, v226, 5, v227
	v_lshl_or_b32 v226, s40, 7, v226
	v_lshlrev_b32_e32 v226, 1, v226
	v_mov_b32_e32 v227, 0x1600
	v_mad_u32_u24 v224, v225, v227, v226
	v_mul_f32_e32 v188, 0xbfb8aa3b, v124
	v_mul_f32_e32 v189, 0xbfb8aa3b, v125
	v_mul_f32_e32 v190, 0xbfb8aa3b, v126
	v_mul_f32_e32 v191, 0xbfb8aa3b, v127
; DI u16 f2bf(float a) { return (u16)(pk2(a, 0.f) & 0xffffu); }
; DI float sigmoidf_(float x) { return __builtin_amdgcn_rcpf(1.f + __builtin_amdgcn_exp2f(-1.4426950408889634f * x)); }
; template <int EPI>
; DI void gemm_phase(const u16* __restrict__ A, int lda, const u16* __restrict__ Bt, int K, int N, u16* outb, int ldo,
;                    const float* r0, const float* r1, float* outf, char* lds, int bid, int nb) {
;     ...
;       const int col = (tn * 4 + wc) * 32 + l15;
; #pragma unroll
;       for (int i = 0; i < 8; ++i)
; #pragma unroll
;         for (int r = 0; r < 4; ++r) {
;           const float g0 = acc[i][0][r], u0 = acc[i][2][r], g1 = acc[i][1][r], u1 = acc[i][3][r];
;           u16* o0 = outb + (size_t)(mrow + i * 16 + r) * ldo + col;
;           o0[0] = f2bf(g0 * sigmoidf_(g0) * u0); o0[16] = f2bf(g1 * sigmoidf_(g1) * u1);
;         }
	v_exp_f32_e32 v188, v188
	v_exp_f32_e32 v189, v189
	v_exp_f32_e32 v190, v190
	v_exp_f32_e32 v191, v191
	v_add_f32_e32 v188, 1.0, v188
	v_add_f32_e32 v189, 1.0, v189
	v_add_f32_e32 v190, 1.0, v190
	v_add_f32_e32 v191, 1.0, v191
	v_rcp_f32_e32 v188, v188
	v_rcp_f32_e32 v189, v189
	v_rcp_f32_e32 v190, v190
	v_rcp_f32_e32 v191, v191
	v_mul_f32_e32 v188, v124, v188
	v_mul_f32_e32 v189, v125, v189
	v_mul_f32_e32 v190, v126, v190
	v_mul_f32_e32 v191, v127, v191
	v_mul_f32_e32 v188, v116, v188
	v_mul_f32_e32 v189, v117, v189
	v_mul_f32_e32 v190, v118, v190
	v_mul_f32_e32 v191, v119, v191
	v_cvt_pk_bf16_f32 v200, v188, v189
	v_cvt_pk_bf16_f32 v201, v190, v191
	global_store_dwordx2 v224, v[200:201], s[8:9] offset:0
	v_mul_f32_e32 v188, 0xbfb8aa3b, v120
	v_mul_f32_e32 v189, 0xbfb8aa3b, v121
	v_mul_f32_e32 v190, 0xbfb8aa3b, v122
	v_mul_f32_e32 v191, 0xbfb8aa3b, v123
	v_exp_f32_e32 v188, v188
	v_exp_f32_e32 v189, v189
	v_exp_f32_e32 v190, v190
	v_exp_f32_e32 v191, v191
	v_add_f32_e32 v188, 1.0, v188
	v_add_f32_e32 v189, 1.0, v189
	v_add_f32_e32 v190, 1.0, v190
	v_add_f32_e32 v191, 1.0, v191
	v_rcp_f32_e32 v188, v188
	v_rcp_f32_e32 v189, v189
	v_rcp_f32_e32 v190, v190
	v_rcp_f32_e32 v191, v191
	v_mul_f32_e32 v188, v120, v188
	v_mul_f32_e32 v189, v121, v189
	v_mul_f32_e32 v190, v122, v190
	v_mul_f32_e32 v191, v123, v191
	v_mul_f32_e32 v188, v112, v188
	v_mul_f32_e32 v189, v113, v189
	v_mul_f32_e32 v190, v114, v190
	v_mul_f32_e32 v191, v115, v191
	v_cvt_pk_bf16_f32 v202, v188, v189
	v_cvt_pk_bf16_f32 v203, v190, v191
	global_store_dwordx2 v224, v[202:203], s[8:9] offset:32
	v_add_u32_e32 v224, 0x16000, v224
	v_mul_f32_e32 v188, 0xbfb8aa3b, v108
	v_mul_f32_e32 v189, 0xbfb8aa3b, v109
	v_mul_f32_e32 v190, 0xbfb8aa3b, v110
	v_mul_f32_e32 v191, 0xbfb8aa3b, v111
	v_exp_f32_e32 v188, v188
	v_exp_f32_e32 v189, v189
	v_exp_f32_e32 v190, v190
	v_exp_f32_e32 v191, v191
	v_add_f32_e32 v188, 1.0, v188
	v_add_f32_e32 v189, 1.0, v189
	v_add_f32_e32 v190, 1.0, v190
	v_add_f32_e32 v191, 1.0, v191
	v_rcp_f32_e32 v188, v188
	v_rcp_f32_e32 v189, v189
	v_rcp_f32_e32 v190, v190
	v_rcp_f32_e32 v191, v191
	v_mul_f32_e32 v188, v108, v188
	v_mul_f32_e32 v189, v109, v189
	v_mul_f32_e32 v190, v110, v190
	v_mul_f32_e32 v191, v111, v191
	v_mul_f32_e32 v188, v100, v188
	v_mul_f32_e32 v189, v101, v189
	v_mul_f32_e32 v190, v102, v190
	v_mul_f32_e32 v191, v103, v191
	v_cvt_pk_bf16_f32 v204, v188, v189
	v_cvt_pk_bf16_f32 v205, v190, v191
	global_store_dwordx2 v224, v[204:205], s[8:9] offset:0
	v_mul_f32_e32 v188, 0xbfb8aa3b, v104
	v_mul_f32_e32 v189, 0xbfb8aa3b, v105
	v_mul_f32_e32 v190, 0xbfb8aa3b, v106
	v_mul_f32_e32 v191, 0xbfb8aa3b, v107
	v_exp_f32_e32 v188, v188
	v_exp_f32_e32 v189, v189
	v_exp_f32_e32 v190, v190
	v_exp_f32_e32 v191, v191
	v_add_f32_e32 v188, 1.0, v188
	v_add_f32_e32 v189, 1.0, v189
	v_add_f32_e32 v190, 1.0, v190
	v_add_f32_e32 v191, 1.0, v191
	v_rcp_f32_e32 v188, v188
	v_rcp_f32_e32 v189, v189
	v_rcp_f32_e32 v190, v190
	v_rcp_f32_e32 v191, v191
	v_mul_f32_e32 v188, v104, v188
	v_mul_f32_e32 v189, v105, v189
	v_mul_f32_e32 v190, v106, v190
	v_mul_f32_e32 v191, v107, v191
	v_mul_f32_e32 v188, v96, v188
	v_mul_f32_e32 v189, v97, v189
	v_mul_f32_e32 v190, v98, v190
	v_mul_f32_e32 v191, v99, v191
	v_cvt_pk_bf16_f32 v206, v188, v189
	v_cvt_pk_bf16_f32 v207, v190, v191
	global_store_dwordx2 v224, v[206:207], s[8:9] offset:32
	v_add_u32_e32 v224, 0x16000, v224
	v_mul_f32_e32 v188, 0xbfb8aa3b, v92
	v_mul_f32_e32 v189, 0xbfb8aa3b, v93
	v_mul_f32_e32 v190, 0xbfb8aa3b, v94
	v_mul_f32_e32 v191, 0xbfb8aa3b, v95
	v_exp_f32_e32 v188, v188
	v_exp_f32_e32 v189, v189
	v_exp_f32_e32 v190, v190
	v_exp_f32_e32 v191, v191
	v_add_f32_e32 v188, 1.0, v188
	v_add_f32_e32 v189, 1.0, v189
	v_add_f32_e32 v190, 1.0, v190
	v_add_f32_e32 v191, 1.0, v191
	v_rcp_f32_e32 v188, v188
	v_rcp_f32_e32 v189, v189
	v_rcp_f32_e32 v190, v190
	v_rcp_f32_e32 v191, v191
	v_mul_f32_e32 v188, v92, v188
	v_mul_f32_e32 v189, v93, v189
	v_mul_f32_e32 v190, v94, v190
	v_mul_f32_e32 v191, v95, v191
	v_mul_f32_e32 v188, v84, v188
	v_mul_f32_e32 v189, v85, v189
	v_mul_f32_e32 v190, v86, v190
	v_mul_f32_e32 v191, v87, v191
	v_cvt_pk_bf16_f32 v208, v188, v189
	v_cvt_pk_bf16_f32 v209, v190, v191
	global_store_dwordx2 v224, v[208:209], s[8:9] offset:0
	v_mul_f32_e32 v188, 0xbfb8aa3b, v88
	v_mul_f32_e32 v189, 0xbfb8aa3b, v89
	v_mul_f32_e32 v190, 0xbfb8aa3b, v90
	v_mul_f32_e32 v191, 0xbfb8aa3b, v91
	v_exp_f32_e32 v188, v188
	v_exp_f32_e32 v189, v189
	v_exp_f32_e32 v190, v190
	v_exp_f32_e32 v191, v191
	v_add_f32_e32 v188, 1.0, v188
	v_add_f32_e32 v189, 1.0, v189
	v_add_f32_e32 v190, 1.0, v190
	v_add_f32_e32 v191, 1.0, v191
	v_rcp_f32_e32 v188, v188
	v_rcp_f32_e32 v189, v189
	v_rcp_f32_e32 v190, v190
	v_rcp_f32_e32 v191, v191
	v_mul_f32_e32 v188, v88, v188
	v_mul_f32_e32 v189, v89, v189
	v_mul_f32_e32 v190, v90, v190
	v_mul_f32_e32 v191, v91, v191
	v_mul_f32_e32 v188, v80, v188
	v_mul_f32_e32 v189, v81, v189
	v_mul_f32_e32 v190, v82, v190
	v_mul_f32_e32 v191, v83, v191
	v_cvt_pk_bf16_f32 v210, v188, v189
	v_cvt_pk_bf16_f32 v211, v190, v191
	global_store_dwordx2 v224, v[210:211], s[8:9] offset:32
	v_add_u32_e32 v224, 0x16000, v224
	v_mul_f32_e32 v188, 0xbfb8aa3b, v76
	v_mul_f32_e32 v189, 0xbfb8aa3b, v77
	v_mul_f32_e32 v190, 0xbfb8aa3b, v78
	v_mul_f32_e32 v191, 0xbfb8aa3b, v79
	v_exp_f32_e32 v188, v188
	v_exp_f32_e32 v189, v189
	v_exp_f32_e32 v190, v190
	v_exp_f32_e32 v191, v191
	v_add_f32_e32 v188, 1.0, v188
	v_add_f32_e32 v189, 1.0, v189
	v_add_f32_e32 v190, 1.0, v190
	v_add_f32_e32 v191, 1.0, v191
	v_rcp_f32_e32 v188, v188
	v_rcp_f32_e32 v189, v189
	v_rcp_f32_e32 v190, v190
	v_rcp_f32_e32 v191, v191
	v_mul_f32_e32 v188, v76, v188
; DI u16 f2bf(float a) { return (u16)(pk2(a, 0.f) & 0xffffu); }
; DI float sigmoidf_(float x) { return __builtin_amdgcn_rcpf(1.f + __builtin_amdgcn_exp2f(-1.4426950408889634f * x)); }
; template <int EPI>
; DI void gemm_phase(const u16* __restrict__ A, int lda, const u16* __restrict__ Bt, int K, int N, u16* outb, int ldo,
;                    const float* r0, const float* r1, float* outf, char* lds, int bid, int nb) {
;     ...
;       const int col = (tn * 4 + wc) * 32 + l15;
; #pragma unroll
;       for (int i = 0; i < 8; ++i)
; #pragma unroll
;         for (int r = 0; r < 4; ++r) {
;           const float g0 = acc[i][0][r], u0 = acc[i][2][r], g1 = acc[i][1][r], u1 = acc[i][3][r];
;           u16* o0 = outb + (size_t)(mrow + i * 16 + r) * ldo + col;
;           o0[0] = f2bf(g0 * sigmoidf_(g0) * u0); o0[16] = f2bf(g1 * sigmoidf_(g1) * u1);
;         }
	v_mul_f32_e32 v189, v77, v189
	v_mul_f32_e32 v190, v78, v190
	v_mul_f32_e32 v191, v79, v191
	v_mul_f32_e32 v188, v68, v188
	v_mul_f32_e32 v189, v69, v189
	v_mul_f32_e32 v190, v70, v190
	v_mul_f32_e32 v191, v71, v191
	v_cvt_pk_bf16_f32 v212, v188, v189
	v_cvt_pk_bf16_f32 v213, v190, v191
	global_store_dwordx2 v224, v[212:213], s[8:9] offset:0
	v_mul_f32_e32 v188, 0xbfb8aa3b, v72
	v_mul_f32_e32 v189, 0xbfb8aa3b, v73
	v_mul_f32_e32 v190, 0xbfb8aa3b, v74
	v_mul_f32_e32 v191, 0xbfb8aa3b, v75
	v_exp_f32_e32 v188, v188
	v_exp_f32_e32 v189, v189
	v_exp_f32_e32 v190, v190
	v_exp_f32_e32 v191, v191
	v_add_f32_e32 v188, 1.0, v188
	v_add_f32_e32 v189, 1.0, v189
	v_add_f32_e32 v190, 1.0, v190
	v_add_f32_e32 v191, 1.0, v191
	v_rcp_f32_e32 v188, v188
	v_rcp_f32_e32 v189, v189
	v_rcp_f32_e32 v190, v190
	v_rcp_f32_e32 v191, v191
	v_mul_f32_e32 v188, v72, v188
	v_mul_f32_e32 v189, v73, v189
	v_mul_f32_e32 v190, v74, v190
	v_mul_f32_e32 v191, v75, v191
	v_mul_f32_e32 v188, v64, v188
	v_mul_f32_e32 v189, v65, v189
	v_mul_f32_e32 v190, v66, v190
	v_mul_f32_e32 v191, v67, v191
	v_cvt_pk_bf16_f32 v214, v188, v189
	v_cvt_pk_bf16_f32 v215, v190, v191
	global_store_dwordx2 v224, v[214:215], s[8:9] offset:32
	v_add_u32_e32 v224, 0x16000, v224
	v_mul_f32_e32 v188, 0xbfb8aa3b, v60
	v_mul_f32_e32 v189, 0xbfb8aa3b, v61
	v_mul_f32_e32 v190, 0xbfb8aa3b, v62
	v_mul_f32_e32 v191, 0xbfb8aa3b, v63
	v_exp_f32_e32 v188, v188
	v_exp_f32_e32 v189, v189
	v_exp_f32_e32 v190, v190
	v_exp_f32_e32 v191, v191
	v_add_f32_e32 v188, 1.0, v188
	v_add_f32_e32 v189, 1.0, v189
	v_add_f32_e32 v190, 1.0, v190
	v_add_f32_e32 v191, 1.0, v191
	v_rcp_f32_e32 v188, v188
	v_rcp_f32_e32 v189, v189
	v_rcp_f32_e32 v190, v190
	v_rcp_f32_e32 v191, v191
	v_mul_f32_e32 v188, v60, v188
	v_mul_f32_e32 v189, v61, v189
	v_mul_f32_e32 v190, v62, v190
	v_mul_f32_e32 v191, v63, v191
	v_mul_f32_e32 v188, v52, v188
	v_mul_f32_e32 v189, v53, v189
	v_mul_f32_e32 v190, v54, v190
	v_mul_f32_e32 v191, v55, v191
	v_cvt_pk_bf16_f32 v200, v188, v189
	v_cvt_pk_bf16_f32 v201, v190, v191
	global_store_dwordx2 v224, v[200:201], s[8:9] offset:0
	v_mul_f32_e32 v188, 0xbfb8aa3b, v56
	v_mul_f32_e32 v189, 0xbfb8aa3b, v57
	v_mul_f32_e32 v190, 0xbfb8aa3b, v58
	v_mul_f32_e32 v191, 0xbfb8aa3b, v59
	v_exp_f32_e32 v188, v188
	v_exp_f32_e32 v189, v189
	v_exp_f32_e32 v190, v190
	v_exp_f32_e32 v191, v191
	v_add_f32_e32 v188, 1.0, v188
	v_add_f32_e32 v189, 1.0, v189
	v_add_f32_e32 v190, 1.0, v190
	v_add_f32_e32 v191, 1.0, v191
	v_rcp_f32_e32 v188, v188
	v_rcp_f32_e32 v189, v189
	v_rcp_f32_e32 v190, v190
	v_rcp_f32_e32 v191, v191
	v_mul_f32_e32 v188, v56, v188
	v_mul_f32_e32 v189, v57, v189
	v_mul_f32_e32 v190, v58, v190
	v_mul_f32_e32 v191, v59, v191
	v_mul_f32_e32 v188, v48, v188
	v_mul_f32_e32 v189, v49, v189
	v_mul_f32_e32 v190, v50, v190
	v_mul_f32_e32 v191, v51, v191
	v_cvt_pk_bf16_f32 v202, v188, v189
	v_cvt_pk_bf16_f32 v203, v190, v191
	global_store_dwordx2 v224, v[202:203], s[8:9] offset:32
	v_add_u32_e32 v224, 0x16000, v224
	v_mul_f32_e32 v188, 0xbfb8aa3b, v44
	v_mul_f32_e32 v189, 0xbfb8aa3b, v45
	v_mul_f32_e32 v190, 0xbfb8aa3b, v46
	v_mul_f32_e32 v191, 0xbfb8aa3b, v47
	v_exp_f32_e32 v188, v188
	v_exp_f32_e32 v189, v189
	v_exp_f32_e32 v190, v190
	v_exp_f32_e32 v191, v191
	v_add_f32_e32 v188, 1.0, v188
	v_add_f32_e32 v189, 1.0, v189
	v_add_f32_e32 v190, 1.0, v190
	v_add_f32_e32 v191, 1.0, v191
	v_rcp_f32_e32 v188, v188
	v_rcp_f32_e32 v189, v189
	v_rcp_f32_e32 v190, v190
	v_rcp_f32_e32 v191, v191
	v_mul_f32_e32 v188, v44, v188
	v_mul_f32_e32 v189, v45, v189
	v_mul_f32_e32 v190, v46, v190
	v_mul_f32_e32 v191, v47, v191
	v_mul_f32_e32 v188, v36, v188
	v_mul_f32_e32 v189, v37, v189
	v_mul_f32_e32 v190, v38, v190
	v_mul_f32_e32 v191, v39, v191
	v_cvt_pk_bf16_f32 v204, v188, v189
	v_cvt_pk_bf16_f32 v205, v190, v191
	global_store_dwordx2 v224, v[204:205], s[8:9] offset:0
	v_mul_f32_e32 v188, 0xbfb8aa3b, v40
	v_mul_f32_e32 v189, 0xbfb8aa3b, v41
	v_mul_f32_e32 v190, 0xbfb8aa3b, v42
	v_mul_f32_e32 v191, 0xbfb8aa3b, v43
	v_exp_f32_e32 v188, v188
	v_exp_f32_e32 v189, v189
	v_exp_f32_e32 v190, v190
	v_exp_f32_e32 v191, v191
	v_add_f32_e32 v188, 1.0, v188
; DI u16 f2bf(float a) { return (u16)(pk2(a, 0.f) & 0xffffu); }
; DI float sigmoidf_(float x) { return __builtin_amdgcn_rcpf(1.f + __builtin_amdgcn_exp2f(-1.4426950408889634f * x)); }
; template <int EPI>
; DI void gemm_phase(const u16* __restrict__ A, int lda, const u16* __restrict__ Bt, int K, int N, u16* outb, int ldo,
;                    const float* r0, const float* r1, float* outf, char* lds, int bid, int nb) {
;     ...
;       const int col = (tn * 4 + wc) * 32 + l15;
; #pragma unroll
;       for (int i = 0; i < 8; ++i)
; #pragma unroll
;         for (int r = 0; r < 4; ++r) {
;           const float g0 = acc[i][0][r], u0 = acc[i][2][r], g1 = acc[i][1][r], u1 = acc[i][3][r];
;           u16* o0 = outb + (size_t)(mrow + i * 16 + r) * ldo + col;
;           o0[0] = f2bf(g0 * sigmoidf_(g0) * u0); o0[16] = f2bf(g1 * sigmoidf_(g1) * u1);
;         }
	v_add_f32_e32 v189, 1.0, v189
	v_add_f32_e32 v190, 1.0, v190
	v_add_f32_e32 v191, 1.0, v191
	v_rcp_f32_e32 v188, v188
	v_rcp_f32_e32 v189, v189
	v_rcp_f32_e32 v190, v190
	v_rcp_f32_e32 v191, v191
	v_mul_f32_e32 v188, v40, v188
	v_mul_f32_e32 v189, v41, v189
	v_mul_f32_e32 v190, v42, v190
	v_mul_f32_e32 v191, v43, v191
	v_mul_f32_e32 v188, v32, v188
	v_mul_f32_e32 v189, v33, v189
	v_mul_f32_e32 v190, v34, v190
	v_mul_f32_e32 v191, v35, v191
	v_cvt_pk_bf16_f32 v206, v188, v189
	v_cvt_pk_bf16_f32 v207, v190, v191
	global_store_dwordx2 v224, v[206:207], s[8:9] offset:32
	v_add_u32_e32 v224, 0x16000, v224
	v_mul_f32_e32 v188, 0xbfb8aa3b, v28
	v_mul_f32_e32 v189, 0xbfb8aa3b, v29
	v_mul_f32_e32 v190, 0xbfb8aa3b, v30
	v_mul_f32_e32 v191, 0xbfb8aa3b, v31
	v_exp_f32_e32 v188, v188
	v_exp_f32_e32 v189, v189
	v_exp_f32_e32 v190, v190
	v_exp_f32_e32 v191, v191
	v_add_f32_e32 v188, 1.0, v188
	v_add_f32_e32 v189, 1.0, v189
	v_add_f32_e32 v190, 1.0, v190
	v_add_f32_e32 v191, 1.0, v191
	v_rcp_f32_e32 v188, v188
	v_rcp_f32_e32 v189, v189
	v_rcp_f32_e32 v190, v190
	v_rcp_f32_e32 v191, v191
	v_mul_f32_e32 v188, v28, v188
	v_mul_f32_e32 v189, v29, v189
	v_mul_f32_e32 v190, v30, v190
	v_mul_f32_e32 v191, v31, v191
	v_mul_f32_e32 v188, v20, v188
	v_mul_f32_e32 v189, v21, v189
	v_mul_f32_e32 v190, v22, v190
	v_mul_f32_e32 v191, v23, v191
	v_cvt_pk_bf16_f32 v208, v188, v189
	v_cvt_pk_bf16_f32 v209, v190, v191
	global_store_dwordx2 v224, v[208:209], s[8:9] offset:0
	v_mul_f32_e32 v188, 0xbfb8aa3b, v24
	v_mul_f32_e32 v189, 0xbfb8aa3b, v25
	v_mul_f32_e32 v190, 0xbfb8aa3b, v26
	v_mul_f32_e32 v191, 0xbfb8aa3b, v27
	v_exp_f32_e32 v188, v188
	v_exp_f32_e32 v189, v189
	v_exp_f32_e32 v190, v190
	v_exp_f32_e32 v191, v191
	v_add_f32_e32 v188, 1.0, v188
	v_add_f32_e32 v189, 1.0, v189
	v_add_f32_e32 v190, 1.0, v190
	v_add_f32_e32 v191, 1.0, v191
	v_rcp_f32_e32 v188, v188
	v_rcp_f32_e32 v189, v189
	v_rcp_f32_e32 v190, v190
	v_rcp_f32_e32 v191, v191
	v_mul_f32_e32 v188, v24, v188
	v_mul_f32_e32 v189, v25, v189
	v_mul_f32_e32 v190, v26, v190
	v_mul_f32_e32 v191, v27, v191
	v_mul_f32_e32 v188, v16, v188
	v_mul_f32_e32 v189, v17, v189
	v_mul_f32_e32 v190, v18, v190
	v_mul_f32_e32 v191, v19, v191
	v_cvt_pk_bf16_f32 v210, v188, v189
	v_cvt_pk_bf16_f32 v211, v190, v191
	global_store_dwordx2 v224, v[210:211], s[8:9] offset:32
	v_add_u32_e32 v224, 0x16000, v224
	v_mul_f32_e32 v188, 0xbfb8aa3b, v12
	v_mul_f32_e32 v189, 0xbfb8aa3b, v13
	v_mul_f32_e32 v190, 0xbfb8aa3b, v14
	v_mul_f32_e32 v191, 0xbfb8aa3b, v15
	v_exp_f32_e32 v188, v188
	v_exp_f32_e32 v189, v189
	v_exp_f32_e32 v190, v190
	v_exp_f32_e32 v191, v191
	v_add_f32_e32 v188, 1.0, v188
	v_add_f32_e32 v189, 1.0, v189
	v_add_f32_e32 v190, 1.0, v190
	v_add_f32_e32 v191, 1.0, v191
	v_rcp_f32_e32 v188, v188
	v_rcp_f32_e32 v189, v189
	v_rcp_f32_e32 v190, v190
	v_rcp_f32_e32 v191, v191
	v_mul_f32_e32 v188, v12, v188
	v_mul_f32_e32 v189, v13, v189
	v_mul_f32_e32 v190, v14, v190
	v_mul_f32_e32 v191, v15, v191
	v_mul_f32_e32 v188, v4, v188
	v_mul_f32_e32 v189, v5, v189
	v_mul_f32_e32 v190, v6, v190
	v_mul_f32_e32 v191, v7, v191
	v_cvt_pk_bf16_f32 v212, v188, v189
	v_cvt_pk_bf16_f32 v213, v190, v191
	global_store_dwordx2 v224, v[212:213], s[8:9] offset:0
	v_mul_f32_e32 v188, 0xbfb8aa3b, v8
	v_mul_f32_e32 v189, 0xbfb8aa3b, v9
	v_mul_f32_e32 v190, 0xbfb8aa3b, v10
	v_mul_f32_e32 v191, 0xbfb8aa3b, v11
	v_exp_f32_e32 v188, v188
	v_exp_f32_e32 v189, v189
	v_exp_f32_e32 v190, v190
	v_exp_f32_e32 v191, v191
	v_add_f32_e32 v188, 1.0, v188
	v_add_f32_e32 v189, 1.0, v189
	v_add_f32_e32 v190, 1.0, v190
	v_add_f32_e32 v191, 1.0, v191
	v_rcp_f32_e32 v188, v188
	v_rcp_f32_e32 v189, v189
	v_rcp_f32_e32 v190, v190
	v_rcp_f32_e32 v191, v191
	v_mul_f32_e32 v188, v8, v188
	v_mul_f32_e32 v189, v9, v189
	v_mul_f32_e32 v190, v10, v190
	v_mul_f32_e32 v191, v11, v191
	v_mul_f32_e32 v188, v0, v188
	v_mul_f32_e32 v189, v1, v189
	v_mul_f32_e32 v190, v2, v190
	v_mul_f32_e32 v191, v3, v191
	v_cvt_pk_bf16_f32 v214, v188, v189
	v_cvt_pk_bf16_f32 v215, v190, v191
	global_store_dwordx2 v224, v[214:215], s[8:9] offset:32
	s_add_i32 s17, s17, 1
	s_cmp_eq_u32 s17, s3
	s_cbranch_scc0 .LBB0_1297

; #define G_LOAD(KT) do { _Pragma("unroll") for (int i = 0; i < 4; ++i) { ra[i] = *(const u32x4*)(Ag + (size_t)i * 64 * lda + (KT) * 64); rb[i] = *(const u32x4*)(Bg + (size_t)i * 64 * K + (KT) * 64); } } while (0)
; #define G_STORE(BUF) do { u16* ad = As + (BUF) * 256 * 64 + sto; u16* bd = Bs + (BUF) * 256 * 64 + sto; _Pragma("unroll") for (int i = 0; i < 4; ++i) { *(u32x4*)(ad + i * 64 * 64) = ra[i]; *(u32x4*)(bd + i * 64 * 64) = rb[i]; } } while (0)
; template <int EPI>
; DI void gemm_phase(const u16* __restrict__ A, int lda, const u16* __restrict__ Bt, int K, int N, u16* outb, int ldo,
;                    const float* r0, const float* r1, float* outf, char* lds, int bid, int nb) {
;     ...
;     G_LOAD(0);
;     G_STORE(0);
;     __syncthreads();
;     for (int kt = 0; kt < nk; ++kt) {
;       const int cur = kt & 1;
;       if (kt + 1 < nk) G_LOAD(kt + 1);
;       G_MMA(cur, fo0);
;       G_MMA(cur, fo1);
;       if (kt + 1 < nk) G_STORE(cur ^ 1);
;       __syncthreads();
;     }
.Lgm7_loop:
	s_waitcnt lgkmcnt(4)
	v_mfma_f32_16x16x32_bf16 v[124:127], v[152:155], v[188:191], v[124:127]
	v_mfma_f32_16x16x32_bf16 v[120:123], v[156:159], v[188:191], v[120:123]
	v_mfma_f32_16x16x32_bf16 v[116:119], v[160:163], v[188:191], v[116:119]
	v_mfma_f32_16x16x32_bf16 v[112:115], v[164:167], v[188:191], v[112:115]
	ds_read_b128 v[188:191], v226 offset:0
	ds_read_b128 v[168:171], v228 offset:0
	v_mfma_f32_16x16x32_bf16 v[108:111], v[152:155], v[192:195], v[108:111]
	v_mfma_f32_16x16x32_bf16 v[104:107], v[156:159], v[192:195], v[104:107]
	v_mfma_f32_16x16x32_bf16 v[100:103], v[160:163], v[192:195], v[100:103]
	v_mfma_f32_16x16x32_bf16 v[96:99], v[164:167], v[192:195], v[96:99]
	ds_read_b128 v[192:195], v226 offset:2048
	ds_read_b128 v[176:179], v228 offset:2048
	v_mfma_f32_16x16x32_bf16 v[92:95], v[152:155], v[196:199], v[92:95]
	v_mfma_f32_16x16x32_bf16 v[88:91], v[156:159], v[196:199], v[88:91]
	v_mfma_f32_16x16x32_bf16 v[84:87], v[160:163], v[196:199], v[84:87]
	v_mfma_f32_16x16x32_bf16 v[80:83], v[164:167], v[196:199], v[80:83]
	ds_read_b128 v[196:199], v226 offset:4096
	ds_read_b128 v[180:183], v228 offset:4096
	v_mfma_f32_16x16x32_bf16 v[76:79], v[152:155], v[200:203], v[76:79]
	v_mfma_f32_16x16x32_bf16 v[72:75], v[156:159], v[200:203], v[72:75]
	v_mfma_f32_16x16x32_bf16 v[68:71], v[160:163], v[200:203], v[68:71]
	v_mfma_f32_16x16x32_bf16 v[64:67], v[164:167], v[200:203], v[64:67]
	ds_read_b128 v[200:203], v226 offset:6144
	ds_read_b128 v[184:187], v228 offset:6144
	s_waitcnt lgkmcnt(11)
	v_mfma_f32_16x16x32_bf16 v[60:63], v[152:155], v[204:207], v[60:63]
	v_mfma_f32_16x16x32_bf16 v[56:59], v[156:159], v[204:207], v[56:59]
	v_mfma_f32_16x16x32_bf16 v[52:55], v[160:163], v[204:207], v[52:55]
	v_mfma_f32_16x16x32_bf16 v[48:51], v[164:167], v[204:207], v[48:51]
	ds_read_b128 v[204:207], v226 offset:8192
	ds_read_b128 v[220:223], v226 offset:14336
	s_waitcnt lgkmcnt(11)
	v_mfma_f32_16x16x32_bf16 v[44:47], v[152:155], v[208:211], v[44:47]
	v_mfma_f32_16x16x32_bf16 v[40:43], v[156:159], v[208:211], v[40:43]
	v_mfma_f32_16x16x32_bf16 v[36:39], v[160:163], v[208:211], v[36:39]
	v_mfma_f32_16x16x32_bf16 v[32:35], v[164:167], v[208:211], v[32:35]
	ds_read_b128 v[208:211], v226 offset:10240
	s_waitcnt lgkmcnt(11)
	v_mfma_f32_16x16x32_bf16 v[28:31], v[152:155], v[212:215], v[28:31]
	v_mfma_f32_16x16x32_bf16 v[24:27], v[156:159], v[212:215], v[24:27]
	v_mfma_f32_16x16x32_bf16 v[20:23], v[160:163], v[212:215], v[20:23]
	v_mfma_f32_16x16x32_bf16 v[16:19], v[164:167], v[212:215], v[16:19]
	ds_read_b128 v[212:215], v226 offset:12288
	v_mfma_f32_16x16x32_bf16 v[12:15], v[152:155], v[216:219], v[12:15]
	v_mfma_f32_16x16x32_bf16 v[8:11], v[156:159], v[216:219], v[8:11]
	v_mfma_f32_16x16x32_bf16 v[4:7], v[160:163], v[216:219], v[4:7]
	v_mfma_f32_16x16x32_bf16 v[0:3], v[164:167], v[216:219], v[0:3]
	s_waitcnt vmcnt(0) lgkmcnt(0)
	s_barrier
	v_mfma_f32_16x16x32_bf16 v[124:127], v[168:171], v[188:191], v[124:127]
	v_mfma_f32_16x16x32_bf16 v[120:123], v[176:179], v[188:191], v[120:123]
	v_mfma_f32_16x16x32_bf16 v[116:119], v[180:183], v[188:191], v[116:119]
	v_mfma_f32_16x16x32_bf16 v[112:115], v[184:187], v[188:191], v[112:115]
	ds_read_b128 v[188:191], v225 offset:0
	ds_read_b128 v[152:155], v227 offset:0
	s_add_u32 s8, s98, 0x0
	s_addc_u32 s9, s99, 0
	s_add_u32 m0, s97, 0x0
	s_nop 0
	global_load_lds_dwordx4 v224, s[8:9]
	v_mfma_f32_16x16x32_bf16 v[108:111], v[168:171], v[192:195], v[108:111]
	v_mfma_f32_16x16x32_bf16 v[104:107], v[176:179], v[192:195], v[104:107]
	v_mfma_f32_16x16x32_bf16 v[100:103], v[180:183], v[192:195], v[100:103]
	v_mfma_f32_16x16x32_bf16 v[96:99], v[184:187], v[192:195], v[96:99]
	ds_read_b128 v[192:195], v225 offset:2048
	ds_read_b128 v[156:159], v227 offset:2048
	s_add_u32 s8, s100, 0x0
	s_addc_u32 s9, s101, 0
	s_add_u32 m0, s97, 0x10000
	s_nop 0
	global_load_lds_dwordx4 v224, s[8:9]
	v_mfma_f32_16x16x32_bf16 v[92:95], v[168:171], v[196:199], v[92:95]
	v_mfma_f32_16x16x32_bf16 v[88:91], v[176:179], v[196:199], v[88:91]
	v_mfma_f32_16x16x32_bf16 v[84:87], v[180:183], v[196:199], v[84:87]
	v_mfma_f32_16x16x32_bf16 v[80:83], v[184:187], v[196:199], v[80:83]
	ds_read_b128 v[196:199], v225 offset:4096
	ds_read_b128 v[160:163], v227 offset:4096
	s_add_u32 s8, s98, 0x58000
	s_addc_u32 s9, s99, 0
	s_add_u32 m0, s97, 0x2000
	s_nop 0
	global_load_lds_dwordx4 v224, s[8:9]
	v_mfma_f32_16x16x32_bf16 v[76:79], v[168:171], v[200:203], v[76:79]
	v_mfma_f32_16x16x32_bf16 v[72:75], v[176:179], v[200:203], v[72:75]
	v_mfma_f32_16x16x32_bf16 v[68:71], v[180:183], v[200:203], v[68:71]
	v_mfma_f32_16x16x32_bf16 v[64:67], v[184:187], v[200:203], v[64:67]
	ds_read_b128 v[200:203], v225 offset:6144
	ds_read_b128 v[164:167], v227 offset:6144
	s_add_u32 s8, s100, 0x58000
	s_addc_u32 s9, s101, 0
	s_add_u32 m0, s97, 0x12000
	s_nop 0
	global_load_lds_dwordx4 v224, s[8:9]
	v_mfma_f32_16x16x32_bf16 v[60:63], v[168:171], v[204:207], v[60:63]
	v_mfma_f32_16x16x32_bf16 v[56:59], v[176:179], v[204:207], v[56:59]
	v_mfma_f32_16x16x32_bf16 v[52:55], v[180:183], v[204:207], v[52:55]
	v_mfma_f32_16x16x32_bf16 v[48:51], v[184:187], v[204:207], v[48:51]
	ds_read_b128 v[204:207], v225 offset:8192
	ds_read_b128 v[216:219], v225 offset:14336
	s_add_u32 s8, s98, 0xb0000
	s_addc_u32 s9, s99, 0
	s_add_u32 m0, s97, 0x4000
	s_nop 0
	global_load_lds_dwordx4 v224, s[8:9]
	v_mfma_f32_16x16x32_bf16 v[44:47], v[168:171], v[208:211], v[44:47]
	v_mfma_f32_16x16x32_bf16 v[40:43], v[176:179], v[208:211], v[40:43]
	v_mfma_f32_16x16x32_bf16 v[36:39], v[180:183], v[208:211], v[36:39]
	v_mfma_f32_16x16x32_bf16 v[32:35], v[184:187], v[208:211], v[32:35]
	ds_read_b128 v[208:211], v225 offset:10240
	s_add_u32 s8, s100, 0xb0000
	s_addc_u32 s9, s101, 0
	s_add_u32 m0, s97, 0x14000
	s_nop 0
	global_load_lds_dwordx4 v224, s[8:9]
	v_mfma_f32_16x16x32_bf16 v[28:31], v[168:171], v[212:215], v[28:31]
	v_mfma_f32_16x16x32_bf16 v[24:27], v[176:179], v[212:215], v[24:27]
	v_mfma_f32_16x16x32_bf16 v[20:23], v[180:183], v[212:215], v[20:23]
	v_mfma_f32_16x16x32_bf16 v[16:19], v[184:187], v[212:215], v[16:19]
	ds_read_b128 v[212:215], v225 offset:12288
	s_add_u32 s8, s98, 0x108000
	s_addc_u32 s9, s99, 0
	s_add_u32 m0, s97, 0x6000
	s_nop 0
	global_load_lds_dwordx4 v224, s[8:9]
	v_mfma_f32_16x16x32_bf16 v[12:15], v[168:171], v[220:223], v[12:15]
	v_mfma_f32_16x16x32_bf16 v[8:11], v[176:179], v[220:223], v[8:11]
	v_mfma_f32_16x16x32_bf16 v[4:7], v[180:183], v[220:223], v[4:7]
	v_mfma_f32_16x16x32_bf16 v[0:3], v[184:187], v[220:223], v[0:3]
	s_add_u32 s8, s100, 0x108000
	s_addc_u32 s9, s101, 0
	s_add_u32 m0, s97, 0x16000
	s_nop 0
	global_load_lds_dwordx4 v224, s[8:9]
	v_xor_b32_e32 v225, 0x8000, v225
	v_xor_b32_e32 v227, 0x8000, v227
	v_xor_b32_e32 v226, 0x8000, v226
	v_xor_b32_e32 v228, 0x8000, v228
	s_xor_b32 s97, s97, 0x8000
	s_add_u32 s98, s98, 0x80
	s_addc_u32 s99, s99, 0
	s_add_u32 s100, s100, 0x80
	s_addc_u32 s101, s101, 0
	s_sub_u32 s28, s28, 1
	s_cmp_lg_u32 s28, 0
	s_cbranch_scc1 .Lgm7_loop
; #define G_LOAD(KT) do { _Pragma("unroll") for (int i = 0; i < 4; ++i) { ra[i] = *(const u32x4*)(Ag + (size_t)i * 64 * lda + (KT) * 64); rb[i] = *(const u32x4*)(Bg + (size_t)i * 64 * K + (KT) * 64); } } while (0)
; #define G_STORE(BUF) do { u16* ad = As + (BUF) * 256 * 64 + sto; u16* bd = Bs + (BUF) * 256 * 64 + sto; _Pragma("unroll") for (int i = 0; i < 4; ++i) { *(u32x4*)(ad + i * 64 * 64) = ra[i]; *(u32x4*)(bd + i * 64 * 64) = rb[i]; } } while (0)
; template <int EPI>
; DI void gemm_phase(const u16* __restrict__ A, int lda, const u16* __restrict__ Bt, int K, int N, u16* outb, int ldo,
;                    const float* r0, const float* r1, float* outf, char* lds, int bid, int nb) {
;     ...
;     G_LOAD(0);
;     G_STORE(0);
;     __syncthreads();
;     for (int kt = 0; kt < nk; ++kt) {
;       const int cur = kt & 1;
;       if (kt + 1 < nk) G_LOAD(kt + 1);
;       G_MMA(cur, fo0);
;       G_MMA(cur, fo1);
;       if (kt + 1 < nk) G_STORE(cur ^ 1);
;       __syncthreads();
	s_waitcnt lgkmcnt(4)
	v_mfma_f32_16x16x32_bf16 v[124:127], v[152:155], v[188:191], v[124:127]
	v_mfma_f32_16x16x32_bf16 v[120:123], v[156:159], v[188:191], v[120:123]
	v_mfma_f32_16x16x32_bf16 v[116:119], v[160:163], v[188:191], v[116:119]
	v_mfma_f32_16x16x32_bf16 v[112:115], v[164:167], v[188:191], v[112:115]
	ds_read_b128 v[188:191], v226 offset:0
	ds_read_b128 v[168:171], v228 offset:0
	v_mfma_f32_16x16x32_bf16 v[108:111], v[152:155], v[192:195], v[108:111]
	v_mfma_f32_16x16x32_bf16 v[104:107], v[156:159], v[192:195], v[104:107]
	v_mfma_f32_16x16x32_bf16 v[100:103], v[160:163], v[192:195], v[100:103]
	v_mfma_f32_16x16x32_bf16 v[96:99], v[164:167], v[192:195], v[96:99]
	ds_read_b128 v[192:195], v226 offset:2048
	ds_read_b128 v[176:179], v228 offset:2048
	v_mfma_f32_16x16x32_bf16 v[92:95], v[152:155], v[196:199], v[92:95]
	v_mfma_f32_16x16x32_bf16 v[88:91], v[156:159], v[196:199], v[88:91]
	v_mfma_f32_16x16x32_bf16 v[84:87], v[160:163], v[196:199], v[84:87]
	v_mfma_f32_16x16x32_bf16 v[80:83], v[164:167], v[196:199], v[80:83]
	ds_read_b128 v[196:199], v226 offset:4096
	ds_read_b128 v[180:183], v228 offset:4096
	v_mfma_f32_16x16x32_bf16 v[76:79], v[152:155], v[200:203], v[76:79]
	v_mfma_f32_16x16x32_bf16 v[72:75], v[156:159], v[200:203], v[72:75]
	v_mfma_f32_16x16x32_bf16 v[68:71], v[160:163], v[200:203], v[68:71]
	v_mfma_f32_16x16x32_bf16 v[64:67], v[164:167], v[200:203], v[64:67]
	ds_read_b128 v[200:203], v226 offset:6144
	ds_read_b128 v[184:187], v228 offset:6144
	s_waitcnt lgkmcnt(11)
	v_mfma_f32_16x16x32_bf16 v[60:63], v[152:155], v[204:207], v[60:63]
	v_mfma_f32_16x16x32_bf16 v[56:59], v[156:159], v[204:207], v[56:59]
	v_mfma_f32_16x16x32_bf16 v[52:55], v[160:163], v[204:207], v[52:55]
	v_mfma_f32_16x16x32_bf16 v[48:51], v[164:167], v[204:207], v[48:51]
	ds_read_b128 v[204:207], v226 offset:8192
	ds_read_b128 v[220:223], v226 offset:14336
	s_waitcnt lgkmcnt(11)
	v_mfma_f32_16x16x32_bf16 v[44:47], v[152:155], v[208:211], v[44:47]
	v_mfma_f32_16x16x32_bf16 v[40:43], v[156:159], v[208:211], v[40:43]
	v_mfma_f32_16x16x32_bf16 v[36:39], v[160:163], v[208:211], v[36:39]
	v_mfma_f32_16x16x32_bf16 v[32:35], v[164:167], v[208:211], v[32:35]
	ds_read_b128 v[208:211], v226 offset:10240
	s_waitcnt lgkmcnt(11)
	v_mfma_f32_16x16x32_bf16 v[28:31], v[152:155], v[212:215], v[28:31]
	v_mfma_f32_16x16x32_bf16 v[24:27], v[156:159], v[212:215], v[24:27]
	v_mfma_f32_16x16x32_bf16 v[20:23], v[160:163], v[212:215], v[20:23]
	v_mfma_f32_16x16x32_bf16 v[16:19], v[164:167], v[212:215], v[16:19]
	ds_read_b128 v[212:215], v226 offset:12288
	v_mfma_f32_16x16x32_bf16 v[12:15], v[152:155], v[216:219], v[12:15]
	v_mfma_f32_16x16x32_bf16 v[8:11], v[156:159], v[216:219], v[8:11]
	v_mfma_f32_16x16x32_bf16 v[4:7], v[160:163], v[216:219], v[4:7]
	v_mfma_f32_16x16x32_bf16 v[0:3], v[164:167], v[216:219], v[0:3]
	s_waitcnt vmcnt(0) lgkmcnt(0)
	s_barrier
	v_mfma_f32_16x16x32_bf16 v[124:127], v[168:171], v[188:191], v[124:127]
	v_mfma_f32_16x16x32_bf16 v[120:123], v[176:179], v[188:191], v[120:123]
	v_mfma_f32_16x16x32_bf16 v[116:119], v[180:183], v[188:191], v[116:119]
	v_mfma_f32_16x16x32_bf16 v[112:115], v[184:187], v[188:191], v[112:115]
	ds_read_b128 v[188:191], v225 offset:0
	ds_read_b128 v[152:155], v227 offset:0
	v_mfma_f32_16x16x32_bf16 v[108:111], v[168:171], v[192:195], v[108:111]
	v_mfma_f32_16x16x32_bf16 v[104:107], v[176:179], v[192:195], v[104:107]
	v_mfma_f32_16x16x32_bf16 v[100:103], v[180:183], v[192:195], v[100:103]
	v_mfma_f32_16x16x32_bf16 v[96:99], v[184:187], v[192:195], v[96:99]
	ds_read_b128 v[192:195], v225 offset:2048
	ds_read_b128 v[156:159], v227 offset:2048
	v_mfma_f32_16x16x32_bf16 v[92:95], v[168:171], v[196:199], v[92:95]
	v_mfma_f32_16x16x32_bf16 v[88:91], v[176:179], v[196:199], v[88:91]
	v_mfma_f32_16x16x32_bf16 v[84:87], v[180:183], v[196:199], v[84:87]
	v_mfma_f32_16x16x32_bf16 v[80:83], v[184:187], v[196:199], v[80:83]
	ds_read_b128 v[196:199], v225 offset:4096
	ds_read_b128 v[160:163], v227 offset:4096
	v_mfma_f32_16x16x32_bf16 v[76:79], v[168:171], v[200:203], v[76:79]
	v_mfma_f32_16x16x32_bf16 v[72:75], v[176:179], v[200:203], v[72:75]
	v_mfma_f32_16x16x32_bf16 v[68:71], v[180:183], v[200:203], v[68:71]
	v_mfma_f32_16x16x32_bf16 v[64:67], v[184:187], v[200:203], v[64:67]
	ds_read_b128 v[200:203], v225 offset:6144
	ds_read_b128 v[164:167], v227 offset:6144
	v_mfma_f32_16x16x32_bf16 v[60:63], v[168:171], v[204:207], v[60:63]
	v_mfma_f32_16x16x32_bf16 v[56:59], v[176:179], v[204:207], v[56:59]
	v_mfma_f32_16x16x32_bf16 v[52:55], v[180:183], v[204:207], v[52:55]
	v_mfma_f32_16x16x32_bf16 v[48:51], v[184:187], v[204:207], v[48:51]
	ds_read_b128 v[204:207], v225 offset:8192
	ds_read_b128 v[216:219], v225 offset:14336
	v_mfma_f32_16x16x32_bf16 v[44:47], v[168:171], v[208:211], v[44:47]
	v_mfma_f32_16x16x32_bf16 v[40:43], v[176:179], v[208:211], v[40:43]
	v_mfma_f32_16x16x32_bf16 v[36:39], v[180:183], v[208:211], v[36:39]
	v_mfma_f32_16x16x32_bf16 v[32:35], v[184:187], v[208:211], v[32:35]
	ds_read_b128 v[208:211], v225 offset:10240
	v_mfma_f32_16x16x32_bf16 v[28:31], v[168:171], v[212:215], v[28:31]
	v_mfma_f32_16x16x32_bf16 v[24:27], v[176:179], v[212:215], v[24:27]
	v_mfma_f32_16x16x32_bf16 v[20:23], v[180:183], v[212:215], v[20:23]
	v_mfma_f32_16x16x32_bf16 v[16:19], v[184:187], v[212:215], v[16:19]
	ds_read_b128 v[212:215], v225 offset:12288
	v_mfma_f32_16x16x32_bf16 v[12:15], v[168:171], v[220:223], v[12:15]
	v_mfma_f32_16x16x32_bf16 v[8:11], v[176:179], v[220:223], v[8:11]
	v_mfma_f32_16x16x32_bf16 v[4:7], v[180:183], v[220:223], v[4:7]
	v_mfma_f32_16x16x32_bf16 v[0:3], v[184:187], v[220:223], v[0:3]
	v_xor_b32_e32 v226, 0x8000, v226
	v_xor_b32_e32 v228, 0x8000, v228
	s_waitcnt lgkmcnt(4)
; #define G_LOAD(KT) do { _Pragma("unroll") for (int i = 0; i < 4; ++i) { ra[i] = *(const u32x4*)(Ag + (size_t)i * 64 * lda + (KT) * 64); rb[i] = *(const u32x4*)(Bg + (size_t)i * 64 * K + (KT) * 64); } } while (0)
; #define G_STORE(BUF) do { u16* ad = As + (BUF) * 256 * 64 + sto; u16* bd = Bs + (BUF) * 256 * 64 + sto; _Pragma("unroll") for (int i = 0; i < 4; ++i) { *(u32x4*)(ad + i * 64 * 64) = ra[i]; *(u32x4*)(bd + i * 64 * 64) = rb[i]; } } while (0)
; template <int EPI>
; DI void gemm_phase(const u16* __restrict__ A, int lda, const u16* __restrict__ Bt, int K, int N, u16* outb, int ldo,
;                    const float* r0, const float* r1, float* outf, char* lds, int bid, int nb) {
;     ...
;     G_LOAD(0);
;     G_STORE(0);
;     __syncthreads();
;     for (int kt = 0; kt < nk; ++kt) {
;       const int cur = kt & 1;
;       if (kt + 1 < nk) G_LOAD(kt + 1);
;       G_MMA(cur, fo0);
;       G_MMA(cur, fo1);
;     ...
;     } else if constexpr (EPI == EPI_RESID) {
;       const int col = tn * 256 + wc * 64 + l15;
;       const float* rb_ = (tm * 256 < M_P) ? r0 : (r1 - (size_t)M_P * DM);
; #pragma unroll
;       for (int i = 0; i < 8; ++i)
; #pragma unroll
;         for (int r = 0; r < 4; ++r) {
;           const size_t i0 = (size_t)(mrow + i * 16 + r) * DM + col;
;           const float x0 = rb_[i0], x1 = rb_[i0 + 16], x2 = rb_[i0 + 32], x3 = rb_[i0 + 48];
;           outf[i0] = x0 + acc[i][0][r]; outf[i0 + 16] = x1 + acc[i][1][r]; outf[i0 + 32] = x2 + acc[i][2][r]; outf[i0 + 48] = x3 + acc[i][3][r];
;         }
	v_mfma_f32_16x16x32_bf16 v[124:127], v[152:155], v[188:191], v[124:127]
	v_mfma_f32_16x16x32_bf16 v[120:123], v[156:159], v[188:191], v[120:123]
	v_mfma_f32_16x16x32_bf16 v[116:119], v[160:163], v[188:191], v[116:119]
	v_mfma_f32_16x16x32_bf16 v[112:115], v[164:167], v[188:191], v[112:115]
	ds_read_b128 v[188:191], v226 offset:0
	ds_read_b128 v[168:171], v228 offset:0
	v_mfma_f32_16x16x32_bf16 v[108:111], v[152:155], v[192:195], v[108:111]
	v_mfma_f32_16x16x32_bf16 v[104:107], v[156:159], v[192:195], v[104:107]
	v_mfma_f32_16x16x32_bf16 v[100:103], v[160:163], v[192:195], v[100:103]
	v_mfma_f32_16x16x32_bf16 v[96:99], v[164:167], v[192:195], v[96:99]
	ds_read_b128 v[192:195], v226 offset:2048
	ds_read_b128 v[176:179], v228 offset:2048
	v_mfma_f32_16x16x32_bf16 v[92:95], v[152:155], v[196:199], v[92:95]
	v_mfma_f32_16x16x32_bf16 v[88:91], v[156:159], v[196:199], v[88:91]
	v_mfma_f32_16x16x32_bf16 v[84:87], v[160:163], v[196:199], v[84:87]
	v_mfma_f32_16x16x32_bf16 v[80:83], v[164:167], v[196:199], v[80:83]
	ds_read_b128 v[196:199], v226 offset:4096
	ds_read_b128 v[180:183], v228 offset:4096
	v_mfma_f32_16x16x32_bf16 v[76:79], v[152:155], v[200:203], v[76:79]
	v_mfma_f32_16x16x32_bf16 v[72:75], v[156:159], v[200:203], v[72:75]
	v_mfma_f32_16x16x32_bf16 v[68:71], v[160:163], v[200:203], v[68:71]
	v_mfma_f32_16x16x32_bf16 v[64:67], v[164:167], v[200:203], v[64:67]
	ds_read_b128 v[200:203], v226 offset:6144
	ds_read_b128 v[184:187], v228 offset:6144
	s_waitcnt lgkmcnt(11)
	v_mfma_f32_16x16x32_bf16 v[60:63], v[152:155], v[204:207], v[60:63]
	v_mfma_f32_16x16x32_bf16 v[56:59], v[156:159], v[204:207], v[56:59]
	v_mfma_f32_16x16x32_bf16 v[52:55], v[160:163], v[204:207], v[52:55]
	v_mfma_f32_16x16x32_bf16 v[48:51], v[164:167], v[204:207], v[48:51]
	ds_read_b128 v[204:207], v226 offset:8192
	ds_read_b128 v[220:223], v226 offset:14336
	s_waitcnt lgkmcnt(11)
	v_mfma_f32_16x16x32_bf16 v[44:47], v[152:155], v[208:211], v[44:47]
	v_mfma_f32_16x16x32_bf16 v[40:43], v[156:159], v[208:211], v[40:43]
	v_mfma_f32_16x16x32_bf16 v[36:39], v[160:163], v[208:211], v[36:39]
	v_mfma_f32_16x16x32_bf16 v[32:35], v[164:167], v[208:211], v[32:35]
	ds_read_b128 v[208:211], v226 offset:10240
	s_waitcnt lgkmcnt(11)
	v_mfma_f32_16x16x32_bf16 v[28:31], v[152:155], v[212:215], v[28:31]
	v_mfma_f32_16x16x32_bf16 v[24:27], v[156:159], v[212:215], v[24:27]
	v_mfma_f32_16x16x32_bf16 v[20:23], v[160:163], v[212:215], v[20:23]
	v_mfma_f32_16x16x32_bf16 v[16:19], v[164:167], v[212:215], v[16:19]
	ds_read_b128 v[212:215], v226 offset:12288
	v_mfma_f32_16x16x32_bf16 v[12:15], v[152:155], v[216:219], v[12:15]
	v_mfma_f32_16x16x32_bf16 v[8:11], v[156:159], v[216:219], v[8:11]
	v_mfma_f32_16x16x32_bf16 v[4:7], v[160:163], v[216:219], v[4:7]
	v_mfma_f32_16x16x32_bf16 v[0:3], v[164:167], v[216:219], v[0:3]
	s_waitcnt vmcnt(0) lgkmcnt(0)
	s_barrier
	v_mfma_f32_16x16x32_bf16 v[124:127], v[168:171], v[188:191], v[124:127]
	v_mfma_f32_16x16x32_bf16 v[120:123], v[176:179], v[188:191], v[120:123]
	v_mfma_f32_16x16x32_bf16 v[116:119], v[180:183], v[188:191], v[116:119]
	v_mfma_f32_16x16x32_bf16 v[112:115], v[184:187], v[188:191], v[112:115]
	v_mfma_f32_16x16x32_bf16 v[108:111], v[168:171], v[192:195], v[108:111]
	v_mfma_f32_16x16x32_bf16 v[104:107], v[176:179], v[192:195], v[104:107]
	v_mfma_f32_16x16x32_bf16 v[100:103], v[180:183], v[192:195], v[100:103]
	v_mfma_f32_16x16x32_bf16 v[96:99], v[184:187], v[192:195], v[96:99]
	v_mfma_f32_16x16x32_bf16 v[92:95], v[168:171], v[196:199], v[92:95]
	v_mfma_f32_16x16x32_bf16 v[88:91], v[176:179], v[196:199], v[88:91]
	v_mfma_f32_16x16x32_bf16 v[84:87], v[180:183], v[196:199], v[84:87]
	v_mfma_f32_16x16x32_bf16 v[80:83], v[184:187], v[196:199], v[80:83]
	v_mfma_f32_16x16x32_bf16 v[76:79], v[168:171], v[200:203], v[76:79]
	v_mfma_f32_16x16x32_bf16 v[72:75], v[176:179], v[200:203], v[72:75]
	v_mfma_f32_16x16x32_bf16 v[68:71], v[180:183], v[200:203], v[68:71]
	v_mfma_f32_16x16x32_bf16 v[64:67], v[184:187], v[200:203], v[64:67]
	v_mfma_f32_16x16x32_bf16 v[60:63], v[168:171], v[204:207], v[60:63]
	v_mfma_f32_16x16x32_bf16 v[56:59], v[176:179], v[204:207], v[56:59]
	v_mfma_f32_16x16x32_bf16 v[52:55], v[180:183], v[204:207], v[52:55]
	v_mfma_f32_16x16x32_bf16 v[48:51], v[184:187], v[204:207], v[48:51]
	v_mfma_f32_16x16x32_bf16 v[44:47], v[168:171], v[208:211], v[44:47]
	v_mfma_f32_16x16x32_bf16 v[40:43], v[176:179], v[208:211], v[40:43]
	v_mfma_f32_16x16x32_bf16 v[36:39], v[180:183], v[208:211], v[36:39]
	v_mfma_f32_16x16x32_bf16 v[32:35], v[184:187], v[208:211], v[32:35]
	v_mfma_f32_16x16x32_bf16 v[28:31], v[168:171], v[212:215], v[28:31]
	v_mfma_f32_16x16x32_bf16 v[24:27], v[176:179], v[212:215], v[24:27]
	v_mfma_f32_16x16x32_bf16 v[20:23], v[180:183], v[212:215], v[20:23]
	v_mfma_f32_16x16x32_bf16 v[16:19], v[184:187], v[212:215], v[16:19]
	v_mfma_f32_16x16x32_bf16 v[12:15], v[168:171], v[220:223], v[12:15]
	v_mfma_f32_16x16x32_bf16 v[8:11], v[176:179], v[220:223], v[8:11]
	v_mfma_f32_16x16x32_bf16 v[4:7], v[180:183], v[220:223], v[4:7]
	v_mfma_f32_16x16x32_bf16 v[0:3], v[184:187], v[220:223], v[0:3]
	s_nop 7
	s_nop 3
	v_and_b32_e32 v225, 15, v174
	v_lshrrev_b32_e32 v226, 8, v174
	v_lshl_or_b32 v225, v226, 7, v225
	v_bfe_u32 v226, v174, 6, 2
	v_bfe_u32 v227, v174, 4, 2
	v_lshlrev_b32_e32 v227, 2, v227
	v_add_u32_e32 v225, s37, v225
	v_lshl_add_u32 v226, v226, 6, v227
	v_add_u32_e32 v226, s38, v226
	v_lshlrev_b32_e32 v226, 2, v226
	v_lshl_add_u32 v224, v225, 12, v226
	v_mov_b32_e32 v229, v224
	v_add_u32_e32 v224, 0x0, v229
	global_load_dwordx4 v[152:155], v224, s[22:23] offset:0
	global_load_dwordx4 v[156:159], v224, s[22:23] offset:64
	global_load_dwordx4 v[160:163], v224, s[22:23] offset:128
	global_load_dwordx4 v[164:167], v224, s[22:23] offset:192
	v_add_u32_e32 v228, 0x10000, v229
	global_load_dwordx4 v[168:171], v228, s[22:23] offset:0
	global_load_dwordx4 v[176:179], v228, s[22:23] offset:64
	global_load_dwordx4 v[180:183], v228, s[22:23] offset:128
	global_load_dwordx4 v[184:187], v228, s[22:23] offset:192
	s_waitcnt vmcnt(4)
; template <int EPI>
; DI void gemm_phase(const u16* __restrict__ A, int lda, const u16* __restrict__ Bt, int K, int N, u16* outb, int ldo,
;                    const float* r0, const float* r1, float* outf, char* lds, int bid, int nb) {
;     ...
;     } else if constexpr (EPI == EPI_RESID) {
;       const int col = tn * 256 + wc * 64 + l15;
;       const float* rb_ = (tm * 256 < M_P) ? r0 : (r1 - (size_t)M_P * DM);
; #pragma unroll
;       for (int i = 0; i < 8; ++i)
; #pragma unroll
;         for (int r = 0; r < 4; ++r) {
;           const size_t i0 = (size_t)(mrow + i * 16 + r) * DM + col;
;           const float x0 = rb_[i0], x1 = rb_[i0 + 16], x2 = rb_[i0 + 32], x3 = rb_[i0 + 48];
;           outf[i0] = x0 + acc[i][0][r]; outf[i0 + 16] = x1 + acc[i][1][r]; outf[i0 + 32] = x2 + acc[i][2][r]; outf[i0 + 48] = x3 + acc[i][3][r];
;         }
	v_add_f32_e32 v152, v124, v152
	v_add_f32_e32 v153, v125, v153
	v_add_f32_e32 v154, v126, v154
	v_add_f32_e32 v155, v127, v155
	v_add_f32_e32 v156, v120, v156
	v_add_f32_e32 v157, v121, v157
	v_add_f32_e32 v158, v122, v158
	v_add_f32_e32 v159, v123, v159
	v_add_f32_e32 v160, v116, v160
	v_add_f32_e32 v161, v117, v161
	v_add_f32_e32 v162, v118, v162
	v_add_f32_e32 v163, v119, v163
	v_add_f32_e32 v164, v112, v164
	v_add_f32_e32 v165, v113, v165
	v_add_f32_e32 v166, v114, v166
	v_add_f32_e32 v167, v115, v167
	global_store_dwordx4 v224, v[152:155], s[22:23] offset:0
	global_store_dwordx4 v224, v[156:159], s[22:23] offset:64
	global_store_dwordx4 v224, v[160:163], s[22:23] offset:128
	global_store_dwordx4 v224, v[164:167], s[22:23] offset:192
	s_nop 1
	v_add_u32_e32 v224, 0x20000, v229
	global_load_dwordx4 v[152:155], v224, s[22:23] offset:0
	global_load_dwordx4 v[156:159], v224, s[22:23] offset:64
	global_load_dwordx4 v[160:163], v224, s[22:23] offset:128
	global_load_dwordx4 v[164:167], v224, s[22:23] offset:192
	s_waitcnt vmcnt(8)
	v_add_f32_e32 v168, v108, v168
	v_add_f32_e32 v169, v109, v169
	v_add_f32_e32 v170, v110, v170
	v_add_f32_e32 v171, v111, v171
	v_add_f32_e32 v176, v104, v176
	v_add_f32_e32 v177, v105, v177
	v_add_f32_e32 v178, v106, v178
	v_add_f32_e32 v179, v107, v179
	v_add_f32_e32 v180, v100, v180
	v_add_f32_e32 v181, v101, v181
	v_add_f32_e32 v182, v102, v182
	v_add_f32_e32 v183, v103, v183
	v_add_f32_e32 v184, v96, v184
	v_add_f32_e32 v185, v97, v185
	v_add_f32_e32 v186, v98, v186
	v_add_f32_e32 v187, v99, v187
	global_store_dwordx4 v228, v[168:171], s[22:23] offset:0
	global_store_dwordx4 v228, v[176:179], s[22:23] offset:64
	global_store_dwordx4 v228, v[180:183], s[22:23] offset:128
	global_store_dwordx4 v228, v[184:187], s[22:23] offset:192
	s_nop 1
	v_add_u32_e32 v228, 0x30000, v229
	global_load_dwordx4 v[168:171], v228, s[22:23] offset:0
	global_load_dwordx4 v[176:179], v228, s[22:23] offset:64
	global_load_dwordx4 v[180:183], v228, s[22:23] offset:128
	global_load_dwordx4 v[184:187], v228, s[22:23] offset:192
	s_waitcnt vmcnt(8)
	v_add_f32_e32 v152, v92, v152
	v_add_f32_e32 v153, v93, v153
	v_add_f32_e32 v154, v94, v154
	v_add_f32_e32 v155, v95, v155
	v_add_f32_e32 v156, v88, v156
	v_add_f32_e32 v157, v89, v157
	v_add_f32_e32 v158, v90, v158
	v_add_f32_e32 v159, v91, v159
	v_add_f32_e32 v160, v84, v160
	v_add_f32_e32 v161, v85, v161
	v_add_f32_e32 v162, v86, v162
	v_add_f32_e32 v163, v87, v163
	v_add_f32_e32 v164, v80, v164
	v_add_f32_e32 v165, v81, v165
	v_add_f32_e32 v166, v82, v166
	v_add_f32_e32 v167, v83, v167
	global_store_dwordx4 v224, v[152:155], s[22:23] offset:0
	global_store_dwordx4 v224, v[156:159], s[22:23] offset:64
	global_store_dwordx4 v224, v[160:163], s[22:23] offset:128
	global_store_dwordx4 v224, v[164:167], s[22:23] offset:192
	s_nop 1
	v_add_u32_e32 v224, 0x40000, v229
	global_load_dwordx4 v[152:155], v224, s[22:23] offset:0
	global_load_dwordx4 v[156:159], v224, s[22:23] offset:64
	global_load_dwordx4 v[160:163], v224, s[22:23] offset:128
	global_load_dwordx4 v[164:167], v224, s[22:23] offset:192
	s_waitcnt vmcnt(8)
	v_add_f32_e32 v168, v76, v168
	v_add_f32_e32 v169, v77, v169
	v_add_f32_e32 v170, v78, v170
	v_add_f32_e32 v171, v79, v171
	v_add_f32_e32 v176, v72, v176
	v_add_f32_e32 v177, v73, v177
	v_add_f32_e32 v178, v74, v178
	v_add_f32_e32 v179, v75, v179
	v_add_f32_e32 v180, v68, v180
	v_add_f32_e32 v181, v69, v181
	v_add_f32_e32 v182, v70, v182
	v_add_f32_e32 v183, v71, v183
	v_add_f32_e32 v184, v64, v184
	v_add_f32_e32 v185, v65, v185
	v_add_f32_e32 v186, v66, v186
	v_add_f32_e32 v187, v67, v187
	global_store_dwordx4 v228, v[168:171], s[22:23] offset:0
	global_store_dwordx4 v228, v[176:179], s[22:23] offset:64
	global_store_dwordx4 v228, v[180:183], s[22:23] offset:128
	global_store_dwordx4 v228, v[184:187], s[22:23] offset:192
	s_nop 1
	v_add_u32_e32 v228, 0x50000, v229
	global_load_dwordx4 v[168:171], v228, s[22:23] offset:0
	global_load_dwordx4 v[176:179], v228, s[22:23] offset:64
	global_load_dwordx4 v[180:183], v228, s[22:23] offset:128
	global_load_dwordx4 v[184:187], v228, s[22:23] offset:192
	s_waitcnt vmcnt(8)
; template <int EPI>
; DI void gemm_phase(const u16* __restrict__ A, int lda, const u16* __restrict__ Bt, int K, int N, u16* outb, int ldo,
;                    const float* r0, const float* r1, float* outf, char* lds, int bid, int nb) {
;     ...
;     } else if constexpr (EPI == EPI_RESID) {
;       const int col = tn * 256 + wc * 64 + l15;
;       const float* rb_ = (tm * 256 < M_P) ? r0 : (r1 - (size_t)M_P * DM);
; #pragma unroll
;       for (int i = 0; i < 8; ++i)
; #pragma unroll
;         for (int r = 0; r < 4; ++r) {
;           const size_t i0 = (size_t)(mrow + i * 16 + r) * DM + col;
;           const float x0 = rb_[i0], x1 = rb_[i0 + 16], x2 = rb_[i0 + 32], x3 = rb_[i0 + 48];
;           outf[i0] = x0 + acc[i][0][r]; outf[i0 + 16] = x1 + acc[i][1][r]; outf[i0 + 32] = x2 + acc[i][2][r]; outf[i0 + 48] = x3 + acc[i][3][r];
;         }
	v_add_f32_e32 v152, v60, v152
	v_add_f32_e32 v153, v61, v153
	v_add_f32_e32 v154, v62, v154
	v_add_f32_e32 v155, v63, v155
	v_add_f32_e32 v156, v56, v156
	v_add_f32_e32 v157, v57, v157
	v_add_f32_e32 v158, v58, v158
	v_add_f32_e32 v159, v59, v159
	v_add_f32_e32 v160, v52, v160
	v_add_f32_e32 v161, v53, v161
	v_add_f32_e32 v162, v54, v162
	v_add_f32_e32 v163, v55, v163
	v_add_f32_e32 v164, v48, v164
	v_add_f32_e32 v165, v49, v165
	v_add_f32_e32 v166, v50, v166
	v_add_f32_e32 v167, v51, v167
	global_store_dwordx4 v224, v[152:155], s[22:23] offset:0
	global_store_dwordx4 v224, v[156:159], s[22:23] offset:64
	global_store_dwordx4 v224, v[160:163], s[22:23] offset:128
	global_store_dwordx4 v224, v[164:167], s[22:23] offset:192
	s_nop 1
	v_add_u32_e32 v224, 0x60000, v229
	global_load_dwordx4 v[152:155], v224, s[22:23] offset:0
	global_load_dwordx4 v[156:159], v224, s[22:23] offset:64
	global_load_dwordx4 v[160:163], v224, s[22:23] offset:128
	global_load_dwordx4 v[164:167], v224, s[22:23] offset:192
	s_waitcnt vmcnt(8)
	v_add_f32_e32 v168, v44, v168
	v_add_f32_e32 v169, v45, v169
	v_add_f32_e32 v170, v46, v170
	v_add_f32_e32 v171, v47, v171
	v_add_f32_e32 v176, v40, v176
	v_add_f32_e32 v177, v41, v177
	v_add_f32_e32 v178, v42, v178
	v_add_f32_e32 v179, v43, v179
	v_add_f32_e32 v180, v36, v180
	v_add_f32_e32 v181, v37, v181
	v_add_f32_e32 v182, v38, v182
	v_add_f32_e32 v183, v39, v183
	v_add_f32_e32 v184, v32, v184
	v_add_f32_e32 v185, v33, v185
	v_add_f32_e32 v186, v34, v186
	v_add_f32_e32 v187, v35, v187
	global_store_dwordx4 v228, v[168:171], s[22:23] offset:0
	global_store_dwordx4 v228, v[176:179], s[22:23] offset:64
	global_store_dwordx4 v228, v[180:183], s[22:23] offset:128
	global_store_dwordx4 v228, v[184:187], s[22:23] offset:192
	s_nop 1
	v_add_u32_e32 v228, 0x70000, v229
	global_load_dwordx4 v[168:171], v228, s[22:23] offset:0
	global_load_dwordx4 v[176:179], v228, s[22:23] offset:64
	global_load_dwordx4 v[180:183], v228, s[22:23] offset:128
	global_load_dwordx4 v[184:187], v228, s[22:23] offset:192
	s_waitcnt vmcnt(8)
	v_add_f32_e32 v152, v28, v152
	v_add_f32_e32 v153, v29, v153
	v_add_f32_e32 v154, v30, v154
	v_add_f32_e32 v155, v31, v155
	v_add_f32_e32 v156, v24, v156
	v_add_f32_e32 v157, v25, v157
	v_add_f32_e32 v158, v26, v158
	v_add_f32_e32 v159, v27, v159
	v_add_f32_e32 v160, v20, v160
	v_add_f32_e32 v161, v21, v161
	v_add_f32_e32 v162, v22, v162
	v_add_f32_e32 v163, v23, v163
	v_add_f32_e32 v164, v16, v164
	v_add_f32_e32 v165, v17, v165
	v_add_f32_e32 v166, v18, v166
	v_add_f32_e32 v167, v19, v167
	global_store_dwordx4 v224, v[152:155], s[22:23] offset:0
	global_store_dwordx4 v224, v[156:159], s[22:23] offset:64
	global_store_dwordx4 v224, v[160:163], s[22:23] offset:128
	global_store_dwordx4 v224, v[164:167], s[22:23] offset:192
	s_waitcnt vmcnt(4)
	v_add_f32_e32 v168, v12, v168
	v_add_f32_e32 v169, v13, v169
	v_add_f32_e32 v170, v14, v170
	v_add_f32_e32 v171, v15, v171
	v_add_f32_e32 v176, v8, v176
	v_add_f32_e32 v177, v9, v177
	v_add_f32_e32 v178, v10, v178
	v_add_f32_e32 v179, v11, v179
	v_add_f32_e32 v180, v4, v180
	v_add_f32_e32 v181, v5, v181
	v_add_f32_e32 v182, v6, v182
	v_add_f32_e32 v183, v7, v183
	v_add_f32_e32 v184, v0, v184
	v_add_f32_e32 v185, v1, v185
	v_add_f32_e32 v186, v2, v186
	v_add_f32_e32 v187, v3, v187
	global_store_dwordx4 v228, v[168:171], s[22:23] offset:0
	global_store_dwordx4 v228, v[176:179], s[22:23] offset:64
	global_store_dwordx4 v228, v[180:183], s[22:23] offset:128
	global_store_dwordx4 v228, v[184:187], s[22:23] offset:192
	s_add_i32 s14, s14, 1
	s_cmp_eq_u32 s14, s3
	s_cbranch_scc0 .LBB0_1359
